# v14: v12 + extra s_setprio 0/1 pair after every 8 MFMAs in all GEMM K-loop MFMA segments (more issue windows for the partner wave)
# speedup vs baseline: 1.0022x; 1.0022x over previous
; #define PG8_STAGE(bufoff, gbase, voff) do { _Pragma("unroll") for (int _i = 0; _i < 2; ++_i) \
;         __builtin_amdgcn_global_load_lds((const unsigned*)((const char*)(gbase) + (voff)[_i]), (PG8_LAS unsigned*)(lds + (bufoff) + ldsw + _i * 8192), 16, 0, 0); } while (0)
; #define PG8_LDA(dst, b, h) do { _Pragma("unroll") for (int m = 0; m < 4; ++m) _Pragma("unroll") for (int k = 0; k < 2; ++k) dst[m][k] = *(const PG8_LAS bf16x8*)(lds + PG8_SA(b, h) + aoff + m * 2048 + k * 1024); } while (0)
; #define PG8_LDB(dst, b, h) do { _Pragma("unroll") for (int n = 0; n < 2; ++n) _Pragma("unroll") for (int k = 0; k < 2; ++k) dst[n][k] = *(const PG8_LAS bf16x8*)(lds + PG8_SB(b, h) + boff + n * 2048 + k * 1024); } while (0)
; #define PG8_MMA(ai, bj, At, Bt) do { __builtin_amdgcn_s_setprio(1); _Pragma("unroll") for (int m = 0; m < 4; ++m) _Pragma("unroll") for (int n = 0; n < 2; ++n) _Pragma("unroll") for (int k = 0; k < 2; ++k) \
;         acc[ai][bj][m][n] = mma_<I8>(Bt[n][k], At[m][k], acc[ai][bj][m][n]); __builtin_amdgcn_s_setprio(0); } while (0)
; #define PG8_WAIT_V(n) asm volatile("s_waitcnt vmcnt(" #n ")" ::: "memory")
; #define PG8_WAIT_L(n) asm volatile("s_waitcnt lgkmcnt(" #n ")" ::: "memory")
; #define PG8_BAR __builtin_amdgcn_s_barrier()
; #define PG8_SCHED __builtin_amdgcn_sched_barrier(0)
; template <class Epi, class Sched, bool ALIGN_EPI = false, bool SP2 = false, bool I8 = false>
; __device__ __forceinline__ void gemm_phase(PG8_LAS unsigned char* lds, const Gemm g, const Sched& S, const Epi& E) {
;     ...
;             PG8_LDB(B0, 0, 0); PG8_LDB(B1, 0, 1); PG8_SCHED; PG8_LDA(At, 0, 0); PG8_STAGE(PG8_SA(1, 1), a1 + hstepA, voffA);
;             PG8_WAIT_V(8); PG8_WAIT_L(0); PG8_BAR; PG8_MMA(0, 0, At, B0); PG8_MMA(0, 1, At, B1); PG8_BAR; PG8_SCHED;
;             PG8_LDA(At, 0, 1); PG8_STAGE(PG8_SB(0, 0), b2, voffB); PG8_STAGE(PG8_SB(0, 1), b2 + hstepB, voffB); PG8_STAGE(PG8_SA(0, 0), a2, voffA);
.LBB0_483:
	ds_read_b128 v[58:61], v187
	ds_read_b128 v[62:65], v187 offset:1024
	ds_read_b128 v[74:77], v187 offset:2048
	ds_read_b128 v[78:81], v187 offset:3072
	ds_read_b128 v[162:165], v188
	ds_read_b128 v[166:169], v188 offset:1024
	ds_read_b128 v[170:173], v188 offset:2048
	ds_read_b128 v[190:193], v188 offset:3072
	s_add_u32 s34, s2, 0xfff80080
	s_addc_u32 s35, s3, -1
	s_cmp_eq_u32 s40, 28
	s_cselect_b32 s37, s7, s35
	s_cselect_b32 s36, s25, s34
	s_cselect_b32 s35, s23, s39
	s_cselect_b32 s34, s33, s38
	v_lshl_add_u64 v[174:175], s[2:3], 0, v[154:155]
	s_add_i32 m0, s31, 0xc000
	ds_read_b128 v[194:197], v189
	ds_read_b128 v[198:201], v189 offset:1024
	ds_read_b128 v[202:205], v189 offset:2048
	ds_read_b128 v[206:209], v189 offset:3072
	ds_read_b128 v[210:213], v189 offset:4096
	ds_read_b128 v[214:217], v189 offset:5120
	ds_read_b128 v[218:221], v189 offset:6144
	ds_read_b128 v[222:225], v189 offset:7168
	global_load_lds_dwordx4 v[174:175], off
	v_lshl_add_u64 v[174:175], s[2:3], 0, v[156:157]
	s_add_i32 m0, s31, 0xe000
	s_nop 0
	global_load_lds_dwordx4 v[174:175], off
	s_waitcnt vmcnt(8)
	s_waitcnt lgkmcnt(0)
	s_barrier
	s_setprio 1
	s_waitcnt lgkmcnt(0)
	v_mfma_i32_16x16x64_i8 v[142:145], v[58:61], v[194:197], v[142:145]
	v_mfma_i32_16x16x64_i8 v[138:141], v[74:77], v[194:197], v[138:141]
	v_mfma_i32_16x16x64_i8 v[126:129], v[58:61], v[202:205], v[126:129]
	v_mfma_i32_16x16x64_i8 v[122:125], v[74:77], v[202:205], v[122:125]
	v_mfma_i32_16x16x64_i8 v[110:113], v[58:61], v[210:213], v[110:113]
	v_mfma_i32_16x16x64_i8 v[106:109], v[74:77], v[210:213], v[106:109]
	v_mfma_i32_16x16x64_i8 v[94:97], v[58:61], v[218:221], v[94:97]
	v_mfma_i32_16x16x64_i8 v[90:93], v[74:77], v[218:221], v[90:93]
	s_setprio 0
	s_setprio 1
	v_mfma_i32_16x16x64_i8 v[142:145], v[62:65], v[198:201], v[142:145]
	v_mfma_i32_16x16x64_i8 v[138:141], v[78:81], v[198:201], v[138:141]
	v_mfma_i32_16x16x64_i8 v[126:129], v[62:65], v[206:209], v[126:129]
	v_mfma_i32_16x16x64_i8 v[122:125], v[78:81], v[206:209], v[122:125]
	v_mfma_i32_16x16x64_i8 v[110:113], v[62:65], v[214:217], v[110:113]
	v_mfma_i32_16x16x64_i8 v[106:109], v[78:81], v[214:217], v[106:109]
	v_mfma_i32_16x16x64_i8 v[94:97], v[62:65], v[222:225], v[94:97]
	v_mfma_i32_16x16x64_i8 v[90:93], v[78:81], v[222:225], v[90:93]
	s_setprio 0
	s_setprio 1
	v_mfma_i32_16x16x64_i8 v[134:137], v[162:165], v[194:197], v[134:137]
	v_mfma_i32_16x16x64_i8 v[130:133], v[170:173], v[194:197], v[130:133]
	v_mfma_i32_16x16x64_i8 v[118:121], v[162:165], v[202:205], v[118:121]
	v_mfma_i32_16x16x64_i8 v[114:117], v[170:173], v[202:205], v[114:117]
	v_mfma_i32_16x16x64_i8 v[102:105], v[162:165], v[210:213], v[102:105]
	v_mfma_i32_16x16x64_i8 v[98:101], v[170:173], v[210:213], v[98:101]
	v_mfma_i32_16x16x64_i8 v[86:89], v[162:165], v[218:221], v[86:89]
	v_mfma_i32_16x16x64_i8 v[82:85], v[170:173], v[218:221], v[82:85]
	s_setprio 0
	s_setprio 1
	v_mfma_i32_16x16x64_i8 v[134:137], v[166:169], v[198:201], v[134:137]
	v_mfma_i32_16x16x64_i8 v[130:133], v[190:193], v[198:201], v[130:133]
	v_mfma_i32_16x16x64_i8 v[118:121], v[166:169], v[206:209], v[118:121]
	v_mfma_i32_16x16x64_i8 v[114:117], v[190:193], v[206:209], v[114:117]
	v_mfma_i32_16x16x64_i8 v[102:105], v[166:169], v[214:217], v[102:105]
	v_mfma_i32_16x16x64_i8 v[98:101], v[190:193], v[214:217], v[98:101]
	v_mfma_i32_16x16x64_i8 v[86:89], v[166:169], v[222:225], v[86:89]
	v_mfma_i32_16x16x64_i8 v[82:85], v[190:193], v[222:225], v[82:85]
	s_setprio 0
	s_barrier
	s_add_i32 s41, s8, s68
	v_lshl_add_u64 v[174:175], s[34:35], 0, v[148:149]
	s_mov_b32 m0, s41
	ds_read_b128 v[194:197], v189 offset:16384
	ds_read_b128 v[198:201], v189 offset:17408
	ds_read_b128 v[202:205], v189 offset:18432
	ds_read_b128 v[206:209], v189 offset:19456
	ds_read_b128 v[210:213], v189 offset:20480
	ds_read_b128 v[214:217], v189 offset:21504
	ds_read_b128 v[218:221], v189 offset:22528
	ds_read_b128 v[222:225], v189 offset:23552
	global_load_lds_dwordx4 v[174:175], off
	s_add_i32 m0, s41, 0x2000
	s_add_u32 vcc_lo, s34, 0x80000
	v_lshl_add_u64 v[226:227], s[34:35], 0, v[152:153]
	s_addc_u32 vcc_hi, s35, 0
	s_add_i32 s41, s9, s68
	global_load_lds_dwordx4 v[226:227], off
	v_lshl_add_u64 v[228:229], vcc, 0, v[148:149]
	s_mov_b32 m0, s41
	v_lshl_add_u64 v[230:231], s[36:37], 0, v[150:151]
	global_load_lds_dwordx4 v[228:229], off
	v_lshl_add_u64 v[228:229], vcc, 0, v[152:153]
	s_add_i32 m0, s41, 0x2000
	s_nop 0
	global_load_lds_dwordx4 v[228:229], off
	v_lshl_add_u64 v[228:229], s[36:37], 0, v[146:147]
	s_mov_b32 m0, s31
	s_nop 0
	global_load_lds_dwordx4 v[228:229], off
	s_mov_b32 m0, s69
	s_nop 0
	global_load_lds_dwordx4 v[230:231], off
	s_waitcnt vmcnt(8)
	s_waitcnt lgkmcnt(0)
	s_barrier
; #define PG8_STAGE(bufoff, gbase, voff) do { _Pragma("unroll") for (int _i = 0; _i < 2; ++_i) \
;         __builtin_amdgcn_global_load_lds((const unsigned*)((const char*)(gbase) + (voff)[_i]), (PG8_LAS unsigned*)(lds + (bufoff) + ldsw + _i * 8192), 16, 0, 0); } while (0)
; #define PG8_LDA(dst, b, h) do { _Pragma("unroll") for (int m = 0; m < 4; ++m) _Pragma("unroll") for (int k = 0; k < 2; ++k) dst[m][k] = *(const PG8_LAS bf16x8*)(lds + PG8_SA(b, h) + aoff + m * 2048 + k * 1024); } while (0)
; #define PG8_LDB(dst, b, h) do { _Pragma("unroll") for (int n = 0; n < 2; ++n) _Pragma("unroll") for (int k = 0; k < 2; ++k) dst[n][k] = *(const PG8_LAS bf16x8*)(lds + PG8_SB(b, h) + boff + n * 2048 + k * 1024); } while (0)
; #define PG8_MMA(ai, bj, At, Bt) do { __builtin_amdgcn_s_setprio(1); _Pragma("unroll") for (int m = 0; m < 4; ++m) _Pragma("unroll") for (int n = 0; n < 2; ++n) _Pragma("unroll") for (int k = 0; k < 2; ++k) \
;         acc[ai][bj][m][n] = mma_<I8>(Bt[n][k], At[m][k], acc[ai][bj][m][n]); __builtin_amdgcn_s_setprio(0); } while (0)
; #define PG8_WAIT_V(n) asm volatile("s_waitcnt vmcnt(" #n ")" ::: "memory")
; #define PG8_WAIT_L(n) asm volatile("s_waitcnt lgkmcnt(" #n ")" ::: "memory")
; #define PG8_BAR __builtin_amdgcn_s_barrier()
; #define PG8_SCHED __builtin_amdgcn_sched_barrier(0)
; template <class Epi, class Sched, bool ALIGN_EPI = false, bool SP2 = false, bool I8 = false>
; __device__ __forceinline__ void gemm_phase(PG8_LAS unsigned char* lds, const Gemm g, const Sched& S, const Epi& E) {
;     ...
;             PG8_WAIT_V(8); PG8_WAIT_L(0); PG8_BAR; PG8_MMA(1, 0, At, B0); PG8_MMA(1, 1, At, B1); PG8_BAR; PG8_SCHED;
;             PG8_LDB(B0, 1, 0); PG8_LDB(B1, 1, 1); PG8_SCHED; PG8_LDA(At, 1, 0); PG8_STAGE(PG8_SA(0, 1), a2 + hstepA, voffA);
;             PG8_WAIT_V(8); PG8_WAIT_L(0); PG8_BAR; PG8_MMA(0, 0, At, B0); PG8_MMA(0, 1, At, B1); PG8_BAR; PG8_SCHED;
	s_setprio 1
	s_waitcnt lgkmcnt(0)
	v_mfma_i32_16x16x64_i8 v[70:73], v[58:61], v[194:197], v[70:73]
	v_mfma_i32_16x16x64_i8 v[66:69], v[74:77], v[194:197], v[66:69]
	v_mfma_i32_16x16x64_i8 v[46:49], v[58:61], v[202:205], v[46:49]
	v_mfma_i32_16x16x64_i8 v[42:45], v[74:77], v[202:205], v[42:45]
	v_mfma_i32_16x16x64_i8 v[30:33], v[58:61], v[210:213], v[30:33]
	v_mfma_i32_16x16x64_i8 v[26:29], v[74:77], v[210:213], v[26:29]
	v_mfma_i32_16x16x64_i8 v[14:17], v[58:61], v[218:221], v[14:17]
	v_mfma_i32_16x16x64_i8 v[10:13], v[74:77], v[218:221], v[10:13]
	s_setprio 0
	s_setprio 1
	v_mfma_i32_16x16x64_i8 v[70:73], v[62:65], v[198:201], v[70:73]
	v_mfma_i32_16x16x64_i8 v[66:69], v[78:81], v[198:201], v[66:69]
	v_mfma_i32_16x16x64_i8 v[46:49], v[62:65], v[206:209], v[46:49]
	v_mfma_i32_16x16x64_i8 v[42:45], v[78:81], v[206:209], v[42:45]
	v_mfma_i32_16x16x64_i8 v[30:33], v[62:65], v[214:217], v[30:33]
	v_mfma_i32_16x16x64_i8 v[26:29], v[78:81], v[214:217], v[26:29]
	v_mfma_i32_16x16x64_i8 v[14:17], v[62:65], v[222:225], v[14:17]
	v_mfma_i32_16x16x64_i8 v[10:13], v[78:81], v[222:225], v[10:13]
	s_setprio 0
	s_setprio 1
	v_mfma_i32_16x16x64_i8 v[54:57], v[162:165], v[194:197], v[54:57]
	v_mfma_i32_16x16x64_i8 v[50:53], v[170:173], v[194:197], v[50:53]
	v_mfma_i32_16x16x64_i8 v[38:41], v[162:165], v[202:205], v[38:41]
	v_mfma_i32_16x16x64_i8 v[34:37], v[170:173], v[202:205], v[34:37]
	v_mfma_i32_16x16x64_i8 v[22:25], v[162:165], v[210:213], v[22:25]
	v_mfma_i32_16x16x64_i8 v[18:21], v[170:173], v[210:213], v[18:21]
	v_mfma_i32_16x16x64_i8 v[6:9], v[162:165], v[218:221], v[6:9]
	v_mfma_i32_16x16x64_i8 v[2:5], v[170:173], v[218:221], v[2:5]
	s_setprio 0
	s_setprio 1
	v_mfma_i32_16x16x64_i8 v[54:57], v[166:169], v[198:201], v[54:57]
	v_mfma_i32_16x16x64_i8 v[50:53], v[190:193], v[198:201], v[50:53]
	v_mfma_i32_16x16x64_i8 v[38:41], v[166:169], v[206:209], v[38:41]
	v_mfma_i32_16x16x64_i8 v[34:37], v[190:193], v[206:209], v[34:37]
	v_mfma_i32_16x16x64_i8 v[22:25], v[166:169], v[214:217], v[22:25]
	v_mfma_i32_16x16x64_i8 v[18:21], v[190:193], v[214:217], v[18:21]
	v_mfma_i32_16x16x64_i8 v[6:9], v[166:169], v[222:225], v[6:9]
	v_mfma_i32_16x16x64_i8 v[2:5], v[190:193], v[222:225], v[2:5]
	s_setprio 0
	s_barrier
	s_add_i32 s41, 0, 0x18000
	s_add_i32 s95, 0, 0x1c000
	v_add_u32_e32 v78, s41, v181
	v_add_u32_e32 v190, s95, v181
	ds_read_b128 v[58:61], v78
	ds_read_b128 v[62:65], v78 offset:1024
	ds_read_b128 v[74:77], v78 offset:2048
	ds_read_b128 v[78:81], v78 offset:3072
	ds_read_b128 v[162:165], v190
	ds_read_b128 v[166:169], v190 offset:1024
	ds_read_b128 v[170:173], v190 offset:2048
	ds_read_b128 v[190:193], v190 offset:3072
	s_add_u32 s36, s36, 0x80000
	s_addc_u32 s37, s37, 0
	s_mov_b32 m0, s70
	v_lshl_add_u64 v[234:235], s[36:37], 0, v[146:147]
	ds_read_b128 v[194:197], v189 offset:32768
	ds_read_b128 v[198:201], v189 offset:33792
	ds_read_b128 v[202:205], v189 offset:34816
	ds_read_b128 v[206:209], v189 offset:35840
	ds_read_b128 v[210:213], v189 offset:36864
	ds_read_b128 v[214:217], v189 offset:37888
	ds_read_b128 v[218:221], v189 offset:38912
	ds_read_b128 v[222:225], v189 offset:39936
	global_load_lds_dwordx4 v[234:235], off
	v_lshl_add_u64 v[234:235], s[36:37], 0, v[150:151]
	s_mov_b32 m0, s71
	s_nop 0
	global_load_lds_dwordx4 v[234:235], off
	s_waitcnt vmcnt(8)
	s_waitcnt lgkmcnt(0)
	s_barrier
	s_setprio 1
	s_waitcnt lgkmcnt(0)
	v_mfma_i32_16x16x64_i8 v[142:145], v[58:61], v[194:197], v[142:145]
	v_mfma_i32_16x16x64_i8 v[138:141], v[74:77], v[194:197], v[138:141]
	v_mfma_i32_16x16x64_i8 v[126:129], v[58:61], v[202:205], v[126:129]
	v_mfma_i32_16x16x64_i8 v[122:125], v[74:77], v[202:205], v[122:125]
	v_mfma_i32_16x16x64_i8 v[110:113], v[58:61], v[210:213], v[110:113]
	v_mfma_i32_16x16x64_i8 v[106:109], v[74:77], v[210:213], v[106:109]
	v_mfma_i32_16x16x64_i8 v[94:97], v[58:61], v[218:221], v[94:97]
	v_mfma_i32_16x16x64_i8 v[90:93], v[74:77], v[218:221], v[90:93]
	s_setprio 0
	s_setprio 1
	v_mfma_i32_16x16x64_i8 v[142:145], v[62:65], v[198:201], v[142:145]
	v_mfma_i32_16x16x64_i8 v[138:141], v[78:81], v[198:201], v[138:141]
	v_mfma_i32_16x16x64_i8 v[126:129], v[62:65], v[206:209], v[126:129]
	v_mfma_i32_16x16x64_i8 v[122:125], v[78:81], v[206:209], v[122:125]
	v_mfma_i32_16x16x64_i8 v[110:113], v[62:65], v[214:217], v[110:113]
	v_mfma_i32_16x16x64_i8 v[106:109], v[78:81], v[214:217], v[106:109]
	v_mfma_i32_16x16x64_i8 v[94:97], v[62:65], v[222:225], v[94:97]
	v_mfma_i32_16x16x64_i8 v[90:93], v[78:81], v[222:225], v[90:93]
	s_setprio 0
	s_setprio 1
	v_mfma_i32_16x16x64_i8 v[134:137], v[162:165], v[194:197], v[134:137]
	v_mfma_i32_16x16x64_i8 v[130:133], v[170:173], v[194:197], v[130:133]
	v_mfma_i32_16x16x64_i8 v[118:121], v[162:165], v[202:205], v[118:121]
	v_mfma_i32_16x16x64_i8 v[114:117], v[170:173], v[202:205], v[114:117]
	v_mfma_i32_16x16x64_i8 v[102:105], v[162:165], v[210:213], v[102:105]
	v_mfma_i32_16x16x64_i8 v[98:101], v[170:173], v[210:213], v[98:101]
	v_mfma_i32_16x16x64_i8 v[86:89], v[162:165], v[218:221], v[86:89]
	v_mfma_i32_16x16x64_i8 v[82:85], v[170:173], v[218:221], v[82:85]
	s_setprio 0
	s_setprio 1
	v_mfma_i32_16x16x64_i8 v[134:137], v[166:169], v[198:201], v[134:137]
	v_mfma_i32_16x16x64_i8 v[130:133], v[190:193], v[198:201], v[130:133]
	v_mfma_i32_16x16x64_i8 v[118:121], v[166:169], v[206:209], v[118:121]
	v_mfma_i32_16x16x64_i8 v[114:117], v[190:193], v[206:209], v[114:117]
	v_mfma_i32_16x16x64_i8 v[102:105], v[166:169], v[214:217], v[102:105]
	v_mfma_i32_16x16x64_i8 v[98:101], v[190:193], v[214:217], v[98:101]
	v_mfma_i32_16x16x64_i8 v[86:89], v[166:169], v[222:225], v[86:89]
	v_mfma_i32_16x16x64_i8 v[82:85], v[190:193], v[222:225], v[82:85]
	s_setprio 0
	s_barrier
; #define PG8_STAGE(bufoff, gbase, voff) do { _Pragma("unroll") for (int _i = 0; _i < 2; ++_i) \
;         __builtin_amdgcn_global_load_lds((const unsigned*)((const char*)(gbase) + (voff)[_i]), (PG8_LAS unsigned*)(lds + (bufoff) + ldsw + _i * 8192), 16, 0, 0); } while (0)
; #define PG8_LDA(dst, b, h) do { _Pragma("unroll") for (int m = 0; m < 4; ++m) _Pragma("unroll") for (int k = 0; k < 2; ++k) dst[m][k] = *(const PG8_LAS bf16x8*)(lds + PG8_SA(b, h) + aoff + m * 2048 + k * 1024); } while (0)
; #define PG8_MMA(ai, bj, At, Bt) do { __builtin_amdgcn_s_setprio(1); _Pragma("unroll") for (int m = 0; m < 4; ++m) _Pragma("unroll") for (int n = 0; n < 2; ++n) _Pragma("unroll") for (int k = 0; k < 2; ++k) \
;         acc[ai][bj][m][n] = mma_<I8>(Bt[n][k], At[m][k], acc[ai][bj][m][n]); __builtin_amdgcn_s_setprio(0); } while (0)
; #define PG8_WAIT_V(n) asm volatile("s_waitcnt vmcnt(" #n ")" ::: "memory")
; #define PG8_WAIT_L(n) asm volatile("s_waitcnt lgkmcnt(" #n ")" ::: "memory")
; #define PG8_BAR __builtin_amdgcn_s_barrier()
; #define PG8_SCHED __builtin_amdgcn_sched_barrier(0)
; template <class Epi, class Sched, bool ALIGN_EPI = false, bool SP2 = false, bool I8 = false>
; __device__ __forceinline__ void gemm_phase(PG8_LAS unsigned char* lds, const Gemm g, const Sched& S, const Epi& E) {
;     ...
;         for (int t = 0; t < nt; t += 2) {
;     ...
;             PG8_LDA(At, 1, 1); PG8_STAGE(PG8_SB(1, 0), b3, voffB); PG8_STAGE(PG8_SB(1, 1), b3 + hstepB, voffB); PG8_STAGE(PG8_SA(1, 0), a3, voffA);
;             PG8_WAIT_V(8); PG8_WAIT_L(0); PG8_BAR; PG8_MMA(1, 0, At, B0); PG8_MMA(1, 1, At, B1); PG8_BAR; PG8_SCHED;
	s_add_i32 s36, s41, s68
	v_lshl_add_u64 v[174:175], v[174:175], 0, s[18:19]
	s_mov_b32 m0, s36
	ds_read_b128 v[194:197], v189 offset:49152
	ds_read_b128 v[198:201], v189 offset:50176
	ds_read_b128 v[202:205], v189 offset:51200
	ds_read_b128 v[206:209], v189 offset:52224
	ds_read_b128 v[210:213], v189 offset:53248
	ds_read_b128 v[214:217], v189 offset:54272
	ds_read_b128 v[218:221], v189 offset:55296
	ds_read_b128 v[222:225], v189 offset:56320
	global_load_lds_dwordx4 v[174:175], off
	s_add_i32 m0, s36, 0x2000
	s_add_u32 s34, s34, 0x80080
	v_lshl_add_u64 v[174:175], v[226:227], 0, s[18:19]
	s_addc_u32 s35, s35, 0
	s_add_i32 s36, s95, s68
	global_load_lds_dwordx4 v[174:175], off
	v_lshl_add_u64 v[174:175], s[34:35], 0, v[148:149]
	s_mov_b32 m0, s36
	s_nop 0
	global_load_lds_dwordx4 v[174:175], off
	v_lshl_add_u64 v[174:175], s[34:35], 0, v[152:153]
	s_add_i32 m0, s36, 0x2000
	s_nop 0
	global_load_lds_dwordx4 v[174:175], off
	v_lshl_add_u64 v[174:175], v[228:229], 0, s[18:19]
	s_mov_b32 m0, s89
	s_nop 0
	global_load_lds_dwordx4 v[174:175], off
	v_lshl_add_u64 v[174:175], v[230:231], 0, s[18:19]
	s_mov_b32 m0, s92
	s_nop 0
	global_load_lds_dwordx4 v[174:175], off
	s_waitcnt vmcnt(8)
	s_waitcnt lgkmcnt(0)
	s_barrier
	s_setprio 1
	s_waitcnt lgkmcnt(0)
	v_mfma_i32_16x16x64_i8 v[70:73], v[58:61], v[194:197], v[70:73]
	v_mfma_i32_16x16x64_i8 v[66:69], v[74:77], v[194:197], v[66:69]
	v_mfma_i32_16x16x64_i8 v[46:49], v[58:61], v[202:205], v[46:49]
	v_mfma_i32_16x16x64_i8 v[42:45], v[74:77], v[202:205], v[42:45]
	v_mfma_i32_16x16x64_i8 v[30:33], v[58:61], v[210:213], v[30:33]
	v_mfma_i32_16x16x64_i8 v[26:29], v[74:77], v[210:213], v[26:29]
	v_mfma_i32_16x16x64_i8 v[14:17], v[58:61], v[218:221], v[14:17]
	v_mfma_i32_16x16x64_i8 v[10:13], v[74:77], v[218:221], v[10:13]
	s_setprio 0
	s_setprio 1
	v_mfma_i32_16x16x64_i8 v[70:73], v[62:65], v[198:201], v[70:73]
	v_mfma_i32_16x16x64_i8 v[66:69], v[78:81], v[198:201], v[66:69]
	v_mfma_i32_16x16x64_i8 v[46:49], v[62:65], v[206:209], v[46:49]
	v_mfma_i32_16x16x64_i8 v[42:45], v[78:81], v[206:209], v[42:45]
	v_mfma_i32_16x16x64_i8 v[30:33], v[62:65], v[214:217], v[30:33]
	v_mfma_i32_16x16x64_i8 v[26:29], v[78:81], v[214:217], v[26:29]
	v_mfma_i32_16x16x64_i8 v[14:17], v[62:65], v[222:225], v[14:17]
	v_mfma_i32_16x16x64_i8 v[10:13], v[78:81], v[222:225], v[10:13]
	s_setprio 0
	s_setprio 1
	v_mfma_i32_16x16x64_i8 v[54:57], v[162:165], v[194:197], v[54:57]
	v_mfma_i32_16x16x64_i8 v[50:53], v[170:173], v[194:197], v[50:53]
	v_mfma_i32_16x16x64_i8 v[38:41], v[162:165], v[202:205], v[38:41]
	v_mfma_i32_16x16x64_i8 v[34:37], v[170:173], v[202:205], v[34:37]
	v_mfma_i32_16x16x64_i8 v[22:25], v[162:165], v[210:213], v[22:25]
	v_mfma_i32_16x16x64_i8 v[18:21], v[170:173], v[210:213], v[18:21]
	v_mfma_i32_16x16x64_i8 v[6:9], v[162:165], v[218:221], v[6:9]
	v_mfma_i32_16x16x64_i8 v[2:5], v[170:173], v[218:221], v[2:5]
	s_setprio 0
	s_setprio 1
	v_mfma_i32_16x16x64_i8 v[54:57], v[166:169], v[198:201], v[54:57]
	v_mfma_i32_16x16x64_i8 v[50:53], v[190:193], v[198:201], v[50:53]
	v_mfma_i32_16x16x64_i8 v[38:41], v[166:169], v[206:209], v[38:41]
	v_mfma_i32_16x16x64_i8 v[34:37], v[190:193], v[206:209], v[34:37]
	v_mfma_i32_16x16x64_i8 v[22:25], v[166:169], v[214:217], v[22:25]
	v_mfma_i32_16x16x64_i8 v[18:21], v[190:193], v[214:217], v[18:21]
	v_mfma_i32_16x16x64_i8 v[6:9], v[166:169], v[222:225], v[6:9]
	v_mfma_i32_16x16x64_i8 v[2:5], v[190:193], v[222:225], v[2:5]
	s_setprio 0
	s_barrier
	s_add_i32 s40, s40, 2
	s_add_u32 s2, s2, 0x100
	s_addc_u32 s3, s3, 0
	s_add_u32 s38, s38, 0x100
	s_addc_u32 s39, s39, 0
	s_cmp_gt_u32 s40, 29
	s_cbranch_scc0 .LBB0_483
	s_and_b64 vcc, exec, s[20:21]
	s_cbranch_vccz .LBB0_486
	s_barrier

; #define PG8_STAGE(bufoff, gbase, voff) do { _Pragma("unroll") for (int _i = 0; _i < 2; ++_i) \
;         __builtin_amdgcn_global_load_lds((const unsigned*)((const char*)(gbase) + (voff)[_i]), (PG8_LAS unsigned*)(lds + (bufoff) + ldsw + _i * 8192), 16, 0, 0); } while (0)
; #define PG8_LDA(dst, b, h) do { _Pragma("unroll") for (int m = 0; m < 4; ++m) _Pragma("unroll") for (int k = 0; k < 2; ++k) dst[m][k] = *(const PG8_LAS bf16x8*)(lds + PG8_SA(b, h) + aoff + m * 2048 + k * 1024); } while (0)
; #define PG8_LDB(dst, b, h) do { _Pragma("unroll") for (int n = 0; n < 2; ++n) _Pragma("unroll") for (int k = 0; k < 2; ++k) dst[n][k] = *(const PG8_LAS bf16x8*)(lds + PG8_SB(b, h) + boff + n * 2048 + k * 1024); } while (0)
; #define PG8_MMA(ai, bj, At, Bt) do { __builtin_amdgcn_s_setprio(1); _Pragma("unroll") for (int m = 0; m < 4; ++m) _Pragma("unroll") for (int n = 0; n < 2; ++n) _Pragma("unroll") for (int k = 0; k < 2; ++k) \
;         acc[ai][bj][m][n] = mma_<I8>(Bt[n][k], At[m][k], acc[ai][bj][m][n]); __builtin_amdgcn_s_setprio(0); } while (0)
; #define PG8_WAIT_V(n) asm volatile("s_waitcnt vmcnt(" #n ")" ::: "memory")
; #define PG8_WAIT_L(n) asm volatile("s_waitcnt lgkmcnt(" #n ")" ::: "memory")
; #define PG8_BAR __builtin_amdgcn_s_barrier()
; template <class Epi, class Sched, bool ALIGN_EPI = false, bool SP2 = false, bool I8 = false>
; __device__ __forceinline__ void gemm_phase(PG8_LAS unsigned char* lds, const Gemm g, const Sched& S, const Epi& E) {
;     ...
;             const bool last = (t == nt - 2);
;             const char* a1 = cA + (size_t)(t + 1) * kstep;
;             const char* a2 = last ? nA : cA + (size_t)(t + 2) * kstep; const char* b2 = last ? nB : cB + (size_t)(t + 2) * kstep;
;             const char* a3 = a2 + kstep; const char* b3 = b2 + kstep;
;             if (last && has_next) S.a_ready(nxt);
;             if constexpr (SP2) {
;             PG8_LDB(B0, 0, 0); PG8_LDB(B1, 0, 1); PG8_SCHED; PG8_LDA(At, 0, 0); PG8_STAGE(PG8_SA(1, 1), a1 + hstepA, voffA);
;             PG8_WAIT_V(8); PG8_WAIT_L(0); PG8_BAR; PG8_MMA(0, 0, At, B0); PG8_MMA(0, 1, At, B1); PG8_BAR; PG8_SCHED;
;             PG8_LDA(At, 0, 1); PG8_STAGE(PG8_SB(0, 0), b2, voffB); PG8_STAGE(PG8_SB(0, 1), b2 + hstepB, voffB); PG8_STAGE(PG8_SA(0, 0), a2, voffA);
;             PG8_WAIT_V(8); PG8_WAIT_L(0); PG8_BAR; PG8_MMA(1, 0, At, B0); PG8_MMA(1, 1, At, B1); PG8_BAR; PG8_SCHED;
.LBB0_541:
	ds_read_b128 v[154:157], v149
	ds_read_b128 v[158:161], v149 offset:1024
	ds_read_b128 v[162:165], v149 offset:2048
	ds_read_b128 v[166:169], v149 offset:3072
	ds_read_b128 v[170:173], v151
	ds_read_b128 v[174:177], v151 offset:1024
	ds_read_b128 v[178:181], v151 offset:2048
	ds_read_b128 v[188:191], v151 offset:3072
	s_add_u32 s34, s30, 0xfff00080
	s_addc_u32 s35, s31, -1
	s_cmp_eq_u32 s94, 60
	s_cselect_b32 s37, s7, s35
	s_cselect_b32 s36, s25, s34
	s_cselect_b32 s35, s23, s93
	s_cselect_b32 s34, s29, s92
	v_lshl_add_u64 v[224:225], s[30:31], 0, v[138:139]
	s_add_i32 m0, s39, 0xc000
	ds_read_b128 v[192:195], v153
	ds_read_b128 v[196:199], v153 offset:1024
	ds_read_b128 v[200:203], v153 offset:2048
	ds_read_b128 v[204:207], v153 offset:3072
	ds_read_b128 v[208:211], v153 offset:4096
	ds_read_b128 v[212:215], v153 offset:5120
	ds_read_b128 v[216:219], v153 offset:6144
	ds_read_b128 v[220:223], v153 offset:7168
	global_load_lds_dwordx4 v[224:225], off
	v_lshl_add_u64 v[224:225], s[30:31], 0, v[140:141]
	s_add_i32 m0, s39, 0xe000
	s_nop 0
	global_load_lds_dwordx4 v[224:225], off
	s_waitcnt vmcnt(8)
	s_waitcnt lgkmcnt(0)
	s_barrier
	s_setprio 1
	s_waitcnt lgkmcnt(0)
	v_mfma_f32_16x16x32_bf16 v[126:129], v[154:157], v[192:195], v[126:129]
	v_mfma_f32_16x16x32_bf16 v[122:125], v[162:165], v[192:195], v[122:125]
	v_mfma_f32_16x16x32_bf16 v[110:113], v[154:157], v[200:203], v[110:113]
	v_mfma_f32_16x16x32_bf16 v[106:109], v[162:165], v[200:203], v[106:109]
	v_mfma_f32_16x16x32_bf16 v[94:97], v[154:157], v[208:211], v[94:97]
	v_mfma_f32_16x16x32_bf16 v[90:93], v[162:165], v[208:211], v[90:93]
	v_mfma_f32_16x16x32_bf16 v[78:81], v[154:157], v[216:219], v[78:81]
	v_mfma_f32_16x16x32_bf16 v[74:77], v[162:165], v[216:219], v[74:77]
	s_setprio 0
	s_setprio 1
	v_mfma_f32_16x16x32_bf16 v[126:129], v[158:161], v[196:199], v[126:129]
	v_mfma_f32_16x16x32_bf16 v[122:125], v[166:169], v[196:199], v[122:125]
	v_mfma_f32_16x16x32_bf16 v[110:113], v[158:161], v[204:207], v[110:113]
	v_mfma_f32_16x16x32_bf16 v[106:109], v[166:169], v[204:207], v[106:109]
	v_mfma_f32_16x16x32_bf16 v[94:97], v[158:161], v[212:215], v[94:97]
	v_mfma_f32_16x16x32_bf16 v[90:93], v[166:169], v[212:215], v[90:93]
	v_mfma_f32_16x16x32_bf16 v[78:81], v[158:161], v[220:223], v[78:81]
	v_mfma_f32_16x16x32_bf16 v[74:77], v[166:169], v[220:223], v[74:77]
	s_setprio 0
	s_setprio 1
	v_mfma_f32_16x16x32_bf16 v[118:121], v[170:173], v[192:195], v[118:121]
	v_mfma_f32_16x16x32_bf16 v[114:117], v[178:181], v[192:195], v[114:117]
	v_mfma_f32_16x16x32_bf16 v[102:105], v[170:173], v[200:203], v[102:105]
	v_mfma_f32_16x16x32_bf16 v[98:101], v[178:181], v[200:203], v[98:101]
	v_mfma_f32_16x16x32_bf16 v[86:89], v[170:173], v[208:211], v[86:89]
	v_mfma_f32_16x16x32_bf16 v[82:85], v[178:181], v[208:211], v[82:85]
	v_mfma_f32_16x16x32_bf16 v[70:73], v[170:173], v[216:219], v[70:73]
	v_mfma_f32_16x16x32_bf16 v[66:69], v[178:181], v[216:219], v[66:69]
	s_setprio 0
	s_setprio 1
	v_mfma_f32_16x16x32_bf16 v[118:121], v[174:177], v[196:199], v[118:121]
	v_mfma_f32_16x16x32_bf16 v[114:117], v[188:191], v[196:199], v[114:117]
	v_mfma_f32_16x16x32_bf16 v[102:105], v[174:177], v[204:207], v[102:105]
	v_mfma_f32_16x16x32_bf16 v[98:101], v[188:191], v[204:207], v[98:101]
	v_mfma_f32_16x16x32_bf16 v[86:89], v[174:177], v[212:215], v[86:89]
	v_mfma_f32_16x16x32_bf16 v[82:85], v[188:191], v[212:215], v[82:85]
	v_mfma_f32_16x16x32_bf16 v[70:73], v[174:177], v[220:223], v[70:73]
	v_mfma_f32_16x16x32_bf16 v[66:69], v[188:191], v[220:223], v[66:69]
	s_setprio 0
	s_barrier
	s_add_i32 s95, s88, s38
	v_lshl_add_u64 v[224:225], s[34:35], 0, v[132:133]
	s_mov_b32 m0, s95
	ds_read_b128 v[192:195], v153 offset:16384
	ds_read_b128 v[196:199], v153 offset:17408
	ds_read_b128 v[200:203], v153 offset:18432
	ds_read_b128 v[204:207], v153 offset:19456
	ds_read_b128 v[208:211], v153 offset:20480
	ds_read_b128 v[212:215], v153 offset:21504
	ds_read_b128 v[216:219], v153 offset:22528
	ds_read_b128 v[220:223], v153 offset:23552
	global_load_lds_dwordx4 v[224:225], off
	s_add_i32 m0, s95, 0x2000
	s_add_u32 vcc_lo, s34, 0x100000
	v_lshl_add_u64 v[226:227], s[34:35], 0, v[136:137]
	s_addc_u32 vcc_hi, s35, 0
	s_add_i32 s95, s89, s38
	global_load_lds_dwordx4 v[226:227], off
	v_lshl_add_u64 v[228:229], vcc, 0, v[132:133]
	s_mov_b32 m0, s95
	v_lshl_add_u64 v[230:231], s[36:37], 0, v[134:135]
	global_load_lds_dwordx4 v[228:229], off
	v_lshl_add_u64 v[228:229], vcc, 0, v[136:137]
	s_add_i32 m0, s95, 0x2000
	s_nop 0
	global_load_lds_dwordx4 v[228:229], off
	v_lshl_add_u64 v[228:229], s[36:37], 0, v[130:131]
	s_mov_b32 m0, s39
	s_nop 0
	global_load_lds_dwordx4 v[228:229], off
	s_mov_b32 m0, s40
	s_nop 0
	global_load_lds_dwordx4 v[230:231], off
	s_waitcnt vmcnt(8)
	s_waitcnt lgkmcnt(0)
	s_barrier
; #define PG8_STAGE(bufoff, gbase, voff) do { _Pragma("unroll") for (int _i = 0; _i < 2; ++_i) \
;         __builtin_amdgcn_global_load_lds((const unsigned*)((const char*)(gbase) + (voff)[_i]), (PG8_LAS unsigned*)(lds + (bufoff) + ldsw + _i * 8192), 16, 0, 0); } while (0)
; #define PG8_LDA(dst, b, h) do { _Pragma("unroll") for (int m = 0; m < 4; ++m) _Pragma("unroll") for (int k = 0; k < 2; ++k) dst[m][k] = *(const PG8_LAS bf16x8*)(lds + PG8_SA(b, h) + aoff + m * 2048 + k * 1024); } while (0)
; #define PG8_LDB(dst, b, h) do { _Pragma("unroll") for (int n = 0; n < 2; ++n) _Pragma("unroll") for (int k = 0; k < 2; ++k) dst[n][k] = *(const PG8_LAS bf16x8*)(lds + PG8_SB(b, h) + boff + n * 2048 + k * 1024); } while (0)
; #define PG8_MMA(ai, bj, At, Bt) do { __builtin_amdgcn_s_setprio(1); _Pragma("unroll") for (int m = 0; m < 4; ++m) _Pragma("unroll") for (int n = 0; n < 2; ++n) _Pragma("unroll") for (int k = 0; k < 2; ++k) \
;         acc[ai][bj][m][n] = mma_<I8>(Bt[n][k], At[m][k], acc[ai][bj][m][n]); __builtin_amdgcn_s_setprio(0); } while (0)
; #define PG8_WAIT_V(n) asm volatile("s_waitcnt vmcnt(" #n ")" ::: "memory")
; #define PG8_WAIT_L(n) asm volatile("s_waitcnt lgkmcnt(" #n ")" ::: "memory")
; #define PG8_BAR __builtin_amdgcn_s_barrier()
; #define PG8_SCHED __builtin_amdgcn_sched_barrier(0)
; template <class Epi, class Sched, bool ALIGN_EPI = false, bool SP2 = false, bool I8 = false>
; __device__ __forceinline__ void gemm_phase(PG8_LAS unsigned char* lds, const Gemm g, const Sched& S, const Epi& E) {
;     ...
;             PG8_WAIT_V(8); PG8_WAIT_L(0); PG8_BAR; PG8_MMA(1, 0, At, B0); PG8_MMA(1, 1, At, B1); PG8_BAR; PG8_SCHED;
;             PG8_LDB(B0, 1, 0); PG8_LDB(B1, 1, 1); PG8_SCHED; PG8_LDA(At, 1, 0); PG8_STAGE(PG8_SA(0, 1), a2 + hstepA, voffA);
;             PG8_WAIT_V(8); PG8_WAIT_L(0); PG8_BAR; PG8_MMA(0, 0, At, B0); PG8_MMA(0, 1, At, B1); PG8_BAR; PG8_SCHED;
	s_setprio 1
	s_waitcnt lgkmcnt(0)
	v_mfma_f32_16x16x32_bf16 v[62:65], v[154:157], v[192:195], v[62:65]
	v_mfma_f32_16x16x32_bf16 v[58:61], v[162:165], v[192:195], v[58:61]
	v_mfma_f32_16x16x32_bf16 v[46:49], v[154:157], v[200:203], v[46:49]
	v_mfma_f32_16x16x32_bf16 v[42:45], v[162:165], v[200:203], v[42:45]
	v_mfma_f32_16x16x32_bf16 v[30:33], v[154:157], v[208:211], v[30:33]
	v_mfma_f32_16x16x32_bf16 v[26:29], v[162:165], v[208:211], v[26:29]
	v_mfma_f32_16x16x32_bf16 v[14:17], v[154:157], v[216:219], v[14:17]
	v_mfma_f32_16x16x32_bf16 v[10:13], v[162:165], v[216:219], v[10:13]
	s_setprio 0
	s_setprio 1
	v_mfma_f32_16x16x32_bf16 v[62:65], v[158:161], v[196:199], v[62:65]
	v_mfma_f32_16x16x32_bf16 v[58:61], v[166:169], v[196:199], v[58:61]
	v_mfma_f32_16x16x32_bf16 v[46:49], v[158:161], v[204:207], v[46:49]
	v_mfma_f32_16x16x32_bf16 v[42:45], v[166:169], v[204:207], v[42:45]
	v_mfma_f32_16x16x32_bf16 v[30:33], v[158:161], v[212:215], v[30:33]
	v_mfma_f32_16x16x32_bf16 v[26:29], v[166:169], v[212:215], v[26:29]
	v_mfma_f32_16x16x32_bf16 v[14:17], v[158:161], v[220:223], v[14:17]
	v_mfma_f32_16x16x32_bf16 v[10:13], v[166:169], v[220:223], v[10:13]
	s_setprio 0
	s_setprio 1
	v_mfma_f32_16x16x32_bf16 v[54:57], v[170:173], v[192:195], v[54:57]
	v_mfma_f32_16x16x32_bf16 v[50:53], v[178:181], v[192:195], v[50:53]
	v_mfma_f32_16x16x32_bf16 v[38:41], v[170:173], v[200:203], v[38:41]
	v_mfma_f32_16x16x32_bf16 v[34:37], v[178:181], v[200:203], v[34:37]
	v_mfma_f32_16x16x32_bf16 v[22:25], v[170:173], v[208:211], v[22:25]
	v_mfma_f32_16x16x32_bf16 v[18:21], v[178:181], v[208:211], v[18:21]
	v_mfma_f32_16x16x32_bf16 v[6:9], v[170:173], v[216:219], v[6:9]
	v_mfma_f32_16x16x32_bf16 v[2:5], v[178:181], v[216:219], v[2:5]
	s_setprio 0
	s_setprio 1
	v_mfma_f32_16x16x32_bf16 v[54:57], v[174:177], v[196:199], v[54:57]
	v_mfma_f32_16x16x32_bf16 v[50:53], v[188:191], v[196:199], v[50:53]
	v_mfma_f32_16x16x32_bf16 v[38:41], v[174:177], v[204:207], v[38:41]
	v_mfma_f32_16x16x32_bf16 v[34:37], v[188:191], v[204:207], v[34:37]
	v_mfma_f32_16x16x32_bf16 v[22:25], v[174:177], v[212:215], v[22:25]
	v_mfma_f32_16x16x32_bf16 v[18:21], v[188:191], v[212:215], v[18:21]
	v_mfma_f32_16x16x32_bf16 v[6:9], v[174:177], v[220:223], v[6:9]
	v_mfma_f32_16x16x32_bf16 v[2:5], v[188:191], v[220:223], v[2:5]
	s_setprio 0
	s_barrier
	s_add_i32 s95, 0, 0x18000
	s_add_i32 vcc_lo, 0, 0x1c000
	v_add_u32_e32 v166, s95, v147
	v_add_u32_e32 v187, vcc_lo, v147
	ds_read_b128 v[154:157], v166
	ds_read_b128 v[158:161], v166 offset:1024
	ds_read_b128 v[162:165], v166 offset:2048
	ds_read_b128 v[166:169], v166 offset:3072
	ds_read_b128 v[170:173], v187
	ds_read_b128 v[174:177], v187 offset:1024
	ds_read_b128 v[178:181], v187 offset:2048
	ds_read_b128 v[188:191], v187 offset:3072
	s_add_u32 s36, s36, 0x100000
	s_addc_u32 s37, s37, 0
	s_mov_b32 m0, s41
	v_lshl_add_u64 v[234:235], s[36:37], 0, v[130:131]
	ds_read_b128 v[192:195], v153 offset:32768
	ds_read_b128 v[196:199], v153 offset:33792
	ds_read_b128 v[200:203], v153 offset:34816
	ds_read_b128 v[204:207], v153 offset:35840
	ds_read_b128 v[208:211], v153 offset:36864
	ds_read_b128 v[212:215], v153 offset:37888
	ds_read_b128 v[216:219], v153 offset:38912
	ds_read_b128 v[220:223], v153 offset:39936
	global_load_lds_dwordx4 v[234:235], off
	v_lshl_add_u64 v[234:235], s[36:37], 0, v[134:135]
	s_mov_b32 m0, s46
	s_nop 0
	global_load_lds_dwordx4 v[234:235], off
	s_waitcnt vmcnt(8)
	s_waitcnt lgkmcnt(0)
	s_barrier
	s_setprio 1
	s_waitcnt lgkmcnt(0)
	v_mfma_f32_16x16x32_bf16 v[126:129], v[154:157], v[192:195], v[126:129]
	v_mfma_f32_16x16x32_bf16 v[122:125], v[162:165], v[192:195], v[122:125]
	v_mfma_f32_16x16x32_bf16 v[110:113], v[154:157], v[200:203], v[110:113]
	v_mfma_f32_16x16x32_bf16 v[106:109], v[162:165], v[200:203], v[106:109]
	v_mfma_f32_16x16x32_bf16 v[94:97], v[154:157], v[208:211], v[94:97]
	v_mfma_f32_16x16x32_bf16 v[90:93], v[162:165], v[208:211], v[90:93]
	v_mfma_f32_16x16x32_bf16 v[78:81], v[154:157], v[216:219], v[78:81]
	v_mfma_f32_16x16x32_bf16 v[74:77], v[162:165], v[216:219], v[74:77]
	s_setprio 0
	s_setprio 1
	v_mfma_f32_16x16x32_bf16 v[126:129], v[158:161], v[196:199], v[126:129]
	v_mfma_f32_16x16x32_bf16 v[122:125], v[166:169], v[196:199], v[122:125]
	v_mfma_f32_16x16x32_bf16 v[110:113], v[158:161], v[204:207], v[110:113]
	v_mfma_f32_16x16x32_bf16 v[106:109], v[166:169], v[204:207], v[106:109]
	v_mfma_f32_16x16x32_bf16 v[94:97], v[158:161], v[212:215], v[94:97]
	v_mfma_f32_16x16x32_bf16 v[90:93], v[166:169], v[212:215], v[90:93]
	v_mfma_f32_16x16x32_bf16 v[78:81], v[158:161], v[220:223], v[78:81]
	v_mfma_f32_16x16x32_bf16 v[74:77], v[166:169], v[220:223], v[74:77]
	s_setprio 0
	s_setprio 1
	v_mfma_f32_16x16x32_bf16 v[118:121], v[170:173], v[192:195], v[118:121]
	v_mfma_f32_16x16x32_bf16 v[114:117], v[178:181], v[192:195], v[114:117]
	v_mfma_f32_16x16x32_bf16 v[102:105], v[170:173], v[200:203], v[102:105]
	v_mfma_f32_16x16x32_bf16 v[98:101], v[178:181], v[200:203], v[98:101]
	v_mfma_f32_16x16x32_bf16 v[86:89], v[170:173], v[208:211], v[86:89]
	v_mfma_f32_16x16x32_bf16 v[82:85], v[178:181], v[208:211], v[82:85]
	v_mfma_f32_16x16x32_bf16 v[70:73], v[170:173], v[216:219], v[70:73]
	v_mfma_f32_16x16x32_bf16 v[66:69], v[178:181], v[216:219], v[66:69]
	s_setprio 0
	s_setprio 1
	v_mfma_f32_16x16x32_bf16 v[118:121], v[174:177], v[196:199], v[118:121]
	v_mfma_f32_16x16x32_bf16 v[114:117], v[188:191], v[196:199], v[114:117]
	v_mfma_f32_16x16x32_bf16 v[102:105], v[174:177], v[204:207], v[102:105]
	v_mfma_f32_16x16x32_bf16 v[98:101], v[188:191], v[204:207], v[98:101]
	v_mfma_f32_16x16x32_bf16 v[86:89], v[174:177], v[212:215], v[86:89]
	v_mfma_f32_16x16x32_bf16 v[82:85], v[188:191], v[212:215], v[82:85]
	v_mfma_f32_16x16x32_bf16 v[70:73], v[174:177], v[220:223], v[70:73]
	v_mfma_f32_16x16x32_bf16 v[66:69], v[188:191], v[220:223], v[66:69]
	s_setprio 0
	s_barrier
; #define PG8_STAGE(bufoff, gbase, voff) do { _Pragma("unroll") for (int _i = 0; _i < 2; ++_i) \
;         __builtin_amdgcn_global_load_lds((const unsigned*)((const char*)(gbase) + (voff)[_i]), (PG8_LAS unsigned*)(lds + (bufoff) + ldsw + _i * 8192), 16, 0, 0); } while (0)
; #define PG8_LDA(dst, b, h) do { _Pragma("unroll") for (int m = 0; m < 4; ++m) _Pragma("unroll") for (int k = 0; k < 2; ++k) dst[m][k] = *(const PG8_LAS bf16x8*)(lds + PG8_SA(b, h) + aoff + m * 2048 + k * 1024); } while (0)
; #define PG8_MMA(ai, bj, At, Bt) do { __builtin_amdgcn_s_setprio(1); _Pragma("unroll") for (int m = 0; m < 4; ++m) _Pragma("unroll") for (int n = 0; n < 2; ++n) _Pragma("unroll") for (int k = 0; k < 2; ++k) \
;         acc[ai][bj][m][n] = mma_<I8>(Bt[n][k], At[m][k], acc[ai][bj][m][n]); __builtin_amdgcn_s_setprio(0); } while (0)
; #define PG8_WAIT_V(n) asm volatile("s_waitcnt vmcnt(" #n ")" ::: "memory")
; #define PG8_WAIT_L(n) asm volatile("s_waitcnt lgkmcnt(" #n ")" ::: "memory")
; #define PG8_BAR __builtin_amdgcn_s_barrier()
; #define PG8_SCHED __builtin_amdgcn_sched_barrier(0)
; template <class Epi, class Sched, bool ALIGN_EPI = false, bool SP2 = false, bool I8 = false>
; __device__ __forceinline__ void gemm_phase(PG8_LAS unsigned char* lds, const Gemm g, const Sched& S, const Epi& E) {
;     ...
;             PG8_LDA(At, 1, 1); PG8_STAGE(PG8_SB(1, 0), b3, voffB); PG8_STAGE(PG8_SB(1, 1), b3 + hstepB, voffB); PG8_STAGE(PG8_SA(1, 0), a3, voffA);
;             PG8_WAIT_V(8); PG8_WAIT_L(0); PG8_BAR; PG8_MMA(1, 0, At, B0); PG8_MMA(1, 1, At, B1); PG8_BAR; PG8_SCHED;
;     ...
;         if constexpr (ALIGN_EPI) { if (wr == 0) PG8_BAR; }
	s_add_i32 s36, s95, s38
	v_lshl_add_u64 v[224:225], v[224:225], 0, s[18:19]
	s_mov_b32 m0, s36
	ds_read_b128 v[192:195], v153 offset:49152
	ds_read_b128 v[196:199], v153 offset:50176
	ds_read_b128 v[200:203], v153 offset:51200
	ds_read_b128 v[204:207], v153 offset:52224
	ds_read_b128 v[208:211], v153 offset:53248
	ds_read_b128 v[212:215], v153 offset:54272
	ds_read_b128 v[216:219], v153 offset:55296
	ds_read_b128 v[220:223], v153 offset:56320
	global_load_lds_dwordx4 v[224:225], off
	s_add_i32 m0, s36, 0x2000
	s_add_u32 s34, s34, 0x100080
	v_lshl_add_u64 v[224:225], v[226:227], 0, s[18:19]
	s_addc_u32 s35, s35, 0
	s_add_i32 s36, vcc_lo, s38
	global_load_lds_dwordx4 v[224:225], off
	v_lshl_add_u64 v[224:225], s[34:35], 0, v[132:133]
	s_mov_b32 m0, s36
	s_nop 0
	global_load_lds_dwordx4 v[224:225], off
	v_lshl_add_u64 v[224:225], s[34:35], 0, v[136:137]
	s_add_i32 m0, s36, 0x2000
	s_nop 0
	global_load_lds_dwordx4 v[224:225], off
	v_lshl_add_u64 v[224:225], v[228:229], 0, s[18:19]
	s_mov_b32 m0, s68
	s_nop 0
	global_load_lds_dwordx4 v[224:225], off
	v_lshl_add_u64 v[224:225], v[230:231], 0, s[18:19]
	s_mov_b32 m0, s69
	s_nop 0
	global_load_lds_dwordx4 v[224:225], off
	s_waitcnt vmcnt(8)
	s_waitcnt lgkmcnt(0)
	s_barrier
	s_setprio 1
	s_waitcnt lgkmcnt(0)
	v_mfma_f32_16x16x32_bf16 v[62:65], v[154:157], v[192:195], v[62:65]
	v_mfma_f32_16x16x32_bf16 v[58:61], v[162:165], v[192:195], v[58:61]
	v_mfma_f32_16x16x32_bf16 v[46:49], v[154:157], v[200:203], v[46:49]
	v_mfma_f32_16x16x32_bf16 v[42:45], v[162:165], v[200:203], v[42:45]
	v_mfma_f32_16x16x32_bf16 v[30:33], v[154:157], v[208:211], v[30:33]
	v_mfma_f32_16x16x32_bf16 v[26:29], v[162:165], v[208:211], v[26:29]
	v_mfma_f32_16x16x32_bf16 v[14:17], v[154:157], v[216:219], v[14:17]
	v_mfma_f32_16x16x32_bf16 v[10:13], v[162:165], v[216:219], v[10:13]
	s_setprio 0
	s_setprio 1
	v_mfma_f32_16x16x32_bf16 v[62:65], v[158:161], v[196:199], v[62:65]
	v_mfma_f32_16x16x32_bf16 v[58:61], v[166:169], v[196:199], v[58:61]
	v_mfma_f32_16x16x32_bf16 v[46:49], v[158:161], v[204:207], v[46:49]
	v_mfma_f32_16x16x32_bf16 v[42:45], v[166:169], v[204:207], v[42:45]
	v_mfma_f32_16x16x32_bf16 v[30:33], v[158:161], v[212:215], v[30:33]
	v_mfma_f32_16x16x32_bf16 v[26:29], v[166:169], v[212:215], v[26:29]
	v_mfma_f32_16x16x32_bf16 v[14:17], v[158:161], v[220:223], v[14:17]
	v_mfma_f32_16x16x32_bf16 v[10:13], v[166:169], v[220:223], v[10:13]
	s_setprio 0
	s_setprio 1
	v_mfma_f32_16x16x32_bf16 v[54:57], v[170:173], v[192:195], v[54:57]
	v_mfma_f32_16x16x32_bf16 v[50:53], v[178:181], v[192:195], v[50:53]
	v_mfma_f32_16x16x32_bf16 v[38:41], v[170:173], v[200:203], v[38:41]
	v_mfma_f32_16x16x32_bf16 v[34:37], v[178:181], v[200:203], v[34:37]
	v_mfma_f32_16x16x32_bf16 v[22:25], v[170:173], v[208:211], v[22:25]
	v_mfma_f32_16x16x32_bf16 v[18:21], v[178:181], v[208:211], v[18:21]
	v_mfma_f32_16x16x32_bf16 v[6:9], v[170:173], v[216:219], v[6:9]
	v_mfma_f32_16x16x32_bf16 v[2:5], v[178:181], v[216:219], v[2:5]
	s_setprio 0
	s_setprio 1
	v_mfma_f32_16x16x32_bf16 v[54:57], v[174:177], v[196:199], v[54:57]
	v_mfma_f32_16x16x32_bf16 v[50:53], v[188:191], v[196:199], v[50:53]
	v_mfma_f32_16x16x32_bf16 v[38:41], v[174:177], v[204:207], v[38:41]
	v_mfma_f32_16x16x32_bf16 v[34:37], v[188:191], v[204:207], v[34:37]
	v_mfma_f32_16x16x32_bf16 v[22:25], v[174:177], v[212:215], v[22:25]
	v_mfma_f32_16x16x32_bf16 v[18:21], v[188:191], v[212:215], v[18:21]
	v_mfma_f32_16x16x32_bf16 v[6:9], v[174:177], v[220:223], v[6:9]
	v_mfma_f32_16x16x32_bf16 v[2:5], v[188:191], v[220:223], v[2:5]
	s_setprio 0
	s_barrier
	s_add_i32 s94, s94, 2
	s_add_u32 s30, s30, 0x100
	s_addc_u32 s31, s31, 0
	s_add_u32 s92, s92, 0x100
	s_addc_u32 s93, s93, 0
	s_cmp_gt_u32 s94, 61
	s_cbranch_scc0 .LBB0_541
	s_and_b64 vcc, exec, s[20:21]
	s_cbranch_vccz .LBB0_544
	s_barrier

; #define PG8_STAGE(bufoff, gbase, voff) do { _Pragma("unroll") for (int _i = 0; _i < 2; ++_i) \
;         __builtin_amdgcn_global_load_lds((const unsigned*)((const char*)(gbase) + (voff)[_i]), (PG8_LAS unsigned*)(lds + (bufoff) + ldsw + _i * 8192), 16, 0, 0); } while (0)
; #define PG8_LDA(dst, b, h) do { _Pragma("unroll") for (int m = 0; m < 4; ++m) _Pragma("unroll") for (int k = 0; k < 2; ++k) dst[m][k] = *(const PG8_LAS bf16x8*)(lds + PG8_SA(b, h) + aoff + m * 2048 + k * 1024); } while (0)
; #define PG8_LDB(dst, b, h) do { _Pragma("unroll") for (int n = 0; n < 2; ++n) _Pragma("unroll") for (int k = 0; k < 2; ++k) dst[n][k] = *(const PG8_LAS bf16x8*)(lds + PG8_SB(b, h) + boff + n * 2048 + k * 1024); } while (0)
; #define PG8_MMA(ai, bj, At, Bt) do { __builtin_amdgcn_s_setprio(1); _Pragma("unroll") for (int m = 0; m < 4; ++m) _Pragma("unroll") for (int n = 0; n < 2; ++n) _Pragma("unroll") for (int k = 0; k < 2; ++k) \
;         acc[ai][bj][m][n] = mma_<I8>(Bt[n][k], At[m][k], acc[ai][bj][m][n]); __builtin_amdgcn_s_setprio(0); } while (0)
; #define PG8_WAIT_V(n) asm volatile("s_waitcnt vmcnt(" #n ")" ::: "memory")
; #define PG8_WAIT_L(n) asm volatile("s_waitcnt lgkmcnt(" #n ")" ::: "memory")
; #define PG8_BAR __builtin_amdgcn_s_barrier()
; template <class Epi, class Sched, bool ALIGN_EPI = false, bool SP2 = false, bool I8 = false>
; __device__ __forceinline__ void gemm_phase(PG8_LAS unsigned char* lds, const Gemm g, const Sched& S, const Epi& E) {
;     ...
;             const bool last = (t == nt - 2);
;             const char* a1 = cA + (size_t)(t + 1) * kstep;
;             const char* a2 = last ? nA : cA + (size_t)(t + 2) * kstep; const char* b2 = last ? nB : cB + (size_t)(t + 2) * kstep;
;             const char* a3 = a2 + kstep; const char* b3 = b2 + kstep;
;             if (last && has_next) S.a_ready(nxt);
;             if constexpr (SP2) {
;             PG8_LDB(B0, 0, 0); PG8_LDB(B1, 0, 1); PG8_SCHED; PG8_LDA(At, 0, 0); PG8_STAGE(PG8_SA(1, 1), a1 + hstepA, voffA);
;             PG8_WAIT_V(8); PG8_WAIT_L(0); PG8_BAR; PG8_MMA(0, 0, At, B0); PG8_MMA(0, 1, At, B1); PG8_BAR; PG8_SCHED;
;             PG8_LDA(At, 0, 1); PG8_STAGE(PG8_SB(0, 0), b2, voffB); PG8_STAGE(PG8_SB(0, 1), b2 + hstepB, voffB); PG8_STAGE(PG8_SA(0, 0), a2, voffA);
;             PG8_WAIT_V(8); PG8_WAIT_L(0); PG8_BAR; PG8_MMA(1, 0, At, B0); PG8_MMA(1, 1, At, B1); PG8_BAR; PG8_SCHED;
.LBB0_607:
	ds_read_b128 v[58:61], v177
	ds_read_b128 v[62:65], v177 offset:1024
	ds_read_b128 v[74:77], v177 offset:2048
	ds_read_b128 v[78:81], v177 offset:3072
	ds_read_b128 v[162:165], v178
	ds_read_b128 v[166:169], v178 offset:1024
	ds_read_b128 v[170:173], v178 offset:2048
	ds_read_b128 v[180:183], v178 offset:3072
	s_add_u32 s34, s2, 0xfff80080
	s_addc_u32 s35, s3, -1
	s_cmp_eq_u32 s39, 28
	s_cselect_b32 s37, s7, s35
	s_cselect_b32 s36, s9, s34
	s_cselect_b32 s35, s23, s38
	s_cselect_b32 s34, s25, s31
	v_lshl_add_u64 v[174:175], s[2:3], 0, v[154:155]
	s_add_i32 m0, s69, 0xc000
	ds_read_b128 v[184:187], v179
	ds_read_b128 v[188:191], v179 offset:1024
	ds_read_b128 v[192:195], v179 offset:2048
	ds_read_b128 v[196:199], v179 offset:3072
	ds_read_b128 v[200:203], v179 offset:4096
	ds_read_b128 v[204:207], v179 offset:5120
	ds_read_b128 v[208:211], v179 offset:6144
	ds_read_b128 v[212:215], v179 offset:7168
	global_load_lds_dwordx4 v[174:175], off
	v_lshl_add_u64 v[174:175], s[2:3], 0, v[156:157]
	s_add_i32 m0, s69, 0xe000
	s_nop 0
	global_load_lds_dwordx4 v[174:175], off
	s_waitcnt vmcnt(8)
	s_waitcnt lgkmcnt(0)
	s_barrier
	s_setprio 1
	s_waitcnt lgkmcnt(0)
	v_mfma_i32_16x16x64_i8 v[142:145], v[58:61], v[184:187], v[142:145]
	v_mfma_i32_16x16x64_i8 v[138:141], v[74:77], v[184:187], v[138:141]
	v_mfma_i32_16x16x64_i8 v[126:129], v[58:61], v[192:195], v[126:129]
	v_mfma_i32_16x16x64_i8 v[122:125], v[74:77], v[192:195], v[122:125]
	v_mfma_i32_16x16x64_i8 v[110:113], v[58:61], v[200:203], v[110:113]
	v_mfma_i32_16x16x64_i8 v[106:109], v[74:77], v[200:203], v[106:109]
	v_mfma_i32_16x16x64_i8 v[94:97], v[58:61], v[208:211], v[94:97]
	v_mfma_i32_16x16x64_i8 v[90:93], v[74:77], v[208:211], v[90:93]
	s_setprio 0
	s_setprio 1
	v_mfma_i32_16x16x64_i8 v[142:145], v[62:65], v[188:191], v[142:145]
	v_mfma_i32_16x16x64_i8 v[138:141], v[78:81], v[188:191], v[138:141]
	v_mfma_i32_16x16x64_i8 v[126:129], v[62:65], v[196:199], v[126:129]
	v_mfma_i32_16x16x64_i8 v[122:125], v[78:81], v[196:199], v[122:125]
	v_mfma_i32_16x16x64_i8 v[110:113], v[62:65], v[204:207], v[110:113]
	v_mfma_i32_16x16x64_i8 v[106:109], v[78:81], v[204:207], v[106:109]
	v_mfma_i32_16x16x64_i8 v[94:97], v[62:65], v[212:215], v[94:97]
	v_mfma_i32_16x16x64_i8 v[90:93], v[78:81], v[212:215], v[90:93]
	s_setprio 0
	s_setprio 1
	v_mfma_i32_16x16x64_i8 v[134:137], v[162:165], v[184:187], v[134:137]
	v_mfma_i32_16x16x64_i8 v[130:133], v[170:173], v[184:187], v[130:133]
	v_mfma_i32_16x16x64_i8 v[118:121], v[162:165], v[192:195], v[118:121]
	v_mfma_i32_16x16x64_i8 v[114:117], v[170:173], v[192:195], v[114:117]
	v_mfma_i32_16x16x64_i8 v[102:105], v[162:165], v[200:203], v[102:105]
	v_mfma_i32_16x16x64_i8 v[98:101], v[170:173], v[200:203], v[98:101]
	v_mfma_i32_16x16x64_i8 v[86:89], v[162:165], v[208:211], v[86:89]
	v_mfma_i32_16x16x64_i8 v[82:85], v[170:173], v[208:211], v[82:85]
	s_setprio 0
	s_setprio 1
	v_mfma_i32_16x16x64_i8 v[134:137], v[166:169], v[188:191], v[134:137]
	v_mfma_i32_16x16x64_i8 v[130:133], v[180:183], v[188:191], v[130:133]
	v_mfma_i32_16x16x64_i8 v[118:121], v[166:169], v[196:199], v[118:121]
	v_mfma_i32_16x16x64_i8 v[114:117], v[180:183], v[196:199], v[114:117]
	v_mfma_i32_16x16x64_i8 v[102:105], v[166:169], v[204:207], v[102:105]
	v_mfma_i32_16x16x64_i8 v[98:101], v[180:183], v[204:207], v[98:101]
	v_mfma_i32_16x16x64_i8 v[86:89], v[166:169], v[212:215], v[86:89]
	v_mfma_i32_16x16x64_i8 v[82:85], v[180:183], v[212:215], v[82:85]
	s_setprio 0
	s_barrier
	s_add_i32 s40, s33, s68
	v_lshl_add_u64 v[174:175], s[34:35], 0, v[148:149]
	s_mov_b32 m0, s40
	ds_read_b128 v[184:187], v179 offset:16384
	ds_read_b128 v[188:191], v179 offset:17408
	ds_read_b128 v[192:195], v179 offset:18432
	ds_read_b128 v[196:199], v179 offset:19456
	ds_read_b128 v[200:203], v179 offset:20480
	ds_read_b128 v[204:207], v179 offset:21504
	ds_read_b128 v[208:211], v179 offset:22528
	ds_read_b128 v[212:215], v179 offset:23552
	global_load_lds_dwordx4 v[174:175], off
	s_add_i32 m0, s40, 0x2000
	s_add_u32 s40, s34, 0x80000
	v_lshl_add_u64 v[216:217], s[34:35], 0, v[152:153]
	s_addc_u32 s41, s35, 0
	s_add_i32 vcc_lo, s8, s68
	global_load_lds_dwordx4 v[216:217], off
	v_lshl_add_u64 v[218:219], s[40:41], 0, v[148:149]
	s_mov_b32 m0, vcc_lo
	v_lshl_add_u64 v[220:221], s[36:37], 0, v[150:151]
	global_load_lds_dwordx4 v[218:219], off
	v_lshl_add_u64 v[218:219], s[40:41], 0, v[152:153]
	s_add_i32 m0, vcc_lo, 0x2000
	s_nop 0
	global_load_lds_dwordx4 v[218:219], off
	v_lshl_add_u64 v[218:219], s[36:37], 0, v[146:147]
	s_mov_b32 m0, s69
	s_nop 0
	global_load_lds_dwordx4 v[218:219], off
	s_mov_b32 m0, s70
	s_nop 0
	global_load_lds_dwordx4 v[220:221], off
	s_waitcnt vmcnt(8)
	s_waitcnt lgkmcnt(0)
	s_barrier
; #define PG8_STAGE(bufoff, gbase, voff) do { _Pragma("unroll") for (int _i = 0; _i < 2; ++_i) \
;         __builtin_amdgcn_global_load_lds((const unsigned*)((const char*)(gbase) + (voff)[_i]), (PG8_LAS unsigned*)(lds + (bufoff) + ldsw + _i * 8192), 16, 0, 0); } while (0)
; #define PG8_LDA(dst, b, h) do { _Pragma("unroll") for (int m = 0; m < 4; ++m) _Pragma("unroll") for (int k = 0; k < 2; ++k) dst[m][k] = *(const PG8_LAS bf16x8*)(lds + PG8_SA(b, h) + aoff + m * 2048 + k * 1024); } while (0)
; #define PG8_LDB(dst, b, h) do { _Pragma("unroll") for (int n = 0; n < 2; ++n) _Pragma("unroll") for (int k = 0; k < 2; ++k) dst[n][k] = *(const PG8_LAS bf16x8*)(lds + PG8_SB(b, h) + boff + n * 2048 + k * 1024); } while (0)
; #define PG8_MMA(ai, bj, At, Bt) do { __builtin_amdgcn_s_setprio(1); _Pragma("unroll") for (int m = 0; m < 4; ++m) _Pragma("unroll") for (int n = 0; n < 2; ++n) _Pragma("unroll") for (int k = 0; k < 2; ++k) \
;         acc[ai][bj][m][n] = mma_<I8>(Bt[n][k], At[m][k], acc[ai][bj][m][n]); __builtin_amdgcn_s_setprio(0); } while (0)
; #define PG8_WAIT_V(n) asm volatile("s_waitcnt vmcnt(" #n ")" ::: "memory")
; #define PG8_WAIT_L(n) asm volatile("s_waitcnt lgkmcnt(" #n ")" ::: "memory")
; #define PG8_BAR __builtin_amdgcn_s_barrier()
; #define PG8_SCHED __builtin_amdgcn_sched_barrier(0)
; template <class Epi, class Sched, bool ALIGN_EPI = false, bool SP2 = false, bool I8 = false>
; __device__ __forceinline__ void gemm_phase(PG8_LAS unsigned char* lds, const Gemm g, const Sched& S, const Epi& E) {
;     ...
;             PG8_WAIT_V(8); PG8_WAIT_L(0); PG8_BAR; PG8_MMA(1, 0, At, B0); PG8_MMA(1, 1, At, B1); PG8_BAR; PG8_SCHED;
;             PG8_LDB(B0, 1, 0); PG8_LDB(B1, 1, 1); PG8_SCHED; PG8_LDA(At, 1, 0); PG8_STAGE(PG8_SA(0, 1), a2 + hstepA, voffA);
;             PG8_WAIT_V(8); PG8_WAIT_L(0); PG8_BAR; PG8_MMA(0, 0, At, B0); PG8_MMA(0, 1, At, B1); PG8_BAR; PG8_SCHED;
	s_setprio 1
	s_waitcnt lgkmcnt(0)
	v_mfma_i32_16x16x64_i8 v[70:73], v[58:61], v[184:187], v[70:73]
	v_mfma_i32_16x16x64_i8 v[66:69], v[74:77], v[184:187], v[66:69]
	v_mfma_i32_16x16x64_i8 v[46:49], v[58:61], v[192:195], v[46:49]
	v_mfma_i32_16x16x64_i8 v[42:45], v[74:77], v[192:195], v[42:45]
	v_mfma_i32_16x16x64_i8 v[30:33], v[58:61], v[200:203], v[30:33]
	v_mfma_i32_16x16x64_i8 v[26:29], v[74:77], v[200:203], v[26:29]
	v_mfma_i32_16x16x64_i8 v[14:17], v[58:61], v[208:211], v[14:17]
	v_mfma_i32_16x16x64_i8 v[10:13], v[74:77], v[208:211], v[10:13]
	s_setprio 0
	s_setprio 1
	v_mfma_i32_16x16x64_i8 v[70:73], v[62:65], v[188:191], v[70:73]
	v_mfma_i32_16x16x64_i8 v[66:69], v[78:81], v[188:191], v[66:69]
	v_mfma_i32_16x16x64_i8 v[46:49], v[62:65], v[196:199], v[46:49]
	v_mfma_i32_16x16x64_i8 v[42:45], v[78:81], v[196:199], v[42:45]
	v_mfma_i32_16x16x64_i8 v[30:33], v[62:65], v[204:207], v[30:33]
	v_mfma_i32_16x16x64_i8 v[26:29], v[78:81], v[204:207], v[26:29]
	v_mfma_i32_16x16x64_i8 v[14:17], v[62:65], v[212:215], v[14:17]
	v_mfma_i32_16x16x64_i8 v[10:13], v[78:81], v[212:215], v[10:13]
	s_setprio 0
	s_setprio 1
	v_mfma_i32_16x16x64_i8 v[54:57], v[162:165], v[184:187], v[54:57]
	v_mfma_i32_16x16x64_i8 v[50:53], v[170:173], v[184:187], v[50:53]
	v_mfma_i32_16x16x64_i8 v[38:41], v[162:165], v[192:195], v[38:41]
	v_mfma_i32_16x16x64_i8 v[34:37], v[170:173], v[192:195], v[34:37]
	v_mfma_i32_16x16x64_i8 v[22:25], v[162:165], v[200:203], v[22:25]
	v_mfma_i32_16x16x64_i8 v[18:21], v[170:173], v[200:203], v[18:21]
	v_mfma_i32_16x16x64_i8 v[6:9], v[162:165], v[208:211], v[6:9]
	v_mfma_i32_16x16x64_i8 v[2:5], v[170:173], v[208:211], v[2:5]
	s_setprio 0
	s_setprio 1
	v_mfma_i32_16x16x64_i8 v[54:57], v[166:169], v[188:191], v[54:57]
	v_mfma_i32_16x16x64_i8 v[50:53], v[180:183], v[188:191], v[50:53]
	v_mfma_i32_16x16x64_i8 v[38:41], v[166:169], v[196:199], v[38:41]
	v_mfma_i32_16x16x64_i8 v[34:37], v[180:183], v[196:199], v[34:37]
	v_mfma_i32_16x16x64_i8 v[22:25], v[166:169], v[204:207], v[22:25]
	v_mfma_i32_16x16x64_i8 v[18:21], v[180:183], v[204:207], v[18:21]
	v_mfma_i32_16x16x64_i8 v[6:9], v[166:169], v[212:215], v[6:9]
	v_mfma_i32_16x16x64_i8 v[2:5], v[180:183], v[212:215], v[2:5]
	s_setprio 0
	s_barrier
	s_add_i32 s40, 0, 0x18000
	s_add_i32 s41, 0, 0x1c000
	v_add_u32_e32 v78, s40, v176
	v_add_u32_e32 v180, s41, v176
	ds_read_b128 v[58:61], v78
	ds_read_b128 v[62:65], v78 offset:1024
	ds_read_b128 v[74:77], v78 offset:2048
	ds_read_b128 v[78:81], v78 offset:3072
	ds_read_b128 v[162:165], v180
	ds_read_b128 v[166:169], v180 offset:1024
	ds_read_b128 v[170:173], v180 offset:2048
	ds_read_b128 v[180:183], v180 offset:3072
	s_add_u32 s36, s36, 0x80000
	s_addc_u32 s37, s37, 0
	s_mov_b32 m0, s71
	v_lshl_add_u64 v[222:223], s[36:37], 0, v[146:147]
	ds_read_b128 v[184:187], v179 offset:32768
	ds_read_b128 v[188:191], v179 offset:33792
	ds_read_b128 v[192:195], v179 offset:34816
	ds_read_b128 v[196:199], v179 offset:35840
	ds_read_b128 v[200:203], v179 offset:36864
	ds_read_b128 v[204:207], v179 offset:37888
	ds_read_b128 v[208:211], v179 offset:38912
	ds_read_b128 v[212:215], v179 offset:39936
	global_load_lds_dwordx4 v[222:223], off
	v_lshl_add_u64 v[222:223], s[36:37], 0, v[150:151]
	s_mov_b32 m0, s88
	s_nop 0
	global_load_lds_dwordx4 v[222:223], off
	s_waitcnt vmcnt(8)
	s_waitcnt lgkmcnt(0)
	s_barrier
	s_setprio 1
	s_waitcnt lgkmcnt(0)
	v_mfma_i32_16x16x64_i8 v[142:145], v[58:61], v[184:187], v[142:145]
	v_mfma_i32_16x16x64_i8 v[138:141], v[74:77], v[184:187], v[138:141]
	v_mfma_i32_16x16x64_i8 v[126:129], v[58:61], v[192:195], v[126:129]
	v_mfma_i32_16x16x64_i8 v[122:125], v[74:77], v[192:195], v[122:125]
	v_mfma_i32_16x16x64_i8 v[110:113], v[58:61], v[200:203], v[110:113]
	v_mfma_i32_16x16x64_i8 v[106:109], v[74:77], v[200:203], v[106:109]
	v_mfma_i32_16x16x64_i8 v[94:97], v[58:61], v[208:211], v[94:97]
	v_mfma_i32_16x16x64_i8 v[90:93], v[74:77], v[208:211], v[90:93]
	s_setprio 0
	s_setprio 1
	v_mfma_i32_16x16x64_i8 v[142:145], v[62:65], v[188:191], v[142:145]
	v_mfma_i32_16x16x64_i8 v[138:141], v[78:81], v[188:191], v[138:141]
	v_mfma_i32_16x16x64_i8 v[126:129], v[62:65], v[196:199], v[126:129]
	v_mfma_i32_16x16x64_i8 v[122:125], v[78:81], v[196:199], v[122:125]
	v_mfma_i32_16x16x64_i8 v[110:113], v[62:65], v[204:207], v[110:113]
	v_mfma_i32_16x16x64_i8 v[106:109], v[78:81], v[204:207], v[106:109]
	v_mfma_i32_16x16x64_i8 v[94:97], v[62:65], v[212:215], v[94:97]
	v_mfma_i32_16x16x64_i8 v[90:93], v[78:81], v[212:215], v[90:93]
	s_setprio 0
	s_setprio 1
	v_mfma_i32_16x16x64_i8 v[134:137], v[162:165], v[184:187], v[134:137]
	v_mfma_i32_16x16x64_i8 v[130:133], v[170:173], v[184:187], v[130:133]
	v_mfma_i32_16x16x64_i8 v[118:121], v[162:165], v[192:195], v[118:121]
	v_mfma_i32_16x16x64_i8 v[114:117], v[170:173], v[192:195], v[114:117]
	v_mfma_i32_16x16x64_i8 v[102:105], v[162:165], v[200:203], v[102:105]
	v_mfma_i32_16x16x64_i8 v[98:101], v[170:173], v[200:203], v[98:101]
	v_mfma_i32_16x16x64_i8 v[86:89], v[162:165], v[208:211], v[86:89]
	v_mfma_i32_16x16x64_i8 v[82:85], v[170:173], v[208:211], v[82:85]
	s_setprio 0
	s_setprio 1
	v_mfma_i32_16x16x64_i8 v[134:137], v[166:169], v[188:191], v[134:137]
	v_mfma_i32_16x16x64_i8 v[130:133], v[180:183], v[188:191], v[130:133]
	v_mfma_i32_16x16x64_i8 v[118:121], v[166:169], v[196:199], v[118:121]
	v_mfma_i32_16x16x64_i8 v[114:117], v[180:183], v[196:199], v[114:117]
	v_mfma_i32_16x16x64_i8 v[102:105], v[166:169], v[204:207], v[102:105]
	v_mfma_i32_16x16x64_i8 v[98:101], v[180:183], v[204:207], v[98:101]
	v_mfma_i32_16x16x64_i8 v[86:89], v[166:169], v[212:215], v[86:89]
	v_mfma_i32_16x16x64_i8 v[82:85], v[180:183], v[212:215], v[82:85]
	s_setprio 0
	s_barrier
; #define PG8_STAGE(bufoff, gbase, voff) do { _Pragma("unroll") for (int _i = 0; _i < 2; ++_i) \
;         __builtin_amdgcn_global_load_lds((const unsigned*)((const char*)(gbase) + (voff)[_i]), (PG8_LAS unsigned*)(lds + (bufoff) + ldsw + _i * 8192), 16, 0, 0); } while (0)
; #define PG8_LDA(dst, b, h) do { _Pragma("unroll") for (int m = 0; m < 4; ++m) _Pragma("unroll") for (int k = 0; k < 2; ++k) dst[m][k] = *(const PG8_LAS bf16x8*)(lds + PG8_SA(b, h) + aoff + m * 2048 + k * 1024); } while (0)
; #define PG8_MMA(ai, bj, At, Bt) do { __builtin_amdgcn_s_setprio(1); _Pragma("unroll") for (int m = 0; m < 4; ++m) _Pragma("unroll") for (int n = 0; n < 2; ++n) _Pragma("unroll") for (int k = 0; k < 2; ++k) \
;         acc[ai][bj][m][n] = mma_<I8>(Bt[n][k], At[m][k], acc[ai][bj][m][n]); __builtin_amdgcn_s_setprio(0); } while (0)
; #define PG8_WAIT_V(n) asm volatile("s_waitcnt vmcnt(" #n ")" ::: "memory")
; #define PG8_WAIT_L(n) asm volatile("s_waitcnt lgkmcnt(" #n ")" ::: "memory")
; #define PG8_BAR __builtin_amdgcn_s_barrier()
; #define PG8_SCHED __builtin_amdgcn_sched_barrier(0)
; template <class Epi, class Sched, bool ALIGN_EPI = false, bool SP2 = false, bool I8 = false>
; __device__ __forceinline__ void gemm_phase(PG8_LAS unsigned char* lds, const Gemm g, const Sched& S, const Epi& E) {
;     ...
;             PG8_LDA(At, 1, 1); PG8_STAGE(PG8_SB(1, 0), b3, voffB); PG8_STAGE(PG8_SB(1, 1), b3 + hstepB, voffB); PG8_STAGE(PG8_SA(1, 0), a3, voffA);
;             PG8_WAIT_V(8); PG8_WAIT_L(0); PG8_BAR; PG8_MMA(1, 0, At, B0); PG8_MMA(1, 1, At, B1); PG8_BAR; PG8_SCHED;
;     ...
;         if constexpr (ALIGN_EPI) { if (wr == 0) PG8_BAR; }
	s_add_i32 s36, s40, s68
	v_lshl_add_u64 v[174:175], v[174:175], 0, s[18:19]
	s_mov_b32 m0, s36
	ds_read_b128 v[184:187], v179 offset:49152
	ds_read_b128 v[188:191], v179 offset:50176
	ds_read_b128 v[192:195], v179 offset:51200
	ds_read_b128 v[196:199], v179 offset:52224
	ds_read_b128 v[200:203], v179 offset:53248
	ds_read_b128 v[204:207], v179 offset:54272
	ds_read_b128 v[208:211], v179 offset:55296
	ds_read_b128 v[212:215], v179 offset:56320
	global_load_lds_dwordx4 v[174:175], off
	s_add_i32 m0, s36, 0x2000
	s_add_u32 s34, s34, 0x80080
	v_lshl_add_u64 v[174:175], v[216:217], 0, s[18:19]
	s_addc_u32 s35, s35, 0
	s_add_i32 s36, s41, s68
	global_load_lds_dwordx4 v[174:175], off
	v_lshl_add_u64 v[174:175], s[34:35], 0, v[148:149]
	s_mov_b32 m0, s36
	s_nop 0
	global_load_lds_dwordx4 v[174:175], off
	v_lshl_add_u64 v[174:175], s[34:35], 0, v[152:153]
	s_add_i32 m0, s36, 0x2000
	s_nop 0
	global_load_lds_dwordx4 v[174:175], off
	v_lshl_add_u64 v[174:175], v[218:219], 0, s[18:19]
	s_mov_b32 m0, s92
	s_nop 0
	global_load_lds_dwordx4 v[174:175], off
	v_lshl_add_u64 v[174:175], v[220:221], 0, s[18:19]
	s_mov_b32 m0, s93
	s_nop 0
	global_load_lds_dwordx4 v[174:175], off
	s_waitcnt vmcnt(8)
	s_waitcnt lgkmcnt(0)
	s_barrier
	s_setprio 1
	s_waitcnt lgkmcnt(0)
	v_mfma_i32_16x16x64_i8 v[70:73], v[58:61], v[184:187], v[70:73]
	v_mfma_i32_16x16x64_i8 v[66:69], v[74:77], v[184:187], v[66:69]
	v_mfma_i32_16x16x64_i8 v[46:49], v[58:61], v[192:195], v[46:49]
	v_mfma_i32_16x16x64_i8 v[42:45], v[74:77], v[192:195], v[42:45]
	v_mfma_i32_16x16x64_i8 v[30:33], v[58:61], v[200:203], v[30:33]
	v_mfma_i32_16x16x64_i8 v[26:29], v[74:77], v[200:203], v[26:29]
	v_mfma_i32_16x16x64_i8 v[14:17], v[58:61], v[208:211], v[14:17]
	v_mfma_i32_16x16x64_i8 v[10:13], v[74:77], v[208:211], v[10:13]
	s_setprio 0
	s_setprio 1
	v_mfma_i32_16x16x64_i8 v[70:73], v[62:65], v[188:191], v[70:73]
	v_mfma_i32_16x16x64_i8 v[66:69], v[78:81], v[188:191], v[66:69]
	v_mfma_i32_16x16x64_i8 v[46:49], v[62:65], v[196:199], v[46:49]
	v_mfma_i32_16x16x64_i8 v[42:45], v[78:81], v[196:199], v[42:45]
	v_mfma_i32_16x16x64_i8 v[30:33], v[62:65], v[204:207], v[30:33]
	v_mfma_i32_16x16x64_i8 v[26:29], v[78:81], v[204:207], v[26:29]
	v_mfma_i32_16x16x64_i8 v[14:17], v[62:65], v[212:215], v[14:17]
	v_mfma_i32_16x16x64_i8 v[10:13], v[78:81], v[212:215], v[10:13]
	s_setprio 0
	s_setprio 1
	v_mfma_i32_16x16x64_i8 v[54:57], v[162:165], v[184:187], v[54:57]
	v_mfma_i32_16x16x64_i8 v[50:53], v[170:173], v[184:187], v[50:53]
	v_mfma_i32_16x16x64_i8 v[38:41], v[162:165], v[192:195], v[38:41]
	v_mfma_i32_16x16x64_i8 v[34:37], v[170:173], v[192:195], v[34:37]
	v_mfma_i32_16x16x64_i8 v[22:25], v[162:165], v[200:203], v[22:25]
	v_mfma_i32_16x16x64_i8 v[18:21], v[170:173], v[200:203], v[18:21]
	v_mfma_i32_16x16x64_i8 v[6:9], v[162:165], v[208:211], v[6:9]
	v_mfma_i32_16x16x64_i8 v[2:5], v[170:173], v[208:211], v[2:5]
	s_setprio 0
	s_setprio 1
	v_mfma_i32_16x16x64_i8 v[54:57], v[166:169], v[188:191], v[54:57]
	v_mfma_i32_16x16x64_i8 v[50:53], v[180:183], v[188:191], v[50:53]
	v_mfma_i32_16x16x64_i8 v[38:41], v[166:169], v[196:199], v[38:41]
	v_mfma_i32_16x16x64_i8 v[34:37], v[180:183], v[196:199], v[34:37]
	v_mfma_i32_16x16x64_i8 v[22:25], v[166:169], v[204:207], v[22:25]
	v_mfma_i32_16x16x64_i8 v[18:21], v[180:183], v[204:207], v[18:21]
	v_mfma_i32_16x16x64_i8 v[6:9], v[166:169], v[212:215], v[6:9]
	v_mfma_i32_16x16x64_i8 v[2:5], v[180:183], v[212:215], v[2:5]
	s_setprio 0
	s_barrier
	s_add_i32 s39, s39, 2
	s_add_u32 s2, s2, 0x100
	s_addc_u32 s3, s3, 0
	s_add_u32 s31, s31, 0x100
	s_addc_u32 s38, s38, 0
	s_cmp_gt_u32 s39, 29
	s_cbranch_scc0 .LBB0_607
	s_and_b64 vcc, exec, s[20:21]
	s_cbranch_vccz .LBB0_610
	s_barrier

; #define PG8_STAGE(bufoff, gbase, voff) do { _Pragma("unroll") for (int _i = 0; _i < 2; ++_i) \
;         __builtin_amdgcn_global_load_lds((const unsigned*)((const char*)(gbase) + (voff)[_i]), (PG8_LAS unsigned*)(lds + (bufoff) + ldsw + _i * 8192), 16, 0, 0); } while (0)
; #define PG8_LDA(dst, b, h) do { _Pragma("unroll") for (int m = 0; m < 4; ++m) _Pragma("unroll") for (int k = 0; k < 2; ++k) dst[m][k] = *(const PG8_LAS bf16x8*)(lds + PG8_SA(b, h) + aoff + m * 2048 + k * 1024); } while (0)
; #define PG8_LDB(dst, b, h) do { _Pragma("unroll") for (int n = 0; n < 2; ++n) _Pragma("unroll") for (int k = 0; k < 2; ++k) dst[n][k] = *(const PG8_LAS bf16x8*)(lds + PG8_SB(b, h) + boff + n * 2048 + k * 1024); } while (0)
; #define PG8_WAIT_V(n) asm volatile("s_waitcnt vmcnt(" #n ")" ::: "memory")
; #define PG8_WAIT_L(n) asm volatile("s_waitcnt lgkmcnt(" #n ")" ::: "memory")
; #define PG8_BAR __builtin_amdgcn_s_barrier()
; #define PG8_SCHED __builtin_amdgcn_sched_barrier(0)
; template <class Epi, class Sched, bool ALIGN_EPI = false, bool SP2 = false, bool I8 = false>
; __device__ __forceinline__ void gemm_phase(PG8_LAS unsigned char* lds, const Gemm g, const Sched& S, const Epi& E) {
;     ...
;         const char* nA = has_next ? (const char*)g.A + (size_t)nxt.pm * tstepA + PG8_K0B(nxt) : cA; const char* nB = has_next ? (const char*)g.Bt + (size_t)nxt.pn * tstepB + PG8_K0B(nxt) : cB;
;         for (int t = 0; t < nt; t += 2) {
;             const bool last = (t == nt - 2);
;             const char* a1 = cA + (size_t)(t + 1) * kstep;
;             const char* a2 = last ? nA : cA + (size_t)(t + 2) * kstep; const char* b2 = last ? nB : cB + (size_t)(t + 2) * kstep;
;             const char* a3 = a2 + kstep; const char* b3 = b2 + kstep;
;             if (last && has_next) S.a_ready(nxt);
;             if constexpr (SP2) {
;             PG8_LDB(B0, 0, 0); PG8_LDB(B1, 0, 1); PG8_SCHED; PG8_LDA(At, 0, 0); PG8_STAGE(PG8_SA(1, 1), a1 + hstepA, voffA);
;             PG8_WAIT_V(8); PG8_WAIT_L(0); PG8_BAR; PG8_MMA(0, 0, At, B0); PG8_MMA(0, 1, At, B1); PG8_BAR; PG8_SCHED;
;             PG8_LDA(At, 0, 1); PG8_STAGE(PG8_SB(0, 0), b2, voffB); PG8_STAGE(PG8_SB(0, 1), b2 + hstepB, voffB); PG8_STAGE(PG8_SA(0, 0), a2, voffA);
;             PG8_WAIT_V(8); PG8_WAIT_L(0); PG8_BAR; PG8_MMA(1, 0, At, B0); PG8_MMA(1, 1, At, B1); PG8_BAR; PG8_SCHED;
.LBB0_1092:
	ds_read_b128 v[58:61], v172
	ds_read_b128 v[62:65], v172 offset:1024
	ds_read_b128 v[74:77], v172 offset:2048
	ds_read_b128 v[78:81], v172 offset:3072
	ds_read_b128 v[164:167], v173
	ds_read_b128 v[168:171], v173 offset:1024
	ds_read_b128 v[176:179], v173 offset:2048
	ds_read_b128 v[180:183], v173 offset:3072
	s_add_i32 s47, s22, 2
	s_add_u32 s23, s8, 0xfffe0080
	s_addc_u32 s24, s9, -1
	s_cmp_eq_u32 s3, s22
	s_cselect_b32 s22, s20, s17
	s_cselect_b32 s25, s1, s24
	s_cselect_b32 s24, s0, s23
	s_cselect_b32 s23, s21, s19
	v_lshl_add_u64 v[216:217], s[8:9], 0, v[156:157]
	s_add_i32 m0, s33, 0xc000
	ds_read_b128 v[184:187], v174
	ds_read_b128 v[188:191], v174 offset:1024
	ds_read_b128 v[192:195], v174 offset:2048
	ds_read_b128 v[196:199], v174 offset:3072
	ds_read_b128 v[200:203], v174 offset:4096
	ds_read_b128 v[204:207], v174 offset:5120
	ds_read_b128 v[208:211], v174 offset:6144
	ds_read_b128 v[212:215], v174 offset:7168
	global_load_lds_dwordx4 v[216:217], off
	v_lshl_add_u64 v[216:217], s[8:9], 0, v[158:159]
	s_add_i32 m0, s33, 0xe000
	s_nop 0
	global_load_lds_dwordx4 v[216:217], off
	s_waitcnt vmcnt(8)
	s_waitcnt lgkmcnt(0)
	s_barrier
	s_setprio 1
	s_waitcnt lgkmcnt(0)
	v_mfma_f32_16x16x32_bf16 v[142:145], v[58:61], v[184:187], v[142:145]
	v_mfma_f32_16x16x32_bf16 v[138:141], v[74:77], v[184:187], v[138:141]
	v_mfma_f32_16x16x32_bf16 v[126:129], v[58:61], v[192:195], v[126:129]
	v_mfma_f32_16x16x32_bf16 v[122:125], v[74:77], v[192:195], v[122:125]
	v_mfma_f32_16x16x32_bf16 v[110:113], v[58:61], v[200:203], v[110:113]
	v_mfma_f32_16x16x32_bf16 v[106:109], v[74:77], v[200:203], v[106:109]
	v_mfma_f32_16x16x32_bf16 v[94:97], v[58:61], v[208:211], v[94:97]
	v_mfma_f32_16x16x32_bf16 v[90:93], v[74:77], v[208:211], v[90:93]
	s_setprio 0
	s_setprio 1
	v_mfma_f32_16x16x32_bf16 v[142:145], v[62:65], v[188:191], v[142:145]
	v_mfma_f32_16x16x32_bf16 v[138:141], v[78:81], v[188:191], v[138:141]
	v_mfma_f32_16x16x32_bf16 v[126:129], v[62:65], v[196:199], v[126:129]
	v_mfma_f32_16x16x32_bf16 v[122:125], v[78:81], v[196:199], v[122:125]
	v_mfma_f32_16x16x32_bf16 v[110:113], v[62:65], v[204:207], v[110:113]
	v_mfma_f32_16x16x32_bf16 v[106:109], v[78:81], v[204:207], v[106:109]
	v_mfma_f32_16x16x32_bf16 v[94:97], v[62:65], v[212:215], v[94:97]
	v_mfma_f32_16x16x32_bf16 v[90:93], v[78:81], v[212:215], v[90:93]
	s_setprio 0
	s_setprio 1
	v_mfma_f32_16x16x32_bf16 v[134:137], v[164:167], v[184:187], v[134:137]
	v_mfma_f32_16x16x32_bf16 v[130:133], v[176:179], v[184:187], v[130:133]
	v_mfma_f32_16x16x32_bf16 v[118:121], v[164:167], v[192:195], v[118:121]
	v_mfma_f32_16x16x32_bf16 v[114:117], v[176:179], v[192:195], v[114:117]
	v_mfma_f32_16x16x32_bf16 v[102:105], v[164:167], v[200:203], v[102:105]
	v_mfma_f32_16x16x32_bf16 v[98:101], v[176:179], v[200:203], v[98:101]
	v_mfma_f32_16x16x32_bf16 v[86:89], v[164:167], v[208:211], v[86:89]
	v_mfma_f32_16x16x32_bf16 v[82:85], v[176:179], v[208:211], v[82:85]
	s_setprio 0
	s_setprio 1
	v_mfma_f32_16x16x32_bf16 v[134:137], v[168:171], v[188:191], v[134:137]
	v_mfma_f32_16x16x32_bf16 v[130:133], v[180:183], v[188:191], v[130:133]
	v_mfma_f32_16x16x32_bf16 v[118:121], v[168:171], v[196:199], v[118:121]
	v_mfma_f32_16x16x32_bf16 v[114:117], v[180:183], v[196:199], v[114:117]
	v_mfma_f32_16x16x32_bf16 v[102:105], v[168:171], v[204:207], v[102:105]
	v_mfma_f32_16x16x32_bf16 v[98:101], v[180:183], v[204:207], v[98:101]
	v_mfma_f32_16x16x32_bf16 v[86:89], v[168:171], v[212:215], v[86:89]
	v_mfma_f32_16x16x32_bf16 v[82:85], v[180:183], v[212:215], v[82:85]
	s_setprio 0
	s_barrier
	s_add_i32 s56, s44, s30
	v_lshl_add_u64 v[216:217], s[22:23], 0, v[148:149]
	s_mov_b32 m0, s56
	ds_read_b128 v[184:187], v174 offset:16384
	ds_read_b128 v[188:191], v174 offset:17408
	ds_read_b128 v[192:195], v174 offset:18432
	ds_read_b128 v[196:199], v174 offset:19456
	ds_read_b128 v[200:203], v174 offset:20480
	ds_read_b128 v[204:207], v174 offset:21504
	ds_read_b128 v[208:211], v174 offset:22528
	ds_read_b128 v[212:215], v174 offset:23552
	global_load_lds_dwordx4 v[216:217], off
	s_add_i32 m0, s56, 0x2000
	s_add_u32 s56, s22, 0x20000
	v_lshl_add_u64 v[218:219], s[22:23], 0, v[152:153]
	s_addc_u32 s57, s23, 0
	s_add_i32 s58, s45, s30
	global_load_lds_dwordx4 v[218:219], off
	v_lshl_add_u64 v[220:221], s[56:57], 0, v[148:149]
	s_mov_b32 m0, s58
	v_lshl_add_u64 v[222:223], s[24:25], 0, v[150:151]
	global_load_lds_dwordx4 v[220:221], off
	v_lshl_add_u64 v[220:221], s[56:57], 0, v[152:153]
	s_add_i32 m0, s58, 0x2000
	s_nop 0
	global_load_lds_dwordx4 v[220:221], off
	v_lshl_add_u64 v[220:221], s[24:25], 0, v[146:147]
	s_mov_b32 m0, s33
	s_nop 0
	global_load_lds_dwordx4 v[220:221], off
	s_mov_b32 m0, s34
	s_nop 0
	global_load_lds_dwordx4 v[222:223], off
	s_waitcnt vmcnt(8)
	s_waitcnt lgkmcnt(0)
	s_barrier
; #define PG8_STAGE(bufoff, gbase, voff) do { _Pragma("unroll") for (int _i = 0; _i < 2; ++_i) \
;         __builtin_amdgcn_global_load_lds((const unsigned*)((const char*)(gbase) + (voff)[_i]), (PG8_LAS unsigned*)(lds + (bufoff) + ldsw + _i * 8192), 16, 0, 0); } while (0)
; #define PG8_LDA(dst, b, h) do { _Pragma("unroll") for (int m = 0; m < 4; ++m) _Pragma("unroll") for (int k = 0; k < 2; ++k) dst[m][k] = *(const PG8_LAS bf16x8*)(lds + PG8_SA(b, h) + aoff + m * 2048 + k * 1024); } while (0)
; #define PG8_LDB(dst, b, h) do { _Pragma("unroll") for (int n = 0; n < 2; ++n) _Pragma("unroll") for (int k = 0; k < 2; ++k) dst[n][k] = *(const PG8_LAS bf16x8*)(lds + PG8_SB(b, h) + boff + n * 2048 + k * 1024); } while (0)
; #define PG8_MMA(ai, bj, At, Bt) do { __builtin_amdgcn_s_setprio(1); _Pragma("unroll") for (int m = 0; m < 4; ++m) _Pragma("unroll") for (int n = 0; n < 2; ++n) _Pragma("unroll") for (int k = 0; k < 2; ++k) \
;         acc[ai][bj][m][n] = mma_<I8>(Bt[n][k], At[m][k], acc[ai][bj][m][n]); __builtin_amdgcn_s_setprio(0); } while (0)
; #define PG8_WAIT_V(n) asm volatile("s_waitcnt vmcnt(" #n ")" ::: "memory")
; #define PG8_WAIT_L(n) asm volatile("s_waitcnt lgkmcnt(" #n ")" ::: "memory")
; #define PG8_BAR __builtin_amdgcn_s_barrier()
; #define PG8_SCHED __builtin_amdgcn_sched_barrier(0)
; template <class Epi, class Sched, bool ALIGN_EPI = false, bool SP2 = false, bool I8 = false>
; __device__ __forceinline__ void gemm_phase(PG8_LAS unsigned char* lds, const Gemm g, const Sched& S, const Epi& E) {
;     ...
;             PG8_WAIT_V(8); PG8_WAIT_L(0); PG8_BAR; PG8_MMA(1, 0, At, B0); PG8_MMA(1, 1, At, B1); PG8_BAR; PG8_SCHED;
;             PG8_LDB(B0, 1, 0); PG8_LDB(B1, 1, 1); PG8_SCHED; PG8_LDA(At, 1, 0); PG8_STAGE(PG8_SA(0, 1), a2 + hstepA, voffA);
;             PG8_WAIT_V(8); PG8_WAIT_L(0); PG8_BAR; PG8_MMA(0, 0, At, B0); PG8_MMA(0, 1, At, B1); PG8_BAR; PG8_SCHED;
	s_setprio 1
	s_waitcnt lgkmcnt(0)
	v_mfma_f32_16x16x32_bf16 v[70:73], v[58:61], v[184:187], v[70:73]
	v_mfma_f32_16x16x32_bf16 v[66:69], v[74:77], v[184:187], v[66:69]
	v_mfma_f32_16x16x32_bf16 v[46:49], v[58:61], v[192:195], v[46:49]
	v_mfma_f32_16x16x32_bf16 v[42:45], v[74:77], v[192:195], v[42:45]
	v_mfma_f32_16x16x32_bf16 v[30:33], v[58:61], v[200:203], v[30:33]
	v_mfma_f32_16x16x32_bf16 v[26:29], v[74:77], v[200:203], v[26:29]
	v_mfma_f32_16x16x32_bf16 v[14:17], v[58:61], v[208:211], v[14:17]
	v_mfma_f32_16x16x32_bf16 v[10:13], v[74:77], v[208:211], v[10:13]
	s_setprio 0
	s_setprio 1
	v_mfma_f32_16x16x32_bf16 v[70:73], v[62:65], v[188:191], v[70:73]
	v_mfma_f32_16x16x32_bf16 v[66:69], v[78:81], v[188:191], v[66:69]
	v_mfma_f32_16x16x32_bf16 v[46:49], v[62:65], v[196:199], v[46:49]
	v_mfma_f32_16x16x32_bf16 v[42:45], v[78:81], v[196:199], v[42:45]
	v_mfma_f32_16x16x32_bf16 v[30:33], v[62:65], v[204:207], v[30:33]
	v_mfma_f32_16x16x32_bf16 v[26:29], v[78:81], v[204:207], v[26:29]
	v_mfma_f32_16x16x32_bf16 v[14:17], v[62:65], v[212:215], v[14:17]
	v_mfma_f32_16x16x32_bf16 v[10:13], v[78:81], v[212:215], v[10:13]
	s_setprio 0
	s_setprio 1
	v_mfma_f32_16x16x32_bf16 v[54:57], v[164:167], v[184:187], v[54:57]
	v_mfma_f32_16x16x32_bf16 v[50:53], v[176:179], v[184:187], v[50:53]
	v_mfma_f32_16x16x32_bf16 v[38:41], v[164:167], v[192:195], v[38:41]
	v_mfma_f32_16x16x32_bf16 v[34:37], v[176:179], v[192:195], v[34:37]
	v_mfma_f32_16x16x32_bf16 v[22:25], v[164:167], v[200:203], v[22:25]
	v_mfma_f32_16x16x32_bf16 v[18:21], v[176:179], v[200:203], v[18:21]
	v_mfma_f32_16x16x32_bf16 v[6:9], v[164:167], v[208:211], v[6:9]
	v_mfma_f32_16x16x32_bf16 v[2:5], v[176:179], v[208:211], v[2:5]
	s_setprio 0
	s_setprio 1
	v_mfma_f32_16x16x32_bf16 v[54:57], v[168:171], v[188:191], v[54:57]
	v_mfma_f32_16x16x32_bf16 v[50:53], v[180:183], v[188:191], v[50:53]
	v_mfma_f32_16x16x32_bf16 v[38:41], v[168:171], v[196:199], v[38:41]
	v_mfma_f32_16x16x32_bf16 v[34:37], v[180:183], v[196:199], v[34:37]
	v_mfma_f32_16x16x32_bf16 v[22:25], v[168:171], v[204:207], v[22:25]
	v_mfma_f32_16x16x32_bf16 v[18:21], v[180:183], v[204:207], v[18:21]
	v_mfma_f32_16x16x32_bf16 v[6:9], v[168:171], v[212:215], v[6:9]
	v_mfma_f32_16x16x32_bf16 v[2:5], v[180:183], v[212:215], v[2:5]
	s_setprio 0
	s_barrier
	s_add_i32 s56, 0, 0x18000
	s_add_i32 s57, 0, 0x1c000
	v_add_u32_e32 v78, s56, v1
	v_add_u32_e32 v154, s57, v1
	ds_read_b128 v[58:61], v78
	ds_read_b128 v[62:65], v78 offset:1024
	ds_read_b128 v[74:77], v78 offset:2048
	ds_read_b128 v[78:81], v78 offset:3072
	ds_read_b128 v[164:167], v154
	ds_read_b128 v[168:171], v154 offset:1024
	ds_read_b128 v[176:179], v154 offset:2048
	ds_read_b128 v[180:183], v154 offset:3072
	s_add_u32 s24, s24, 0x20000
	s_addc_u32 s25, s25, 0
	s_mov_b32 m0, s35
	v_lshl_add_u64 v[224:225], s[24:25], 0, v[146:147]
	ds_read_b128 v[184:187], v174 offset:32768
	ds_read_b128 v[188:191], v174 offset:33792
	ds_read_b128 v[192:195], v174 offset:34816
	ds_read_b128 v[196:199], v174 offset:35840
	ds_read_b128 v[200:203], v174 offset:36864
	ds_read_b128 v[204:207], v174 offset:37888
	ds_read_b128 v[208:211], v174 offset:38912
	ds_read_b128 v[212:215], v174 offset:39936
	global_load_lds_dwordx4 v[224:225], off
	v_lshl_add_u64 v[224:225], s[24:25], 0, v[150:151]
	s_mov_b32 m0, s36
	s_nop 0
	global_load_lds_dwordx4 v[224:225], off
	s_waitcnt vmcnt(8)
	s_waitcnt lgkmcnt(0)
	s_barrier
	s_setprio 1
	s_waitcnt lgkmcnt(0)
	v_mfma_f32_16x16x32_bf16 v[142:145], v[58:61], v[184:187], v[142:145]
	v_mfma_f32_16x16x32_bf16 v[138:141], v[74:77], v[184:187], v[138:141]
	v_mfma_f32_16x16x32_bf16 v[126:129], v[58:61], v[192:195], v[126:129]
	v_mfma_f32_16x16x32_bf16 v[122:125], v[74:77], v[192:195], v[122:125]
	v_mfma_f32_16x16x32_bf16 v[110:113], v[58:61], v[200:203], v[110:113]
	v_mfma_f32_16x16x32_bf16 v[106:109], v[74:77], v[200:203], v[106:109]
	v_mfma_f32_16x16x32_bf16 v[94:97], v[58:61], v[208:211], v[94:97]
	v_mfma_f32_16x16x32_bf16 v[90:93], v[74:77], v[208:211], v[90:93]
	s_setprio 0
	s_setprio 1
	v_mfma_f32_16x16x32_bf16 v[142:145], v[62:65], v[188:191], v[142:145]
	v_mfma_f32_16x16x32_bf16 v[138:141], v[78:81], v[188:191], v[138:141]
	v_mfma_f32_16x16x32_bf16 v[126:129], v[62:65], v[196:199], v[126:129]
	v_mfma_f32_16x16x32_bf16 v[122:125], v[78:81], v[196:199], v[122:125]
	v_mfma_f32_16x16x32_bf16 v[110:113], v[62:65], v[204:207], v[110:113]
	v_mfma_f32_16x16x32_bf16 v[106:109], v[78:81], v[204:207], v[106:109]
	v_mfma_f32_16x16x32_bf16 v[94:97], v[62:65], v[212:215], v[94:97]
	v_mfma_f32_16x16x32_bf16 v[90:93], v[78:81], v[212:215], v[90:93]
	s_setprio 0
	s_setprio 1
	v_mfma_f32_16x16x32_bf16 v[134:137], v[164:167], v[184:187], v[134:137]
	v_mfma_f32_16x16x32_bf16 v[130:133], v[176:179], v[184:187], v[130:133]
	v_mfma_f32_16x16x32_bf16 v[118:121], v[164:167], v[192:195], v[118:121]
	v_mfma_f32_16x16x32_bf16 v[114:117], v[176:179], v[192:195], v[114:117]
	v_mfma_f32_16x16x32_bf16 v[102:105], v[164:167], v[200:203], v[102:105]
	v_mfma_f32_16x16x32_bf16 v[98:101], v[176:179], v[200:203], v[98:101]
	v_mfma_f32_16x16x32_bf16 v[86:89], v[164:167], v[208:211], v[86:89]
	v_mfma_f32_16x16x32_bf16 v[82:85], v[176:179], v[208:211], v[82:85]
	s_setprio 0
	s_setprio 1
	v_mfma_f32_16x16x32_bf16 v[134:137], v[168:171], v[188:191], v[134:137]
	v_mfma_f32_16x16x32_bf16 v[130:133], v[180:183], v[188:191], v[130:133]
	v_mfma_f32_16x16x32_bf16 v[118:121], v[168:171], v[196:199], v[118:121]
	v_mfma_f32_16x16x32_bf16 v[114:117], v[180:183], v[196:199], v[114:117]
	v_mfma_f32_16x16x32_bf16 v[102:105], v[168:171], v[204:207], v[102:105]
	v_mfma_f32_16x16x32_bf16 v[98:101], v[180:183], v[204:207], v[98:101]
	v_mfma_f32_16x16x32_bf16 v[86:89], v[168:171], v[212:215], v[86:89]
	v_mfma_f32_16x16x32_bf16 v[82:85], v[180:183], v[212:215], v[82:85]
	s_setprio 0
	s_barrier
; #define PG8_STAGE(bufoff, gbase, voff) do { _Pragma("unroll") for (int _i = 0; _i < 2; ++_i) \
;         __builtin_amdgcn_global_load_lds((const unsigned*)((const char*)(gbase) + (voff)[_i]), (PG8_LAS unsigned*)(lds + (bufoff) + ldsw + _i * 8192), 16, 0, 0); } while (0)
; #define PG8_LDA(dst, b, h) do { _Pragma("unroll") for (int m = 0; m < 4; ++m) _Pragma("unroll") for (int k = 0; k < 2; ++k) dst[m][k] = *(const PG8_LAS bf16x8*)(lds + PG8_SA(b, h) + aoff + m * 2048 + k * 1024); } while (0)
; #define PG8_MMA(ai, bj, At, Bt) do { __builtin_amdgcn_s_setprio(1); _Pragma("unroll") for (int m = 0; m < 4; ++m) _Pragma("unroll") for (int n = 0; n < 2; ++n) _Pragma("unroll") for (int k = 0; k < 2; ++k) \
;         acc[ai][bj][m][n] = mma_<I8>(Bt[n][k], At[m][k], acc[ai][bj][m][n]); __builtin_amdgcn_s_setprio(0); } while (0)
; #define PG8_WAIT_V(n) asm volatile("s_waitcnt vmcnt(" #n ")" ::: "memory")
; #define PG8_WAIT_L(n) asm volatile("s_waitcnt lgkmcnt(" #n ")" ::: "memory")
; #define PG8_BAR __builtin_amdgcn_s_barrier()
; #define PG8_SCHED __builtin_amdgcn_sched_barrier(0)
; template <class Epi, class Sched, bool ALIGN_EPI = false, bool SP2 = false, bool I8 = false>
; __device__ __forceinline__ void gemm_phase(PG8_LAS unsigned char* lds, const Gemm g, const Sched& S, const Epi& E) {
;     ...
;             PG8_LDA(At, 1, 1); PG8_STAGE(PG8_SB(1, 0), b3, voffB); PG8_STAGE(PG8_SB(1, 1), b3 + hstepB, voffB); PG8_STAGE(PG8_SA(1, 0), a3, voffA);
;             PG8_WAIT_V(8); PG8_WAIT_L(0); PG8_BAR; PG8_MMA(1, 0, At, B0); PG8_MMA(1, 1, At, B1); PG8_BAR; PG8_SCHED;
;     ...
;         if constexpr (ALIGN_EPI) { if (wr == 0) PG8_BAR; }
	s_add_i32 s24, s56, s30
	v_lshl_add_u64 v[216:217], v[216:217], 0, s[12:13]
	s_mov_b32 m0, s24
	ds_read_b128 v[184:187], v174 offset:49152
	ds_read_b128 v[188:191], v174 offset:50176
	ds_read_b128 v[192:195], v174 offset:51200
	ds_read_b128 v[196:199], v174 offset:52224
	ds_read_b128 v[200:203], v174 offset:53248
	ds_read_b128 v[204:207], v174 offset:54272
	ds_read_b128 v[208:211], v174 offset:55296
	ds_read_b128 v[212:215], v174 offset:56320
	global_load_lds_dwordx4 v[216:217], off
	s_add_i32 m0, s24, 0x2000
	s_add_u32 s22, s22, 0x20080
	v_lshl_add_u64 v[216:217], v[218:219], 0, s[12:13]
	s_addc_u32 s23, s23, 0
	s_add_i32 s24, s57, s30
	global_load_lds_dwordx4 v[216:217], off
	v_lshl_add_u64 v[216:217], s[22:23], 0, v[148:149]
	s_mov_b32 m0, s24
	s_nop 0
	global_load_lds_dwordx4 v[216:217], off
	v_lshl_add_u64 v[216:217], s[22:23], 0, v[152:153]
	s_add_i32 m0, s24, 0x2000
	s_nop 0
	global_load_lds_dwordx4 v[216:217], off
	v_lshl_add_u64 v[216:217], v[220:221], 0, s[12:13]
	s_mov_b32 m0, s40
	s_nop 0
	global_load_lds_dwordx4 v[216:217], off
	v_lshl_add_u64 v[216:217], v[222:223], 0, s[12:13]
	s_mov_b32 m0, s41
	s_nop 0
	global_load_lds_dwordx4 v[216:217], off
	s_waitcnt vmcnt(8)
	s_waitcnt lgkmcnt(0)
	s_barrier
	s_setprio 1
	s_waitcnt lgkmcnt(0)
	v_mfma_f32_16x16x32_bf16 v[70:73], v[58:61], v[184:187], v[70:73]
	v_mfma_f32_16x16x32_bf16 v[66:69], v[74:77], v[184:187], v[66:69]
	v_mfma_f32_16x16x32_bf16 v[46:49], v[58:61], v[192:195], v[46:49]
	v_mfma_f32_16x16x32_bf16 v[42:45], v[74:77], v[192:195], v[42:45]
	v_mfma_f32_16x16x32_bf16 v[30:33], v[58:61], v[200:203], v[30:33]
	v_mfma_f32_16x16x32_bf16 v[26:29], v[74:77], v[200:203], v[26:29]
	v_mfma_f32_16x16x32_bf16 v[14:17], v[58:61], v[208:211], v[14:17]
	v_mfma_f32_16x16x32_bf16 v[10:13], v[74:77], v[208:211], v[10:13]
	s_setprio 0
	s_setprio 1
	v_mfma_f32_16x16x32_bf16 v[70:73], v[62:65], v[188:191], v[70:73]
	v_mfma_f32_16x16x32_bf16 v[66:69], v[78:81], v[188:191], v[66:69]
	v_mfma_f32_16x16x32_bf16 v[46:49], v[62:65], v[196:199], v[46:49]
	v_mfma_f32_16x16x32_bf16 v[42:45], v[78:81], v[196:199], v[42:45]
	v_mfma_f32_16x16x32_bf16 v[30:33], v[62:65], v[204:207], v[30:33]
	v_mfma_f32_16x16x32_bf16 v[26:29], v[78:81], v[204:207], v[26:29]
	v_mfma_f32_16x16x32_bf16 v[14:17], v[62:65], v[212:215], v[14:17]
	v_mfma_f32_16x16x32_bf16 v[10:13], v[78:81], v[212:215], v[10:13]
	s_setprio 0
	s_setprio 1
	v_mfma_f32_16x16x32_bf16 v[54:57], v[164:167], v[184:187], v[54:57]
	v_mfma_f32_16x16x32_bf16 v[50:53], v[176:179], v[184:187], v[50:53]
	v_mfma_f32_16x16x32_bf16 v[38:41], v[164:167], v[192:195], v[38:41]
	v_mfma_f32_16x16x32_bf16 v[34:37], v[176:179], v[192:195], v[34:37]
	v_mfma_f32_16x16x32_bf16 v[22:25], v[164:167], v[200:203], v[22:25]
	v_mfma_f32_16x16x32_bf16 v[18:21], v[176:179], v[200:203], v[18:21]
	v_mfma_f32_16x16x32_bf16 v[6:9], v[164:167], v[208:211], v[6:9]
	v_mfma_f32_16x16x32_bf16 v[2:5], v[176:179], v[208:211], v[2:5]
	s_setprio 0
	s_setprio 1
	v_mfma_f32_16x16x32_bf16 v[54:57], v[168:171], v[188:191], v[54:57]
	v_mfma_f32_16x16x32_bf16 v[50:53], v[180:183], v[188:191], v[50:53]
	v_mfma_f32_16x16x32_bf16 v[38:41], v[168:171], v[196:199], v[38:41]
	v_mfma_f32_16x16x32_bf16 v[34:37], v[180:183], v[196:199], v[34:37]
	v_mfma_f32_16x16x32_bf16 v[22:25], v[168:171], v[204:207], v[22:25]
	v_mfma_f32_16x16x32_bf16 v[18:21], v[180:183], v[204:207], v[18:21]
	v_mfma_f32_16x16x32_bf16 v[6:9], v[168:171], v[212:215], v[6:9]
	v_mfma_f32_16x16x32_bf16 v[2:5], v[180:183], v[212:215], v[2:5]
	s_setprio 0
	s_barrier
	s_add_u32 s8, s8, 0x100
	s_addc_u32 s9, s9, 0
	s_add_u32 s17, s17, 0x100
	s_addc_u32 s19, s19, 0
	s_cmp_ge_u32 s47, s7
	s_mov_b32 s22, s47
	s_cbranch_scc0 .LBB0_1092
	s_and_b64 vcc, exec, s[14:15]
	s_cbranch_vccz .LBB0_1095
	s_barrier

; #define PG8_STAGE(bufoff, gbase, voff) do { _Pragma("unroll") for (int _i = 0; _i < 2; ++_i) \
;         __builtin_amdgcn_global_load_lds((const unsigned*)((const char*)(gbase) + (voff)[_i]), (PG8_LAS unsigned*)(lds + (bufoff) + ldsw + _i * 8192), 16, 0, 0); } while (0)
; #define PG8_LDA(dst, b, h) do { _Pragma("unroll") for (int m = 0; m < 4; ++m) _Pragma("unroll") for (int k = 0; k < 2; ++k) dst[m][k] = *(const PG8_LAS bf16x8*)(lds + PG8_SA(b, h) + aoff + m * 2048 + k * 1024); } while (0)
; #define PG8_LDB(dst, b, h) do { _Pragma("unroll") for (int n = 0; n < 2; ++n) _Pragma("unroll") for (int k = 0; k < 2; ++k) dst[n][k] = *(const PG8_LAS bf16x8*)(lds + PG8_SB(b, h) + boff + n * 2048 + k * 1024); } while (0)
; #define PG8_MMA(ai, bj, At, Bt) do { __builtin_amdgcn_s_setprio(1); _Pragma("unroll") for (int m = 0; m < 4; ++m) _Pragma("unroll") for (int n = 0; n < 2; ++n) _Pragma("unroll") for (int k = 0; k < 2; ++k) \
;         acc[ai][bj][m][n] = mma_<I8>(Bt[n][k], At[m][k], acc[ai][bj][m][n]); __builtin_amdgcn_s_setprio(0); } while (0)
; #define PG8_WAIT_V(n) asm volatile("s_waitcnt vmcnt(" #n ")" ::: "memory")
; #define PG8_WAIT_L(n) asm volatile("s_waitcnt lgkmcnt(" #n ")" ::: "memory")
; #define PG8_BAR __builtin_amdgcn_s_barrier()
; template <class Epi, class Sched, bool ALIGN_EPI = false, bool SP2 = false, bool I8 = false>
; __device__ __forceinline__ void gemm_phase(PG8_LAS unsigned char* lds, const Gemm g, const Sched& S, const Epi& E) {
;     ...
;             const bool last = (t == nt - 2);
;             const char* a1 = cA + (size_t)(t + 1) * kstep;
;             const char* a2 = last ? nA : cA + (size_t)(t + 2) * kstep; const char* b2 = last ? nB : cB + (size_t)(t + 2) * kstep;
;             const char* a3 = a2 + kstep; const char* b3 = b2 + kstep;
;             if (last && has_next) S.a_ready(nxt);
;             if constexpr (SP2) {
;             PG8_LDB(B0, 0, 0); PG8_LDB(B1, 0, 1); PG8_SCHED; PG8_LDA(At, 0, 0); PG8_STAGE(PG8_SA(1, 1), a1 + hstepA, voffA);
;             PG8_WAIT_V(8); PG8_WAIT_L(0); PG8_BAR; PG8_MMA(0, 0, At, B0); PG8_MMA(0, 1, At, B1); PG8_BAR; PG8_SCHED;
;             PG8_LDA(At, 0, 1); PG8_STAGE(PG8_SB(0, 0), b2, voffB); PG8_STAGE(PG8_SB(0, 1), b2 + hstepB, voffB); PG8_STAGE(PG8_SA(0, 0), a2, voffA);
;             PG8_WAIT_V(8); PG8_WAIT_L(0); PG8_BAR; PG8_MMA(1, 0, At, B0); PG8_MMA(1, 1, At, B1); PG8_BAR; PG8_SCHED;
.LBB0_1538:
	ds_read_b128 v[146:149], v154
	ds_read_b128 v[150:153], v154 offset:1024
	ds_read_b128 v[158:161], v154 offset:2048
	ds_read_b128 v[162:165], v154 offset:3072
	ds_read_b128 v[166:169], v155
	ds_read_b128 v[170:173], v155 offset:1024
	ds_read_b128 v[174:177], v155 offset:2048
	ds_read_b128 v[178:181], v155 offset:3072
	s_add_u32 s24, s22, 0xfffe0080
	s_addc_u32 s25, s23, -1
	s_cmp_eq_u32 s49, 4
	s_cselect_b32 s27, s15, s25
	s_cselect_b32 s26, s45, s24
	s_cselect_b32 s25, s13, s48
	s_cselect_b32 s24, s46, s47
	v_lshl_add_u64 v[214:215], s[22:23], 0, v[138:139]
	s_add_i32 m0, s21, 0xc000
	ds_read_b128 v[182:185], v156
	ds_read_b128 v[186:189], v156 offset:1024
	ds_read_b128 v[190:193], v156 offset:2048
	ds_read_b128 v[194:197], v156 offset:3072
	ds_read_b128 v[198:201], v156 offset:4096
	ds_read_b128 v[202:205], v156 offset:5120
	ds_read_b128 v[206:209], v156 offset:6144
	ds_read_b128 v[210:213], v156 offset:7168
	global_load_lds_dwordx4 v[214:215], off
	v_lshl_add_u64 v[214:215], s[22:23], 0, v[140:141]
	s_add_i32 m0, s21, 0xe000
	s_nop 0
	global_load_lds_dwordx4 v[214:215], off
	s_waitcnt vmcnt(8)
	s_waitcnt lgkmcnt(0)
	s_barrier
	s_setprio 1
	s_waitcnt lgkmcnt(0)
	v_mfma_f32_16x16x32_bf16 v[126:129], v[146:149], v[182:185], v[126:129]
	v_mfma_f32_16x16x32_bf16 v[122:125], v[158:161], v[182:185], v[122:125]
	v_mfma_f32_16x16x32_bf16 v[114:117], v[146:149], v[190:193], v[114:117]
	v_mfma_f32_16x16x32_bf16 v[106:109], v[158:161], v[190:193], v[106:109]
	v_mfma_f32_16x16x32_bf16 v[94:97], v[146:149], v[198:201], v[94:97]
	v_mfma_f32_16x16x32_bf16 v[90:93], v[158:161], v[198:201], v[90:93]
	v_mfma_f32_16x16x32_bf16 v[86:89], v[146:149], v[206:209], v[86:89]
	v_mfma_f32_16x16x32_bf16 v[82:85], v[158:161], v[206:209], v[82:85]
	s_setprio 0
	s_setprio 1
	v_mfma_f32_16x16x32_bf16 v[126:129], v[150:153], v[186:189], v[126:129]
	v_mfma_f32_16x16x32_bf16 v[122:125], v[162:165], v[186:189], v[122:125]
	v_mfma_f32_16x16x32_bf16 v[114:117], v[150:153], v[194:197], v[114:117]
	v_mfma_f32_16x16x32_bf16 v[106:109], v[162:165], v[194:197], v[106:109]
	v_mfma_f32_16x16x32_bf16 v[94:97], v[150:153], v[202:205], v[94:97]
	v_mfma_f32_16x16x32_bf16 v[90:93], v[162:165], v[202:205], v[90:93]
	v_mfma_f32_16x16x32_bf16 v[86:89], v[150:153], v[210:213], v[86:89]
	v_mfma_f32_16x16x32_bf16 v[82:85], v[162:165], v[210:213], v[82:85]
	s_setprio 0
	s_setprio 1
	v_mfma_f32_16x16x32_bf16 v[118:121], v[166:169], v[182:185], v[118:121]
	v_mfma_f32_16x16x32_bf16 v[110:113], v[174:177], v[182:185], v[110:113]
	v_mfma_f32_16x16x32_bf16 v[102:105], v[166:169], v[190:193], v[102:105]
	v_mfma_f32_16x16x32_bf16 v[98:101], v[174:177], v[190:193], v[98:101]
	v_mfma_f32_16x16x32_bf16 v[78:81], v[166:169], v[198:201], v[78:81]
	v_mfma_f32_16x16x32_bf16 v[74:77], v[174:177], v[198:201], v[74:77]
	v_mfma_f32_16x16x32_bf16 v[70:73], v[166:169], v[206:209], v[70:73]
	v_mfma_f32_16x16x32_bf16 v[66:69], v[174:177], v[206:209], v[66:69]
	s_setprio 0
	s_setprio 1
	v_mfma_f32_16x16x32_bf16 v[118:121], v[170:173], v[186:189], v[118:121]
	v_mfma_f32_16x16x32_bf16 v[110:113], v[178:181], v[186:189], v[110:113]
	v_mfma_f32_16x16x32_bf16 v[102:105], v[170:173], v[194:197], v[102:105]
	v_mfma_f32_16x16x32_bf16 v[98:101], v[178:181], v[194:197], v[98:101]
	v_mfma_f32_16x16x32_bf16 v[78:81], v[170:173], v[202:205], v[78:81]
	v_mfma_f32_16x16x32_bf16 v[74:77], v[178:181], v[202:205], v[74:77]
	v_mfma_f32_16x16x32_bf16 v[70:73], v[170:173], v[210:213], v[70:73]
	v_mfma_f32_16x16x32_bf16 v[66:69], v[178:181], v[210:213], v[66:69]
	s_setprio 0
	s_barrier
	s_add_i32 s50, s42, s34
	v_lshl_add_u64 v[214:215], s[24:25], 0, v[132:133]
	s_mov_b32 m0, s50
	ds_read_b128 v[182:185], v156 offset:16384
	ds_read_b128 v[186:189], v156 offset:17408
	ds_read_b128 v[190:193], v156 offset:18432
	ds_read_b128 v[194:197], v156 offset:19456
	ds_read_b128 v[198:201], v156 offset:20480
	ds_read_b128 v[202:205], v156 offset:21504
	ds_read_b128 v[206:209], v156 offset:22528
	ds_read_b128 v[210:213], v156 offset:23552
	global_load_lds_dwordx4 v[214:215], off
	s_add_i32 m0, s50, 0x2000
	s_add_u32 s50, s24, 0x20000
	v_lshl_add_u64 v[216:217], s[24:25], 0, v[136:137]
	s_addc_u32 s51, s25, 0
	s_add_i32 s52, s43, s34
	global_load_lds_dwordx4 v[216:217], off
	v_lshl_add_u64 v[218:219], s[50:51], 0, v[132:133]
	s_mov_b32 m0, s52
	v_lshl_add_u64 v[220:221], s[26:27], 0, v[134:135]
	global_load_lds_dwordx4 v[218:219], off
	v_lshl_add_u64 v[218:219], s[50:51], 0, v[136:137]
	s_add_i32 m0, s52, 0x2000
	s_nop 0
	global_load_lds_dwordx4 v[218:219], off
	v_lshl_add_u64 v[218:219], s[26:27], 0, v[130:131]
	s_mov_b32 m0, s21
	s_nop 0
	global_load_lds_dwordx4 v[218:219], off
	s_mov_b32 m0, s35
	s_nop 0
	global_load_lds_dwordx4 v[220:221], off
	s_waitcnt vmcnt(8)
	s_waitcnt lgkmcnt(0)
	s_barrier
; #define PG8_STAGE(bufoff, gbase, voff) do { _Pragma("unroll") for (int _i = 0; _i < 2; ++_i) \
;         __builtin_amdgcn_global_load_lds((const unsigned*)((const char*)(gbase) + (voff)[_i]), (PG8_LAS unsigned*)(lds + (bufoff) + ldsw + _i * 8192), 16, 0, 0); } while (0)
; #define PG8_LDA(dst, b, h) do { _Pragma("unroll") for (int m = 0; m < 4; ++m) _Pragma("unroll") for (int k = 0; k < 2; ++k) dst[m][k] = *(const PG8_LAS bf16x8*)(lds + PG8_SA(b, h) + aoff + m * 2048 + k * 1024); } while (0)
; #define PG8_LDB(dst, b, h) do { _Pragma("unroll") for (int n = 0; n < 2; ++n) _Pragma("unroll") for (int k = 0; k < 2; ++k) dst[n][k] = *(const PG8_LAS bf16x8*)(lds + PG8_SB(b, h) + boff + n * 2048 + k * 1024); } while (0)
; #define PG8_MMA(ai, bj, At, Bt) do { __builtin_amdgcn_s_setprio(1); _Pragma("unroll") for (int m = 0; m < 4; ++m) _Pragma("unroll") for (int n = 0; n < 2; ++n) _Pragma("unroll") for (int k = 0; k < 2; ++k) \
;         acc[ai][bj][m][n] = mma_<I8>(Bt[n][k], At[m][k], acc[ai][bj][m][n]); __builtin_amdgcn_s_setprio(0); } while (0)
; #define PG8_WAIT_V(n) asm volatile("s_waitcnt vmcnt(" #n ")" ::: "memory")
; #define PG8_WAIT_L(n) asm volatile("s_waitcnt lgkmcnt(" #n ")" ::: "memory")
; #define PG8_BAR __builtin_amdgcn_s_barrier()
; #define PG8_SCHED __builtin_amdgcn_sched_barrier(0)
; template <class Epi, class Sched, bool ALIGN_EPI = false, bool SP2 = false, bool I8 = false>
; __device__ __forceinline__ void gemm_phase(PG8_LAS unsigned char* lds, const Gemm g, const Sched& S, const Epi& E) {
;     ...
;             PG8_WAIT_V(8); PG8_WAIT_L(0); PG8_BAR; PG8_MMA(1, 0, At, B0); PG8_MMA(1, 1, At, B1); PG8_BAR; PG8_SCHED;
;             PG8_LDB(B0, 1, 0); PG8_LDB(B1, 1, 1); PG8_SCHED; PG8_LDA(At, 1, 0); PG8_STAGE(PG8_SA(0, 1), a2 + hstepA, voffA);
;             PG8_WAIT_V(8); PG8_WAIT_L(0); PG8_BAR; PG8_MMA(0, 0, At, B0); PG8_MMA(0, 1, At, B1); PG8_BAR; PG8_SCHED;
	s_setprio 1
	s_waitcnt lgkmcnt(0)
	v_mfma_f32_16x16x32_bf16 v[62:65], v[146:149], v[182:185], v[62:65]
	v_mfma_f32_16x16x32_bf16 v[58:61], v[158:161], v[182:185], v[58:61]
	v_mfma_f32_16x16x32_bf16 v[54:57], v[146:149], v[190:193], v[54:57]
	v_mfma_f32_16x16x32_bf16 v[50:53], v[158:161], v[190:193], v[50:53]
	v_mfma_f32_16x16x32_bf16 v[30:33], v[146:149], v[198:201], v[30:33]
	v_mfma_f32_16x16x32_bf16 v[26:29], v[158:161], v[198:201], v[26:29]
	v_mfma_f32_16x16x32_bf16 v[22:25], v[146:149], v[206:209], v[22:25]
	v_mfma_f32_16x16x32_bf16 v[10:13], v[158:161], v[206:209], v[10:13]
	s_setprio 0
	s_setprio 1
	v_mfma_f32_16x16x32_bf16 v[62:65], v[150:153], v[186:189], v[62:65]
	v_mfma_f32_16x16x32_bf16 v[58:61], v[162:165], v[186:189], v[58:61]
	v_mfma_f32_16x16x32_bf16 v[54:57], v[150:153], v[194:197], v[54:57]
	v_mfma_f32_16x16x32_bf16 v[50:53], v[162:165], v[194:197], v[50:53]
	v_mfma_f32_16x16x32_bf16 v[30:33], v[150:153], v[202:205], v[30:33]
	v_mfma_f32_16x16x32_bf16 v[26:29], v[162:165], v[202:205], v[26:29]
	v_mfma_f32_16x16x32_bf16 v[22:25], v[150:153], v[210:213], v[22:25]
	v_mfma_f32_16x16x32_bf16 v[10:13], v[162:165], v[210:213], v[10:13]
	s_setprio 0
	s_setprio 1
	v_mfma_f32_16x16x32_bf16 v[46:49], v[166:169], v[182:185], v[46:49]
	v_mfma_f32_16x16x32_bf16 v[42:45], v[174:177], v[182:185], v[42:45]
	v_mfma_f32_16x16x32_bf16 v[38:41], v[166:169], v[190:193], v[38:41]
	v_mfma_f32_16x16x32_bf16 v[34:37], v[174:177], v[190:193], v[34:37]
	v_mfma_f32_16x16x32_bf16 v[18:21], v[166:169], v[198:201], v[18:21]
	v_mfma_f32_16x16x32_bf16 v[14:17], v[174:177], v[198:201], v[14:17]
	v_mfma_f32_16x16x32_bf16 v[6:9], v[166:169], v[206:209], v[6:9]
	v_mfma_f32_16x16x32_bf16 v[2:5], v[174:177], v[206:209], v[2:5]
	s_setprio 0
	s_setprio 1
	v_mfma_f32_16x16x32_bf16 v[46:49], v[170:173], v[186:189], v[46:49]
	v_mfma_f32_16x16x32_bf16 v[42:45], v[178:181], v[186:189], v[42:45]
	v_mfma_f32_16x16x32_bf16 v[38:41], v[170:173], v[194:197], v[38:41]
	v_mfma_f32_16x16x32_bf16 v[34:37], v[178:181], v[194:197], v[34:37]
	v_mfma_f32_16x16x32_bf16 v[18:21], v[170:173], v[202:205], v[18:21]
	v_mfma_f32_16x16x32_bf16 v[14:17], v[178:181], v[202:205], v[14:17]
	v_mfma_f32_16x16x32_bf16 v[6:9], v[170:173], v[210:213], v[6:9]
	v_mfma_f32_16x16x32_bf16 v[2:5], v[178:181], v[210:213], v[2:5]
	s_setprio 0
	s_barrier
	s_add_i32 s50, 0, 0x18000
	v_add_u32_e32 v157, s50, v1
	s_add_i32 s51, 0, 0x1c000
	ds_read_b128 v[146:149], v157
	ds_read_b128 v[150:153], v157 offset:1024
	ds_read_b128 v[158:161], v157 offset:2048
	ds_read_b128 v[162:165], v157 offset:3072
	v_add_u32_e32 v157, s51, v1
	ds_read_b128 v[166:169], v157
	ds_read_b128 v[170:173], v157 offset:1024
	ds_read_b128 v[174:177], v157 offset:2048
	ds_read_b128 v[178:181], v157 offset:3072
	s_add_u32 s26, s26, 0x20000
	s_addc_u32 s27, s27, 0
	s_mov_b32 m0, s36
	v_lshl_add_u64 v[222:223], s[26:27], 0, v[130:131]
	ds_read_b128 v[182:185], v156 offset:32768
	ds_read_b128 v[186:189], v156 offset:33792
	ds_read_b128 v[190:193], v156 offset:34816
	ds_read_b128 v[194:197], v156 offset:35840
	ds_read_b128 v[198:201], v156 offset:36864
	ds_read_b128 v[202:205], v156 offset:37888
	ds_read_b128 v[206:209], v156 offset:38912
	ds_read_b128 v[210:213], v156 offset:39936
	global_load_lds_dwordx4 v[222:223], off
	v_lshl_add_u64 v[222:223], s[26:27], 0, v[134:135]
	s_mov_b32 m0, s37
	s_nop 0
	global_load_lds_dwordx4 v[222:223], off
	s_waitcnt vmcnt(8)
	s_waitcnt lgkmcnt(0)
	s_barrier
	s_setprio 1
	s_waitcnt lgkmcnt(0)
	v_mfma_f32_16x16x32_bf16 v[126:129], v[146:149], v[182:185], v[126:129]
	v_mfma_f32_16x16x32_bf16 v[122:125], v[158:161], v[182:185], v[122:125]
	v_mfma_f32_16x16x32_bf16 v[114:117], v[146:149], v[190:193], v[114:117]
	v_mfma_f32_16x16x32_bf16 v[106:109], v[158:161], v[190:193], v[106:109]
	v_mfma_f32_16x16x32_bf16 v[94:97], v[146:149], v[198:201], v[94:97]
	v_mfma_f32_16x16x32_bf16 v[90:93], v[158:161], v[198:201], v[90:93]
	v_mfma_f32_16x16x32_bf16 v[86:89], v[146:149], v[206:209], v[86:89]
	v_mfma_f32_16x16x32_bf16 v[82:85], v[158:161], v[206:209], v[82:85]
	s_setprio 0
	s_setprio 1
	v_mfma_f32_16x16x32_bf16 v[126:129], v[150:153], v[186:189], v[126:129]
	v_mfma_f32_16x16x32_bf16 v[122:125], v[162:165], v[186:189], v[122:125]
	v_mfma_f32_16x16x32_bf16 v[114:117], v[150:153], v[194:197], v[114:117]
	v_mfma_f32_16x16x32_bf16 v[106:109], v[162:165], v[194:197], v[106:109]
	v_mfma_f32_16x16x32_bf16 v[94:97], v[150:153], v[202:205], v[94:97]
	v_mfma_f32_16x16x32_bf16 v[90:93], v[162:165], v[202:205], v[90:93]
	v_mfma_f32_16x16x32_bf16 v[86:89], v[150:153], v[210:213], v[86:89]
	v_mfma_f32_16x16x32_bf16 v[82:85], v[162:165], v[210:213], v[82:85]
	s_setprio 0
	s_setprio 1
	v_mfma_f32_16x16x32_bf16 v[118:121], v[166:169], v[182:185], v[118:121]
	v_mfma_f32_16x16x32_bf16 v[110:113], v[174:177], v[182:185], v[110:113]
	v_mfma_f32_16x16x32_bf16 v[102:105], v[166:169], v[190:193], v[102:105]
	v_mfma_f32_16x16x32_bf16 v[98:101], v[174:177], v[190:193], v[98:101]
	v_mfma_f32_16x16x32_bf16 v[78:81], v[166:169], v[198:201], v[78:81]
	v_mfma_f32_16x16x32_bf16 v[74:77], v[174:177], v[198:201], v[74:77]
	v_mfma_f32_16x16x32_bf16 v[70:73], v[166:169], v[206:209], v[70:73]
	v_mfma_f32_16x16x32_bf16 v[66:69], v[174:177], v[206:209], v[66:69]
	s_setprio 0
	s_setprio 1
	v_mfma_f32_16x16x32_bf16 v[118:121], v[170:173], v[186:189], v[118:121]
	v_mfma_f32_16x16x32_bf16 v[110:113], v[178:181], v[186:189], v[110:113]
	v_mfma_f32_16x16x32_bf16 v[102:105], v[170:173], v[194:197], v[102:105]
	v_mfma_f32_16x16x32_bf16 v[98:101], v[178:181], v[194:197], v[98:101]
	v_mfma_f32_16x16x32_bf16 v[78:81], v[170:173], v[202:205], v[78:81]
	v_mfma_f32_16x16x32_bf16 v[74:77], v[178:181], v[202:205], v[74:77]
	v_mfma_f32_16x16x32_bf16 v[70:73], v[170:173], v[210:213], v[70:73]
	v_mfma_f32_16x16x32_bf16 v[66:69], v[178:181], v[210:213], v[66:69]
	s_setprio 0
	s_barrier
; #define PG8_STAGE(bufoff, gbase, voff) do { _Pragma("unroll") for (int _i = 0; _i < 2; ++_i) \
;         __builtin_amdgcn_global_load_lds((const unsigned*)((const char*)(gbase) + (voff)[_i]), (PG8_LAS unsigned*)(lds + (bufoff) + ldsw + _i * 8192), 16, 0, 0); } while (0)
; #define PG8_LDA(dst, b, h) do { _Pragma("unroll") for (int m = 0; m < 4; ++m) _Pragma("unroll") for (int k = 0; k < 2; ++k) dst[m][k] = *(const PG8_LAS bf16x8*)(lds + PG8_SA(b, h) + aoff + m * 2048 + k * 1024); } while (0)
; #define PG8_MMA(ai, bj, At, Bt) do { __builtin_amdgcn_s_setprio(1); _Pragma("unroll") for (int m = 0; m < 4; ++m) _Pragma("unroll") for (int n = 0; n < 2; ++n) _Pragma("unroll") for (int k = 0; k < 2; ++k) \
;         acc[ai][bj][m][n] = mma_<I8>(Bt[n][k], At[m][k], acc[ai][bj][m][n]); __builtin_amdgcn_s_setprio(0); } while (0)
; #define PG8_WAIT_V(n) asm volatile("s_waitcnt vmcnt(" #n ")" ::: "memory")
; #define PG8_WAIT_L(n) asm volatile("s_waitcnt lgkmcnt(" #n ")" ::: "memory")
; #define PG8_BAR __builtin_amdgcn_s_barrier()
; #define PG8_SCHED __builtin_amdgcn_sched_barrier(0)
; template <class Epi, class Sched, bool ALIGN_EPI = false, bool SP2 = false, bool I8 = false>
; __device__ __forceinline__ void gemm_phase(PG8_LAS unsigned char* lds, const Gemm g, const Sched& S, const Epi& E) {
;     ...
;             PG8_LDA(At, 1, 1); PG8_STAGE(PG8_SB(1, 0), b3, voffB); PG8_STAGE(PG8_SB(1, 1), b3 + hstepB, voffB); PG8_STAGE(PG8_SA(1, 0), a3, voffA);
;             PG8_WAIT_V(8); PG8_WAIT_L(0); PG8_BAR; PG8_MMA(1, 0, At, B0); PG8_MMA(1, 1, At, B1); PG8_BAR; PG8_SCHED;
;     ...
;         if constexpr (ALIGN_EPI) { if (wr == 0) PG8_BAR; }
	s_add_i32 s26, s50, s34
	v_lshl_add_u64 v[214:215], v[214:215], 0, s[8:9]
	s_mov_b32 m0, s26
	ds_read_b128 v[182:185], v156 offset:49152
	ds_read_b128 v[186:189], v156 offset:50176
	ds_read_b128 v[190:193], v156 offset:51200
	ds_read_b128 v[194:197], v156 offset:52224
	ds_read_b128 v[198:201], v156 offset:53248
	ds_read_b128 v[202:205], v156 offset:54272
	ds_read_b128 v[206:209], v156 offset:55296
	ds_read_b128 v[210:213], v156 offset:56320
	global_load_lds_dwordx4 v[214:215], off
	s_add_i32 m0, s26, 0x2000
	s_add_u32 s24, s24, 0x20080
	v_lshl_add_u64 v[214:215], v[216:217], 0, s[8:9]
	s_addc_u32 s25, s25, 0
	s_add_i32 s26, s51, s34
	global_load_lds_dwordx4 v[214:215], off
	v_lshl_add_u64 v[214:215], s[24:25], 0, v[132:133]
	s_mov_b32 m0, s26
	s_nop 0
	global_load_lds_dwordx4 v[214:215], off
	v_lshl_add_u64 v[214:215], s[24:25], 0, v[136:137]
	s_add_i32 m0, s26, 0x2000
	s_nop 0
	global_load_lds_dwordx4 v[214:215], off
	v_lshl_add_u64 v[214:215], v[218:219], 0, s[8:9]
	s_mov_b32 m0, s39
	s_nop 0
	global_load_lds_dwordx4 v[214:215], off
	v_lshl_add_u64 v[214:215], v[220:221], 0, s[8:9]
	s_mov_b32 m0, s40
	s_nop 0
	global_load_lds_dwordx4 v[214:215], off
	s_waitcnt vmcnt(8)
	s_waitcnt lgkmcnt(0)
	s_barrier
	s_setprio 1
	s_waitcnt lgkmcnt(0)
	v_mfma_f32_16x16x32_bf16 v[62:65], v[146:149], v[182:185], v[62:65]
	v_mfma_f32_16x16x32_bf16 v[58:61], v[158:161], v[182:185], v[58:61]
	v_mfma_f32_16x16x32_bf16 v[54:57], v[146:149], v[190:193], v[54:57]
	v_mfma_f32_16x16x32_bf16 v[50:53], v[158:161], v[190:193], v[50:53]
	v_mfma_f32_16x16x32_bf16 v[30:33], v[146:149], v[198:201], v[30:33]
	v_mfma_f32_16x16x32_bf16 v[26:29], v[158:161], v[198:201], v[26:29]
	v_mfma_f32_16x16x32_bf16 v[22:25], v[146:149], v[206:209], v[22:25]
	v_mfma_f32_16x16x32_bf16 v[10:13], v[158:161], v[206:209], v[10:13]
	s_setprio 0
	s_setprio 1
	v_mfma_f32_16x16x32_bf16 v[62:65], v[150:153], v[186:189], v[62:65]
	v_mfma_f32_16x16x32_bf16 v[58:61], v[162:165], v[186:189], v[58:61]
	v_mfma_f32_16x16x32_bf16 v[54:57], v[150:153], v[194:197], v[54:57]
	v_mfma_f32_16x16x32_bf16 v[50:53], v[162:165], v[194:197], v[50:53]
	v_mfma_f32_16x16x32_bf16 v[30:33], v[150:153], v[202:205], v[30:33]
	v_mfma_f32_16x16x32_bf16 v[26:29], v[162:165], v[202:205], v[26:29]
	v_mfma_f32_16x16x32_bf16 v[22:25], v[150:153], v[210:213], v[22:25]
	v_mfma_f32_16x16x32_bf16 v[10:13], v[162:165], v[210:213], v[10:13]
	s_setprio 0
	s_setprio 1
	v_mfma_f32_16x16x32_bf16 v[46:49], v[166:169], v[182:185], v[46:49]
	v_mfma_f32_16x16x32_bf16 v[42:45], v[174:177], v[182:185], v[42:45]
	v_mfma_f32_16x16x32_bf16 v[38:41], v[166:169], v[190:193], v[38:41]
	v_mfma_f32_16x16x32_bf16 v[34:37], v[174:177], v[190:193], v[34:37]
	v_mfma_f32_16x16x32_bf16 v[18:21], v[166:169], v[198:201], v[18:21]
	v_mfma_f32_16x16x32_bf16 v[14:17], v[174:177], v[198:201], v[14:17]
	v_mfma_f32_16x16x32_bf16 v[6:9], v[166:169], v[206:209], v[6:9]
	v_mfma_f32_16x16x32_bf16 v[2:5], v[174:177], v[206:209], v[2:5]
	s_setprio 0
	s_setprio 1
	v_mfma_f32_16x16x32_bf16 v[46:49], v[170:173], v[186:189], v[46:49]
	v_mfma_f32_16x16x32_bf16 v[42:45], v[178:181], v[186:189], v[42:45]
	v_mfma_f32_16x16x32_bf16 v[38:41], v[170:173], v[194:197], v[38:41]
	v_mfma_f32_16x16x32_bf16 v[34:37], v[178:181], v[194:197], v[34:37]
	v_mfma_f32_16x16x32_bf16 v[18:21], v[170:173], v[202:205], v[18:21]
	v_mfma_f32_16x16x32_bf16 v[14:17], v[178:181], v[202:205], v[14:17]
	v_mfma_f32_16x16x32_bf16 v[6:9], v[170:173], v[210:213], v[6:9]
	v_mfma_f32_16x16x32_bf16 v[2:5], v[178:181], v[210:213], v[2:5]
	s_setprio 0
	s_barrier
	s_add_i32 s49, s49, 2
	s_add_u32 s22, s22, 0x100
	s_addc_u32 s23, s23, 0
	s_add_u32 s47, s47, 0x100
	s_addc_u32 s48, s48, 0
	s_cmp_gt_u32 s49, 5
	s_cbranch_scc0 .LBB0_1538
	s_and_b64 vcc, exec, s[10:11]
	s_cbranch_vccz .LBB0_1541
	s_barrier

; #define PG8_STAGE(bufoff, gbase, voff) do { _Pragma("unroll") for (int _i = 0; _i < 2; ++_i) \
;         __builtin_amdgcn_global_load_lds((const unsigned*)((const char*)(gbase) + (voff)[_i]), (PG8_LAS unsigned*)(lds + (bufoff) + ldsw + _i * 8192), 16, 0, 0); } while (0)
; #define PG8_LDA(dst, b, h) do { _Pragma("unroll") for (int m = 0; m < 4; ++m) _Pragma("unroll") for (int k = 0; k < 2; ++k) dst[m][k] = *(const PG8_LAS bf16x8*)(lds + PG8_SA(b, h) + aoff + m * 2048 + k * 1024); } while (0)
; #define PG8_LDB(dst, b, h) do { _Pragma("unroll") for (int n = 0; n < 2; ++n) _Pragma("unroll") for (int k = 0; k < 2; ++k) dst[n][k] = *(const PG8_LAS bf16x8*)(lds + PG8_SB(b, h) + boff + n * 2048 + k * 1024); } while (0)
; #define PG8_MMA(ai, bj, At, Bt) do { __builtin_amdgcn_s_setprio(1); _Pragma("unroll") for (int m = 0; m < 4; ++m) _Pragma("unroll") for (int n = 0; n < 2; ++n) _Pragma("unroll") for (int k = 0; k < 2; ++k) \
;         acc[ai][bj][m][n] = mma_<I8>(Bt[n][k], At[m][k], acc[ai][bj][m][n]); __builtin_amdgcn_s_setprio(0); } while (0)
; #define PG8_WAIT_V(n) asm volatile("s_waitcnt vmcnt(" #n ")" ::: "memory")
; #define PG8_WAIT_L(n) asm volatile("s_waitcnt lgkmcnt(" #n ")" ::: "memory")
; #define PG8_BAR __builtin_amdgcn_s_barrier()
; template <class Epi, class Sched, bool ALIGN_EPI = false, bool SP2 = false, bool I8 = false>
; __device__ __forceinline__ void gemm_phase(PG8_LAS unsigned char* lds, const Gemm g, const Sched& S, const Epi& E) {
;     ...
;             const bool last = (t == nt - 2);
;             const char* a1 = cA + (size_t)(t + 1) * kstep;
;             const char* a2 = last ? nA : cA + (size_t)(t + 2) * kstep; const char* b2 = last ? nB : cB + (size_t)(t + 2) * kstep;
;             const char* a3 = a2 + kstep; const char* b3 = b2 + kstep;
;             if (last && has_next) S.a_ready(nxt);
;             if constexpr (SP2) {
;             PG8_LDB(B0, 0, 0); PG8_LDB(B1, 0, 1); PG8_SCHED; PG8_LDA(At, 0, 0); PG8_STAGE(PG8_SA(1, 1), a1 + hstepA, voffA);
;             PG8_WAIT_V(8); PG8_WAIT_L(0); PG8_BAR; PG8_MMA(0, 0, At, B0); PG8_MMA(0, 1, At, B1); PG8_BAR; PG8_SCHED;
;             PG8_LDA(At, 0, 1); PG8_STAGE(PG8_SB(0, 0), b2, voffB); PG8_STAGE(PG8_SB(0, 1), b2 + hstepB, voffB); PG8_STAGE(PG8_SA(0, 0), a2, voffA);
;             PG8_WAIT_V(8); PG8_WAIT_L(0); PG8_BAR; PG8_MMA(1, 0, At, B0); PG8_MMA(1, 1, At, B1); PG8_BAR; PG8_SCHED;
.LBB0_1565:
	ds_read_b128 v[130:133], v176
	ds_read_b128 v[134:137], v176 offset:1024
	ds_read_b128 v[138:141], v176 offset:2048
	ds_read_b128 v[142:145], v176 offset:3072
	ds_read_b128 v[162:165], v177
	ds_read_b128 v[166:169], v177 offset:1024
	ds_read_b128 v[170:173], v177 offset:2048
	ds_read_b128 v[180:183], v177 offset:3072
	s_add_u32 s30, s28, 0xfff80080
	s_addc_u32 s31, s29, -1
	s_cmp_eq_u32 s54, 28
	s_cselect_b32 s35, s7, s31
	s_cselect_b32 s34, s21, s30
	s_cselect_b32 s31, s19, s53
	s_cselect_b32 s30, s27, s52
	v_lshl_add_u64 v[174:175], s[28:29], 0, v[154:155]
	s_add_i32 m0, s40, 0xc000
	ds_read_b128 v[184:187], v178
	ds_read_b128 v[188:191], v178 offset:1024
	ds_read_b128 v[192:195], v178 offset:2048
	ds_read_b128 v[196:199], v178 offset:3072
	ds_read_b128 v[200:203], v178 offset:4096
	ds_read_b128 v[204:207], v178 offset:5120
	ds_read_b128 v[208:211], v178 offset:6144
	ds_read_b128 v[212:215], v178 offset:7168
	global_load_lds_dwordx4 v[174:175], off
	v_lshl_add_u64 v[174:175], s[28:29], 0, v[156:157]
	s_add_i32 m0, s40, 0xe000
	s_nop 0
	global_load_lds_dwordx4 v[174:175], off
	s_waitcnt vmcnt(8)
	s_waitcnt lgkmcnt(0)
	s_barrier
	s_setprio 1
	s_waitcnt lgkmcnt(0)
	v_mfma_f32_16x16x32_bf16 v[126:129], v[130:133], v[184:187], v[126:129]
	v_mfma_f32_16x16x32_bf16 v[122:125], v[138:141], v[184:187], v[122:125]
	v_mfma_f32_16x16x32_bf16 v[110:113], v[130:133], v[192:195], v[110:113]
	v_mfma_f32_16x16x32_bf16 v[106:109], v[138:141], v[192:195], v[106:109]
	v_mfma_f32_16x16x32_bf16 v[94:97], v[130:133], v[200:203], v[94:97]
	v_mfma_f32_16x16x32_bf16 v[90:93], v[138:141], v[200:203], v[90:93]
	v_mfma_f32_16x16x32_bf16 v[78:81], v[130:133], v[208:211], v[78:81]
	v_mfma_f32_16x16x32_bf16 v[74:77], v[138:141], v[208:211], v[74:77]
	s_setprio 0
	s_setprio 1
	v_mfma_f32_16x16x32_bf16 v[126:129], v[134:137], v[188:191], v[126:129]
	v_mfma_f32_16x16x32_bf16 v[122:125], v[142:145], v[188:191], v[122:125]
	v_mfma_f32_16x16x32_bf16 v[110:113], v[134:137], v[196:199], v[110:113]
	v_mfma_f32_16x16x32_bf16 v[106:109], v[142:145], v[196:199], v[106:109]
	v_mfma_f32_16x16x32_bf16 v[94:97], v[134:137], v[204:207], v[94:97]
	v_mfma_f32_16x16x32_bf16 v[90:93], v[142:145], v[204:207], v[90:93]
	v_mfma_f32_16x16x32_bf16 v[78:81], v[134:137], v[212:215], v[78:81]
	v_mfma_f32_16x16x32_bf16 v[74:77], v[142:145], v[212:215], v[74:77]
	s_setprio 0
	s_setprio 1
	v_mfma_f32_16x16x32_bf16 v[118:121], v[162:165], v[184:187], v[118:121]
	v_mfma_f32_16x16x32_bf16 v[114:117], v[170:173], v[184:187], v[114:117]
	v_mfma_f32_16x16x32_bf16 v[102:105], v[162:165], v[192:195], v[102:105]
	v_mfma_f32_16x16x32_bf16 v[98:101], v[170:173], v[192:195], v[98:101]
	v_mfma_f32_16x16x32_bf16 v[86:89], v[162:165], v[200:203], v[86:89]
	v_mfma_f32_16x16x32_bf16 v[82:85], v[170:173], v[200:203], v[82:85]
	v_mfma_f32_16x16x32_bf16 v[70:73], v[162:165], v[208:211], v[70:73]
	v_mfma_f32_16x16x32_bf16 v[66:69], v[170:173], v[208:211], v[66:69]
	s_setprio 0
	s_setprio 1
	v_mfma_f32_16x16x32_bf16 v[118:121], v[166:169], v[188:191], v[118:121]
	v_mfma_f32_16x16x32_bf16 v[114:117], v[180:183], v[188:191], v[114:117]
	v_mfma_f32_16x16x32_bf16 v[102:105], v[166:169], v[196:199], v[102:105]
	v_mfma_f32_16x16x32_bf16 v[98:101], v[180:183], v[196:199], v[98:101]
	v_mfma_f32_16x16x32_bf16 v[86:89], v[166:169], v[204:207], v[86:89]
	v_mfma_f32_16x16x32_bf16 v[82:85], v[180:183], v[204:207], v[82:85]
	v_mfma_f32_16x16x32_bf16 v[70:73], v[166:169], v[212:215], v[70:73]
	v_mfma_f32_16x16x32_bf16 v[66:69], v[180:183], v[212:215], v[66:69]
	s_setprio 0
	s_barrier
	s_add_i32 s55, s50, s39
	v_lshl_add_u64 v[174:175], s[30:31], 0, v[148:149]
	s_mov_b32 m0, s55
	ds_read_b128 v[184:187], v178 offset:16384
	ds_read_b128 v[188:191], v178 offset:17408
	ds_read_b128 v[192:195], v178 offset:18432
	ds_read_b128 v[196:199], v178 offset:19456
	ds_read_b128 v[200:203], v178 offset:20480
	ds_read_b128 v[204:207], v178 offset:21504
	ds_read_b128 v[208:211], v178 offset:22528
	ds_read_b128 v[212:215], v178 offset:23552
	global_load_lds_dwordx4 v[174:175], off
	s_add_i32 m0, s55, 0x2000
	s_add_u32 s56, s30, 0x80000
	v_lshl_add_u64 v[216:217], s[30:31], 0, v[152:153]
	s_addc_u32 s57, s31, 0
	s_add_i32 s55, s51, s39
	global_load_lds_dwordx4 v[216:217], off
	v_lshl_add_u64 v[218:219], s[56:57], 0, v[148:149]
	s_mov_b32 m0, s55
	v_lshl_add_u64 v[220:221], s[34:35], 0, v[150:151]
	global_load_lds_dwordx4 v[218:219], off
	v_lshl_add_u64 v[218:219], s[56:57], 0, v[152:153]
	s_add_i32 m0, s55, 0x2000
	s_nop 0
	global_load_lds_dwordx4 v[218:219], off
	v_lshl_add_u64 v[218:219], s[34:35], 0, v[146:147]
	s_mov_b32 m0, s40
	s_nop 0
	global_load_lds_dwordx4 v[218:219], off
	s_mov_b32 m0, s41
	s_nop 0
	global_load_lds_dwordx4 v[220:221], off
	s_waitcnt vmcnt(8)
	s_waitcnt lgkmcnt(0)
	s_barrier
; #define PG8_STAGE(bufoff, gbase, voff) do { _Pragma("unroll") for (int _i = 0; _i < 2; ++_i) \
;         __builtin_amdgcn_global_load_lds((const unsigned*)((const char*)(gbase) + (voff)[_i]), (PG8_LAS unsigned*)(lds + (bufoff) + ldsw + _i * 8192), 16, 0, 0); } while (0)
; #define PG8_LDA(dst, b, h) do { _Pragma("unroll") for (int m = 0; m < 4; ++m) _Pragma("unroll") for (int k = 0; k < 2; ++k) dst[m][k] = *(const PG8_LAS bf16x8*)(lds + PG8_SA(b, h) + aoff + m * 2048 + k * 1024); } while (0)
; #define PG8_LDB(dst, b, h) do { _Pragma("unroll") for (int n = 0; n < 2; ++n) _Pragma("unroll") for (int k = 0; k < 2; ++k) dst[n][k] = *(const PG8_LAS bf16x8*)(lds + PG8_SB(b, h) + boff + n * 2048 + k * 1024); } while (0)
; #define PG8_MMA(ai, bj, At, Bt) do { __builtin_amdgcn_s_setprio(1); _Pragma("unroll") for (int m = 0; m < 4; ++m) _Pragma("unroll") for (int n = 0; n < 2; ++n) _Pragma("unroll") for (int k = 0; k < 2; ++k) \
;         acc[ai][bj][m][n] = mma_<I8>(Bt[n][k], At[m][k], acc[ai][bj][m][n]); __builtin_amdgcn_s_setprio(0); } while (0)
; #define PG8_WAIT_V(n) asm volatile("s_waitcnt vmcnt(" #n ")" ::: "memory")
; #define PG8_WAIT_L(n) asm volatile("s_waitcnt lgkmcnt(" #n ")" ::: "memory")
; #define PG8_BAR __builtin_amdgcn_s_barrier()
; #define PG8_SCHED __builtin_amdgcn_sched_barrier(0)
; template <class Epi, class Sched, bool ALIGN_EPI = false, bool SP2 = false, bool I8 = false>
; __device__ __forceinline__ void gemm_phase(PG8_LAS unsigned char* lds, const Gemm g, const Sched& S, const Epi& E) {
;     ...
;             PG8_WAIT_V(8); PG8_WAIT_L(0); PG8_BAR; PG8_MMA(1, 0, At, B0); PG8_MMA(1, 1, At, B1); PG8_BAR; PG8_SCHED;
;             PG8_LDB(B0, 1, 0); PG8_LDB(B1, 1, 1); PG8_SCHED; PG8_LDA(At, 1, 0); PG8_STAGE(PG8_SA(0, 1), a2 + hstepA, voffA);
;             PG8_WAIT_V(8); PG8_WAIT_L(0); PG8_BAR; PG8_MMA(0, 0, At, B0); PG8_MMA(0, 1, At, B1); PG8_BAR; PG8_SCHED;
	s_setprio 1
	s_waitcnt lgkmcnt(0)
	v_mfma_f32_16x16x32_bf16 v[62:65], v[130:133], v[184:187], v[62:65]
	v_mfma_f32_16x16x32_bf16 v[58:61], v[138:141], v[184:187], v[58:61]
	v_mfma_f32_16x16x32_bf16 v[46:49], v[130:133], v[192:195], v[46:49]
	v_mfma_f32_16x16x32_bf16 v[42:45], v[138:141], v[192:195], v[42:45]
	v_mfma_f32_16x16x32_bf16 v[30:33], v[130:133], v[200:203], v[30:33]
	v_mfma_f32_16x16x32_bf16 v[26:29], v[138:141], v[200:203], v[26:29]
	v_mfma_f32_16x16x32_bf16 v[14:17], v[130:133], v[208:211], v[14:17]
	v_mfma_f32_16x16x32_bf16 v[10:13], v[138:141], v[208:211], v[10:13]
	s_setprio 0
	s_setprio 1
	v_mfma_f32_16x16x32_bf16 v[62:65], v[134:137], v[188:191], v[62:65]
	v_mfma_f32_16x16x32_bf16 v[58:61], v[142:145], v[188:191], v[58:61]
	v_mfma_f32_16x16x32_bf16 v[46:49], v[134:137], v[196:199], v[46:49]
	v_mfma_f32_16x16x32_bf16 v[42:45], v[142:145], v[196:199], v[42:45]
	v_mfma_f32_16x16x32_bf16 v[30:33], v[134:137], v[204:207], v[30:33]
	v_mfma_f32_16x16x32_bf16 v[26:29], v[142:145], v[204:207], v[26:29]
	v_mfma_f32_16x16x32_bf16 v[14:17], v[134:137], v[212:215], v[14:17]
	v_mfma_f32_16x16x32_bf16 v[10:13], v[142:145], v[212:215], v[10:13]
	s_setprio 0
	s_setprio 1
	v_mfma_f32_16x16x32_bf16 v[54:57], v[162:165], v[184:187], v[54:57]
	v_mfma_f32_16x16x32_bf16 v[50:53], v[170:173], v[184:187], v[50:53]
	v_mfma_f32_16x16x32_bf16 v[38:41], v[162:165], v[192:195], v[38:41]
	v_mfma_f32_16x16x32_bf16 v[34:37], v[170:173], v[192:195], v[34:37]
	v_mfma_f32_16x16x32_bf16 v[22:25], v[162:165], v[200:203], v[22:25]
	v_mfma_f32_16x16x32_bf16 v[18:21], v[170:173], v[200:203], v[18:21]
	v_mfma_f32_16x16x32_bf16 v[6:9], v[162:165], v[208:211], v[6:9]
	v_mfma_f32_16x16x32_bf16 v[2:5], v[170:173], v[208:211], v[2:5]
	s_setprio 0
	s_setprio 1
	v_mfma_f32_16x16x32_bf16 v[54:57], v[166:169], v[188:191], v[54:57]
	v_mfma_f32_16x16x32_bf16 v[50:53], v[180:183], v[188:191], v[50:53]
	v_mfma_f32_16x16x32_bf16 v[38:41], v[166:169], v[196:199], v[38:41]
	v_mfma_f32_16x16x32_bf16 v[34:37], v[180:183], v[196:199], v[34:37]
	v_mfma_f32_16x16x32_bf16 v[22:25], v[166:169], v[204:207], v[22:25]
	v_mfma_f32_16x16x32_bf16 v[18:21], v[180:183], v[204:207], v[18:21]
	v_mfma_f32_16x16x32_bf16 v[6:9], v[166:169], v[212:215], v[6:9]
	v_mfma_f32_16x16x32_bf16 v[2:5], v[180:183], v[212:215], v[2:5]
	s_setprio 0
	s_barrier
	s_add_i32 s55, 0, 0x18000
	s_add_i32 s56, 0, 0x1c000
	v_add_u32_e32 v142, s55, v1
	v_add_u32_e32 v180, s56, v1
	ds_read_b128 v[130:133], v142
	ds_read_b128 v[134:137], v142 offset:1024
	ds_read_b128 v[138:141], v142 offset:2048
	ds_read_b128 v[142:145], v142 offset:3072
	ds_read_b128 v[162:165], v180
	ds_read_b128 v[166:169], v180 offset:1024
	ds_read_b128 v[170:173], v180 offset:2048
	ds_read_b128 v[180:183], v180 offset:3072
	s_add_u32 s34, s34, 0x80000
	s_addc_u32 s35, s35, 0
	s_mov_b32 m0, s42
	v_lshl_add_u64 v[222:223], s[34:35], 0, v[146:147]
	ds_read_b128 v[184:187], v178 offset:32768
	ds_read_b128 v[188:191], v178 offset:33792
	ds_read_b128 v[192:195], v178 offset:34816
	ds_read_b128 v[196:199], v178 offset:35840
	ds_read_b128 v[200:203], v178 offset:36864
	ds_read_b128 v[204:207], v178 offset:37888
	ds_read_b128 v[208:211], v178 offset:38912
	ds_read_b128 v[212:215], v178 offset:39936
	global_load_lds_dwordx4 v[222:223], off
	v_lshl_add_u64 v[222:223], s[34:35], 0, v[150:151]
	s_mov_b32 m0, s43
	s_nop 0
	global_load_lds_dwordx4 v[222:223], off
	s_waitcnt vmcnt(8)
	s_waitcnt lgkmcnt(0)
	s_barrier
	s_setprio 1
	s_waitcnt lgkmcnt(0)
	v_mfma_f32_16x16x32_bf16 v[126:129], v[130:133], v[184:187], v[126:129]
	v_mfma_f32_16x16x32_bf16 v[122:125], v[138:141], v[184:187], v[122:125]
	v_mfma_f32_16x16x32_bf16 v[110:113], v[130:133], v[192:195], v[110:113]
	v_mfma_f32_16x16x32_bf16 v[106:109], v[138:141], v[192:195], v[106:109]
	v_mfma_f32_16x16x32_bf16 v[94:97], v[130:133], v[200:203], v[94:97]
	v_mfma_f32_16x16x32_bf16 v[90:93], v[138:141], v[200:203], v[90:93]
	v_mfma_f32_16x16x32_bf16 v[78:81], v[130:133], v[208:211], v[78:81]
	v_mfma_f32_16x16x32_bf16 v[74:77], v[138:141], v[208:211], v[74:77]
	s_setprio 0
	s_setprio 1
	v_mfma_f32_16x16x32_bf16 v[126:129], v[134:137], v[188:191], v[126:129]
	v_mfma_f32_16x16x32_bf16 v[122:125], v[142:145], v[188:191], v[122:125]
	v_mfma_f32_16x16x32_bf16 v[110:113], v[134:137], v[196:199], v[110:113]
	v_mfma_f32_16x16x32_bf16 v[106:109], v[142:145], v[196:199], v[106:109]
	v_mfma_f32_16x16x32_bf16 v[94:97], v[134:137], v[204:207], v[94:97]
	v_mfma_f32_16x16x32_bf16 v[90:93], v[142:145], v[204:207], v[90:93]
	v_mfma_f32_16x16x32_bf16 v[78:81], v[134:137], v[212:215], v[78:81]
	v_mfma_f32_16x16x32_bf16 v[74:77], v[142:145], v[212:215], v[74:77]
	s_setprio 0
	s_setprio 1
	v_mfma_f32_16x16x32_bf16 v[118:121], v[162:165], v[184:187], v[118:121]
	v_mfma_f32_16x16x32_bf16 v[114:117], v[170:173], v[184:187], v[114:117]
	v_mfma_f32_16x16x32_bf16 v[102:105], v[162:165], v[192:195], v[102:105]
	v_mfma_f32_16x16x32_bf16 v[98:101], v[170:173], v[192:195], v[98:101]
	v_mfma_f32_16x16x32_bf16 v[86:89], v[162:165], v[200:203], v[86:89]
	v_mfma_f32_16x16x32_bf16 v[82:85], v[170:173], v[200:203], v[82:85]
	v_mfma_f32_16x16x32_bf16 v[70:73], v[162:165], v[208:211], v[70:73]
	v_mfma_f32_16x16x32_bf16 v[66:69], v[170:173], v[208:211], v[66:69]
	s_setprio 0
	s_setprio 1
	v_mfma_f32_16x16x32_bf16 v[118:121], v[166:169], v[188:191], v[118:121]
	v_mfma_f32_16x16x32_bf16 v[114:117], v[180:183], v[188:191], v[114:117]
	v_mfma_f32_16x16x32_bf16 v[102:105], v[166:169], v[196:199], v[102:105]
	v_mfma_f32_16x16x32_bf16 v[98:101], v[180:183], v[196:199], v[98:101]
	v_mfma_f32_16x16x32_bf16 v[86:89], v[166:169], v[204:207], v[86:89]
	v_mfma_f32_16x16x32_bf16 v[82:85], v[180:183], v[204:207], v[82:85]
	v_mfma_f32_16x16x32_bf16 v[70:73], v[166:169], v[212:215], v[70:73]
	v_mfma_f32_16x16x32_bf16 v[66:69], v[180:183], v[212:215], v[66:69]
	s_setprio 0
	s_barrier
; #define PG8_STAGE(bufoff, gbase, voff) do { _Pragma("unroll") for (int _i = 0; _i < 2; ++_i) \
;         __builtin_amdgcn_global_load_lds((const unsigned*)((const char*)(gbase) + (voff)[_i]), (PG8_LAS unsigned*)(lds + (bufoff) + ldsw + _i * 8192), 16, 0, 0); } while (0)
; #define PG8_LDA(dst, b, h) do { _Pragma("unroll") for (int m = 0; m < 4; ++m) _Pragma("unroll") for (int k = 0; k < 2; ++k) dst[m][k] = *(const PG8_LAS bf16x8*)(lds + PG8_SA(b, h) + aoff + m * 2048 + k * 1024); } while (0)
; #define PG8_MMA(ai, bj, At, Bt) do { __builtin_amdgcn_s_setprio(1); _Pragma("unroll") for (int m = 0; m < 4; ++m) _Pragma("unroll") for (int n = 0; n < 2; ++n) _Pragma("unroll") for (int k = 0; k < 2; ++k) \
;         acc[ai][bj][m][n] = mma_<I8>(Bt[n][k], At[m][k], acc[ai][bj][m][n]); __builtin_amdgcn_s_setprio(0); } while (0)
; #define PG8_WAIT_V(n) asm volatile("s_waitcnt vmcnt(" #n ")" ::: "memory")
; #define PG8_WAIT_L(n) asm volatile("s_waitcnt lgkmcnt(" #n ")" ::: "memory")
; #define PG8_BAR __builtin_amdgcn_s_barrier()
; #define PG8_SCHED __builtin_amdgcn_sched_barrier(0)
; template <class Epi, class Sched, bool ALIGN_EPI = false, bool SP2 = false, bool I8 = false>
; __device__ __forceinline__ void gemm_phase(PG8_LAS unsigned char* lds, const Gemm g, const Sched& S, const Epi& E) {
;     ...
;             PG8_LDA(At, 1, 1); PG8_STAGE(PG8_SB(1, 0), b3, voffB); PG8_STAGE(PG8_SB(1, 1), b3 + hstepB, voffB); PG8_STAGE(PG8_SA(1, 0), a3, voffA);
;             PG8_WAIT_V(8); PG8_WAIT_L(0); PG8_BAR; PG8_MMA(1, 0, At, B0); PG8_MMA(1, 1, At, B1); PG8_BAR; PG8_SCHED;
;     ...
;         if constexpr (ALIGN_EPI) { if (wr == 0) PG8_BAR; }
	s_add_i32 s34, s55, s39
	v_lshl_add_u64 v[174:175], v[174:175], 0, s[14:15]
	s_mov_b32 m0, s34
	ds_read_b128 v[184:187], v178 offset:49152
	ds_read_b128 v[188:191], v178 offset:50176
	ds_read_b128 v[192:195], v178 offset:51200
	ds_read_b128 v[196:199], v178 offset:52224
	ds_read_b128 v[200:203], v178 offset:53248
	ds_read_b128 v[204:207], v178 offset:54272
	ds_read_b128 v[208:211], v178 offset:55296
	ds_read_b128 v[212:215], v178 offset:56320
	global_load_lds_dwordx4 v[174:175], off
	s_add_i32 m0, s34, 0x2000
	s_add_u32 s30, s30, 0x80080
	v_lshl_add_u64 v[174:175], v[216:217], 0, s[14:15]
	s_addc_u32 s31, s31, 0
	s_add_i32 s34, s56, s39
	global_load_lds_dwordx4 v[174:175], off
	v_lshl_add_u64 v[174:175], s[30:31], 0, v[148:149]
	s_mov_b32 m0, s34
	s_nop 0
	global_load_lds_dwordx4 v[174:175], off
	v_lshl_add_u64 v[174:175], s[30:31], 0, v[152:153]
	s_add_i32 m0, s34, 0x2000
	s_nop 0
	global_load_lds_dwordx4 v[174:175], off
	v_lshl_add_u64 v[174:175], v[218:219], 0, s[14:15]
	s_mov_b32 m0, s46
	s_nop 0
	global_load_lds_dwordx4 v[174:175], off
	v_lshl_add_u64 v[174:175], v[220:221], 0, s[14:15]
	s_mov_b32 m0, s47
	s_nop 0
	global_load_lds_dwordx4 v[174:175], off
	s_waitcnt vmcnt(8)
	s_waitcnt lgkmcnt(0)
	s_barrier
	s_setprio 1
	s_waitcnt lgkmcnt(0)
	v_mfma_f32_16x16x32_bf16 v[62:65], v[130:133], v[184:187], v[62:65]
	v_mfma_f32_16x16x32_bf16 v[58:61], v[138:141], v[184:187], v[58:61]
	v_mfma_f32_16x16x32_bf16 v[46:49], v[130:133], v[192:195], v[46:49]
	v_mfma_f32_16x16x32_bf16 v[42:45], v[138:141], v[192:195], v[42:45]
	v_mfma_f32_16x16x32_bf16 v[30:33], v[130:133], v[200:203], v[30:33]
	v_mfma_f32_16x16x32_bf16 v[26:29], v[138:141], v[200:203], v[26:29]
	v_mfma_f32_16x16x32_bf16 v[14:17], v[130:133], v[208:211], v[14:17]
	v_mfma_f32_16x16x32_bf16 v[10:13], v[138:141], v[208:211], v[10:13]
	s_setprio 0
	s_setprio 1
	v_mfma_f32_16x16x32_bf16 v[62:65], v[134:137], v[188:191], v[62:65]
	v_mfma_f32_16x16x32_bf16 v[58:61], v[142:145], v[188:191], v[58:61]
	v_mfma_f32_16x16x32_bf16 v[46:49], v[134:137], v[196:199], v[46:49]
	v_mfma_f32_16x16x32_bf16 v[42:45], v[142:145], v[196:199], v[42:45]
	v_mfma_f32_16x16x32_bf16 v[30:33], v[134:137], v[204:207], v[30:33]
	v_mfma_f32_16x16x32_bf16 v[26:29], v[142:145], v[204:207], v[26:29]
	v_mfma_f32_16x16x32_bf16 v[14:17], v[134:137], v[212:215], v[14:17]
	v_mfma_f32_16x16x32_bf16 v[10:13], v[142:145], v[212:215], v[10:13]
	s_setprio 0
	s_setprio 1
	v_mfma_f32_16x16x32_bf16 v[54:57], v[162:165], v[184:187], v[54:57]
	v_mfma_f32_16x16x32_bf16 v[50:53], v[170:173], v[184:187], v[50:53]
	v_mfma_f32_16x16x32_bf16 v[38:41], v[162:165], v[192:195], v[38:41]
	v_mfma_f32_16x16x32_bf16 v[34:37], v[170:173], v[192:195], v[34:37]
	v_mfma_f32_16x16x32_bf16 v[22:25], v[162:165], v[200:203], v[22:25]
	v_mfma_f32_16x16x32_bf16 v[18:21], v[170:173], v[200:203], v[18:21]
	v_mfma_f32_16x16x32_bf16 v[6:9], v[162:165], v[208:211], v[6:9]
	v_mfma_f32_16x16x32_bf16 v[2:5], v[170:173], v[208:211], v[2:5]
	s_setprio 0
	s_setprio 1
	v_mfma_f32_16x16x32_bf16 v[54:57], v[166:169], v[188:191], v[54:57]
	v_mfma_f32_16x16x32_bf16 v[50:53], v[180:183], v[188:191], v[50:53]
	v_mfma_f32_16x16x32_bf16 v[38:41], v[166:169], v[196:199], v[38:41]
	v_mfma_f32_16x16x32_bf16 v[34:37], v[180:183], v[196:199], v[34:37]
	v_mfma_f32_16x16x32_bf16 v[22:25], v[166:169], v[204:207], v[22:25]
	v_mfma_f32_16x16x32_bf16 v[18:21], v[180:183], v[204:207], v[18:21]
	v_mfma_f32_16x16x32_bf16 v[6:9], v[166:169], v[212:215], v[6:9]
	v_mfma_f32_16x16x32_bf16 v[2:5], v[180:183], v[212:215], v[2:5]
	s_setprio 0
	s_barrier
	s_add_i32 s54, s54, 2
	s_add_u32 s28, s28, 0x100
	s_addc_u32 s29, s29, 0
	s_add_u32 s52, s52, 0x100
	s_addc_u32 s53, s53, 0
	s_cmp_gt_u32 s54, 29
	s_cbranch_scc0 .LBB0_1565
	s_and_b64 vcc, exec, s[16:17]
	s_cbranch_vccz .LBB0_1568
	s_barrier

; #define PG8_STAGE(bufoff, gbase, voff) do { _Pragma("unroll") for (int _i = 0; _i < 2; ++_i) \
;         __builtin_amdgcn_global_load_lds((const unsigned*)((const char*)(gbase) + (voff)[_i]), (PG8_LAS unsigned*)(lds + (bufoff) + ldsw + _i * 8192), 16, 0, 0); } while (0)
; #define PG8_LDA(dst, b, h) do { _Pragma("unroll") for (int m = 0; m < 4; ++m) _Pragma("unroll") for (int k = 0; k < 2; ++k) dst[m][k] = *(const PG8_LAS bf16x8*)(lds + PG8_SA(b, h) + aoff + m * 2048 + k * 1024); } while (0)
; #define PG8_LDB(dst, b, h) do { _Pragma("unroll") for (int n = 0; n < 2; ++n) _Pragma("unroll") for (int k = 0; k < 2; ++k) dst[n][k] = *(const PG8_LAS bf16x8*)(lds + PG8_SB(b, h) + boff + n * 2048 + k * 1024); } while (0)
; #define PG8_MMA(ai, bj, At, Bt) do { __builtin_amdgcn_s_setprio(1); _Pragma("unroll") for (int m = 0; m < 4; ++m) _Pragma("unroll") for (int n = 0; n < 2; ++n) _Pragma("unroll") for (int k = 0; k < 2; ++k) \
;         acc[ai][bj][m][n] = mma_<I8>(Bt[n][k], At[m][k], acc[ai][bj][m][n]); __builtin_amdgcn_s_setprio(0); } while (0)
; #define PG8_WAIT_V(n) asm volatile("s_waitcnt vmcnt(" #n ")" ::: "memory")
; #define PG8_WAIT_L(n) asm volatile("s_waitcnt lgkmcnt(" #n ")" ::: "memory")
; #define PG8_BAR __builtin_amdgcn_s_barrier()
; template <class Epi, class Sched, bool ALIGN_EPI = false, bool SP2 = false, bool I8 = false>
; __device__ __forceinline__ void gemm_phase(PG8_LAS unsigned char* lds, const Gemm g, const Sched& S, const Epi& E) {
;     ...
;             const bool last = (t == nt - 2);
;             const char* a1 = cA + (size_t)(t + 1) * kstep;
;             const char* a2 = last ? nA : cA + (size_t)(t + 2) * kstep; const char* b2 = last ? nB : cB + (size_t)(t + 2) * kstep;
;             const char* a3 = a2 + kstep; const char* b3 = b2 + kstep;
;             if (last && has_next) S.a_ready(nxt);
;             if constexpr (SP2) {
;             PG8_LDB(B0, 0, 0); PG8_LDB(B1, 0, 1); PG8_SCHED; PG8_LDA(At, 0, 0); PG8_STAGE(PG8_SA(1, 1), a1 + hstepA, voffA);
;             PG8_WAIT_V(8); PG8_WAIT_L(0); PG8_BAR; PG8_MMA(0, 0, At, B0); PG8_MMA(0, 1, At, B1); PG8_BAR; PG8_SCHED;
;             PG8_LDA(At, 0, 1); PG8_STAGE(PG8_SB(0, 0), b2, voffB); PG8_STAGE(PG8_SB(0, 1), b2 + hstepB, voffB); PG8_STAGE(PG8_SA(0, 0), a2, voffA);
;             PG8_WAIT_V(8); PG8_WAIT_L(0); PG8_BAR; PG8_MMA(1, 0, At, B0); PG8_MMA(1, 1, At, B1); PG8_BAR; PG8_SCHED;
.LBB0_1721:
	ds_read_b128 v[34:37], v233
	ds_read_b128 v[38:41], v233 offset:1024
	ds_read_b128 v[42:45], v233 offset:2048
	ds_read_b128 v[62:65], v233 offset:3072
	ds_read_b128 v[146:149], v234
	ds_read_b128 v[150:153], v234 offset:1024
	ds_read_b128 v[154:157], v234 offset:2048
	ds_read_b128 v[158:161], v234 offset:3072
	s_add_u32 s34, s8, 0xfff80080
	s_addc_u32 s35, s9, -1
	s_cmp_eq_u32 s55, 28
	s_cselect_b32 s37, s3, s35
	s_cselect_b32 s36, s7, s34
	s_cselect_b32 s35, s25, s54
	s_cselect_b32 s34, s27, s33
	v_lshl_add_u64 v[206:207], s[8:9], 0, v[178:179]
	s_add_i32 m0, s43, 0xc000
	ds_read_b128 v[162:165], v235
	ds_read_b128 v[166:169], v235 offset:1024
	ds_read_b128 v[170:173], v235 offset:2048
	ds_read_b128 v[186:189], v235 offset:3072
	ds_read_b128 v[190:193], v235 offset:4096
	ds_read_b128 v[194:197], v235 offset:5120
	ds_read_b128 v[198:201], v235 offset:6144
	ds_read_b128 v[202:205], v235 offset:7168
	global_load_lds_dwordx4 v[206:207], off
	v_lshl_add_u64 v[206:207], s[8:9], 0, v[180:181]
	s_add_i32 m0, s43, 0xe000
	s_nop 0
	global_load_lds_dwordx4 v[206:207], off
	s_waitcnt vmcnt(8)
	s_waitcnt lgkmcnt(0)
	s_barrier
	s_setprio 1
	s_waitcnt lgkmcnt(0)
	v_mfma_i32_16x16x64_i8 v[142:145], v[34:37], v[162:165], v[142:145]
	v_mfma_i32_16x16x64_i8 v[138:141], v[42:45], v[162:165], v[138:141]
	v_mfma_i32_16x16x64_i8 v[126:129], v[34:37], v[170:173], v[126:129]
	v_mfma_i32_16x16x64_i8 v[122:125], v[42:45], v[170:173], v[122:125]
	v_mfma_i32_16x16x64_i8 v[110:113], v[34:37], v[190:193], v[110:113]
	v_mfma_i32_16x16x64_i8 v[106:109], v[42:45], v[190:193], v[106:109]
	v_mfma_i32_16x16x64_i8 v[94:97], v[34:37], v[198:201], v[94:97]
	v_mfma_i32_16x16x64_i8 v[90:93], v[42:45], v[198:201], v[90:93]
	s_setprio 0
	s_setprio 1
	v_mfma_i32_16x16x64_i8 v[142:145], v[38:41], v[166:169], v[142:145]
	v_mfma_i32_16x16x64_i8 v[138:141], v[62:65], v[166:169], v[138:141]
	v_mfma_i32_16x16x64_i8 v[126:129], v[38:41], v[186:189], v[126:129]
	v_mfma_i32_16x16x64_i8 v[122:125], v[62:65], v[186:189], v[122:125]
	v_mfma_i32_16x16x64_i8 v[110:113], v[38:41], v[194:197], v[110:113]
	v_mfma_i32_16x16x64_i8 v[106:109], v[62:65], v[194:197], v[106:109]
	v_mfma_i32_16x16x64_i8 v[94:97], v[38:41], v[202:205], v[94:97]
	v_mfma_i32_16x16x64_i8 v[90:93], v[62:65], v[202:205], v[90:93]
	s_setprio 0
	s_setprio 1
	v_mfma_i32_16x16x64_i8 v[134:137], v[146:149], v[162:165], v[134:137]
	v_mfma_i32_16x16x64_i8 v[130:133], v[154:157], v[162:165], v[130:133]
	v_mfma_i32_16x16x64_i8 v[118:121], v[146:149], v[170:173], v[118:121]
	v_mfma_i32_16x16x64_i8 v[114:117], v[154:157], v[170:173], v[114:117]
	v_mfma_i32_16x16x64_i8 v[102:105], v[146:149], v[190:193], v[102:105]
	v_mfma_i32_16x16x64_i8 v[98:101], v[154:157], v[190:193], v[98:101]
	v_mfma_i32_16x16x64_i8 v[86:89], v[146:149], v[198:201], v[86:89]
	v_mfma_i32_16x16x64_i8 v[82:85], v[154:157], v[198:201], v[82:85]
	s_setprio 0
	s_setprio 1
	v_mfma_i32_16x16x64_i8 v[134:137], v[150:153], v[166:169], v[134:137]
	v_mfma_i32_16x16x64_i8 v[130:133], v[158:161], v[166:169], v[130:133]
	v_mfma_i32_16x16x64_i8 v[118:121], v[150:153], v[186:189], v[118:121]
	v_mfma_i32_16x16x64_i8 v[114:117], v[158:161], v[186:189], v[114:117]
	v_mfma_i32_16x16x64_i8 v[102:105], v[150:153], v[194:197], v[102:105]
	v_mfma_i32_16x16x64_i8 v[98:101], v[158:161], v[194:197], v[98:101]
	v_mfma_i32_16x16x64_i8 v[86:89], v[150:153], v[202:205], v[86:89]
	v_mfma_i32_16x16x64_i8 v[82:85], v[158:161], v[202:205], v[82:85]
	s_setprio 0
	s_barrier
	s_add_i32 s56, s52, s40
	v_lshl_add_u64 v[206:207], s[34:35], 0, v[174:175]
	s_mov_b32 m0, s56
	ds_read_b128 v[162:165], v235 offset:16384
	ds_read_b128 v[166:169], v235 offset:17408
	ds_read_b128 v[170:173], v235 offset:18432
	ds_read_b128 v[186:189], v235 offset:19456
	ds_read_b128 v[190:193], v235 offset:20480
	ds_read_b128 v[194:197], v235 offset:21504
	ds_read_b128 v[198:201], v235 offset:22528
	ds_read_b128 v[202:205], v235 offset:23552
	global_load_lds_dwordx4 v[206:207], off
	s_add_i32 m0, s56, 0x2000
	s_add_u32 s56, s34, 0x80000
	v_lshl_add_u64 v[208:209], s[34:35], 0, v[176:177]
	s_addc_u32 s57, s35, 0
	s_add_i32 s58, s53, s40
	global_load_lds_dwordx4 v[208:209], off
	v_lshl_add_u64 v[210:211], s[56:57], 0, v[174:175]
	s_mov_b32 m0, s58
	v_lshl_add_u64 v[212:213], s[36:37], 0, v[176:177]
	global_load_lds_dwordx4 v[210:211], off
	v_lshl_add_u64 v[210:211], s[56:57], 0, v[176:177]
	s_add_i32 m0, s58, 0x2000
	s_nop 0
	global_load_lds_dwordx4 v[210:211], off
	v_lshl_add_u64 v[210:211], s[36:37], 0, v[174:175]
	s_mov_b32 m0, s43
	s_nop 0
	global_load_lds_dwordx4 v[210:211], off
	s_mov_b32 m0, s44
	s_nop 0
	global_load_lds_dwordx4 v[212:213], off
	s_waitcnt vmcnt(8)
	s_waitcnt lgkmcnt(0)
	s_barrier
; #define PG8_STAGE(bufoff, gbase, voff) do { _Pragma("unroll") for (int _i = 0; _i < 2; ++_i) \
;         __builtin_amdgcn_global_load_lds((const unsigned*)((const char*)(gbase) + (voff)[_i]), (PG8_LAS unsigned*)(lds + (bufoff) + ldsw + _i * 8192), 16, 0, 0); } while (0)
; #define PG8_LDA(dst, b, h) do { _Pragma("unroll") for (int m = 0; m < 4; ++m) _Pragma("unroll") for (int k = 0; k < 2; ++k) dst[m][k] = *(const PG8_LAS bf16x8*)(lds + PG8_SA(b, h) + aoff + m * 2048 + k * 1024); } while (0)
; #define PG8_LDB(dst, b, h) do { _Pragma("unroll") for (int n = 0; n < 2; ++n) _Pragma("unroll") for (int k = 0; k < 2; ++k) dst[n][k] = *(const PG8_LAS bf16x8*)(lds + PG8_SB(b, h) + boff + n * 2048 + k * 1024); } while (0)
; #define PG8_MMA(ai, bj, At, Bt) do { __builtin_amdgcn_s_setprio(1); _Pragma("unroll") for (int m = 0; m < 4; ++m) _Pragma("unroll") for (int n = 0; n < 2; ++n) _Pragma("unroll") for (int k = 0; k < 2; ++k) \
;         acc[ai][bj][m][n] = mma_<I8>(Bt[n][k], At[m][k], acc[ai][bj][m][n]); __builtin_amdgcn_s_setprio(0); } while (0)
; #define PG8_WAIT_V(n) asm volatile("s_waitcnt vmcnt(" #n ")" ::: "memory")
; #define PG8_WAIT_L(n) asm volatile("s_waitcnt lgkmcnt(" #n ")" ::: "memory")
; #define PG8_BAR __builtin_amdgcn_s_barrier()
; #define PG8_SCHED __builtin_amdgcn_sched_barrier(0)
; template <class Epi, class Sched, bool ALIGN_EPI = false, bool SP2 = false, bool I8 = false>
; __device__ __forceinline__ void gemm_phase(PG8_LAS unsigned char* lds, const Gemm g, const Sched& S, const Epi& E) {
;     ...
;             PG8_WAIT_V(8); PG8_WAIT_L(0); PG8_BAR; PG8_MMA(1, 0, At, B0); PG8_MMA(1, 1, At, B1); PG8_BAR; PG8_SCHED;
;             PG8_LDB(B0, 1, 0); PG8_LDB(B1, 1, 1); PG8_SCHED; PG8_LDA(At, 1, 0); PG8_STAGE(PG8_SA(0, 1), a2 + hstepA, voffA);
;             PG8_WAIT_V(8); PG8_WAIT_L(0); PG8_BAR; PG8_MMA(0, 0, At, B0); PG8_MMA(0, 1, At, B1); PG8_BAR; PG8_SCHED;
	s_setprio 1
	s_waitcnt lgkmcnt(0)
	v_mfma_i32_16x16x64_i8 v[78:81], v[34:37], v[162:165], v[78:81]
	v_mfma_i32_16x16x64_i8 v[74:77], v[42:45], v[162:165], v[74:77]
	v_mfma_i32_16x16x64_i8 v[58:61], v[34:37], v[170:173], v[58:61]
	v_mfma_i32_16x16x64_i8 v[54:57], v[42:45], v[170:173], v[54:57]
	v_mfma_i32_16x16x64_i8 v[30:33], v[34:37], v[190:193], v[30:33]
	v_mfma_i32_16x16x64_i8 v[26:29], v[42:45], v[190:193], v[26:29]
	v_mfma_i32_16x16x64_i8 v[14:17], v[34:37], v[198:201], v[14:17]
	v_mfma_i32_16x16x64_i8 v[10:13], v[42:45], v[198:201], v[10:13]
	s_setprio 0
	s_setprio 1
	v_mfma_i32_16x16x64_i8 v[78:81], v[38:41], v[166:169], v[78:81]
	v_mfma_i32_16x16x64_i8 v[74:77], v[62:65], v[166:169], v[74:77]
	v_mfma_i32_16x16x64_i8 v[58:61], v[38:41], v[186:189], v[58:61]
	v_mfma_i32_16x16x64_i8 v[54:57], v[62:65], v[186:189], v[54:57]
	v_mfma_i32_16x16x64_i8 v[30:33], v[38:41], v[194:197], v[30:33]
	v_mfma_i32_16x16x64_i8 v[26:29], v[62:65], v[194:197], v[26:29]
	v_mfma_i32_16x16x64_i8 v[14:17], v[38:41], v[202:205], v[14:17]
	v_mfma_i32_16x16x64_i8 v[10:13], v[62:65], v[202:205], v[10:13]
	s_setprio 0
	s_setprio 1
	v_mfma_i32_16x16x64_i8 v[46:49], v[154:157], v[170:173], v[46:49]
	v_mfma_i32_16x16x64_i8 v[22:25], v[146:149], v[190:193], v[22:25]
	v_mfma_i32_16x16x64_i8 v[18:21], v[154:157], v[190:193], v[18:21]
	v_mfma_i32_16x16x64_i8 v[6:9], v[146:149], v[198:201], v[6:9]
	v_mfma_i32_16x16x64_i8 v[2:5], v[154:157], v[198:201], v[2:5]
	v_mfma_i32_16x16x64_i8 v[34:37], v[146:149], v[162:165], v[70:73]
	v_mfma_i32_16x16x64_i8 v[38:41], v[154:157], v[162:165], v[66:69]
	v_mfma_i32_16x16x64_i8 v[42:45], v[146:149], v[170:173], v[50:53]
	s_setprio 0
	s_setprio 1
	v_mfma_i32_16x16x64_i8 v[46:49], v[158:161], v[186:189], v[46:49]
	v_mfma_i32_16x16x64_i8 v[22:25], v[150:153], v[194:197], v[22:25]
	v_mfma_i32_16x16x64_i8 v[18:21], v[158:161], v[194:197], v[18:21]
	v_mfma_i32_16x16x64_i8 v[6:9], v[150:153], v[202:205], v[6:9]
	v_mfma_i32_16x16x64_i8 v[2:5], v[158:161], v[202:205], v[2:5]
	v_mfma_i32_16x16x64_i8 v[34:37], v[150:153], v[166:169], v[34:37]
	v_mfma_i32_16x16x64_i8 v[38:41], v[158:161], v[166:169], v[38:41]
	v_mfma_i32_16x16x64_i8 v[42:45], v[150:153], v[186:189], v[42:45]
	s_setprio 0
	s_barrier
	s_add_i32 s56, 0, 0x18000
	s_add_i32 s57, 0, 0x1c000
	v_add_u32_e32 v70, s56, v1
	v_add_u32_e32 v158, s57, v1
	ds_read_b128 v[50:53], v70
	ds_read_b128 v[62:65], v70 offset:1024
	ds_read_b128 v[66:69], v70 offset:2048
	ds_read_b128 v[70:73], v70 offset:3072
	ds_read_b128 v[146:149], v158
	ds_read_b128 v[150:153], v158 offset:1024
	ds_read_b128 v[154:157], v158 offset:2048
	ds_read_b128 v[158:161], v158 offset:3072
	s_add_u32 s36, s36, 0x80000
	s_addc_u32 s37, s37, 0
	s_mov_b32 m0, s45
	v_lshl_add_u64 v[214:215], s[36:37], 0, v[174:175]
	ds_read_b128 v[162:165], v235 offset:32768
	ds_read_b128 v[166:169], v235 offset:33792
	ds_read_b128 v[170:173], v235 offset:34816
	ds_read_b128 v[186:189], v235 offset:35840
	ds_read_b128 v[190:193], v235 offset:36864
	ds_read_b128 v[194:197], v235 offset:37888
	ds_read_b128 v[198:201], v235 offset:38912
	ds_read_b128 v[202:205], v235 offset:39936
	global_load_lds_dwordx4 v[214:215], off
	v_lshl_add_u64 v[214:215], s[36:37], 0, v[176:177]
	s_mov_b32 m0, s46
	s_nop 0
	global_load_lds_dwordx4 v[214:215], off
	s_waitcnt vmcnt(8)
	s_waitcnt lgkmcnt(0)
	s_barrier
	s_setprio 1
	s_waitcnt lgkmcnt(0)
	v_mfma_i32_16x16x64_i8 v[142:145], v[50:53], v[162:165], v[142:145]
	v_mfma_i32_16x16x64_i8 v[138:141], v[66:69], v[162:165], v[138:141]
	v_mfma_i32_16x16x64_i8 v[126:129], v[50:53], v[170:173], v[126:129]
	v_mfma_i32_16x16x64_i8 v[122:125], v[66:69], v[170:173], v[122:125]
	v_mfma_i32_16x16x64_i8 v[110:113], v[50:53], v[190:193], v[110:113]
	v_mfma_i32_16x16x64_i8 v[106:109], v[66:69], v[190:193], v[106:109]
	v_mfma_i32_16x16x64_i8 v[94:97], v[50:53], v[198:201], v[94:97]
	v_mfma_i32_16x16x64_i8 v[90:93], v[66:69], v[198:201], v[90:93]
	s_setprio 0
	s_setprio 1
	v_mfma_i32_16x16x64_i8 v[142:145], v[62:65], v[166:169], v[142:145]
	v_mfma_i32_16x16x64_i8 v[138:141], v[70:73], v[166:169], v[138:141]
	v_mfma_i32_16x16x64_i8 v[126:129], v[62:65], v[186:189], v[126:129]
	v_mfma_i32_16x16x64_i8 v[122:125], v[70:73], v[186:189], v[122:125]
	v_mfma_i32_16x16x64_i8 v[110:113], v[62:65], v[194:197], v[110:113]
	v_mfma_i32_16x16x64_i8 v[106:109], v[70:73], v[194:197], v[106:109]
	v_mfma_i32_16x16x64_i8 v[94:97], v[62:65], v[202:205], v[94:97]
	v_mfma_i32_16x16x64_i8 v[90:93], v[70:73], v[202:205], v[90:93]
	s_setprio 0
	s_setprio 1
	v_mfma_i32_16x16x64_i8 v[134:137], v[146:149], v[162:165], v[134:137]
	v_mfma_i32_16x16x64_i8 v[130:133], v[154:157], v[162:165], v[130:133]
	v_mfma_i32_16x16x64_i8 v[118:121], v[146:149], v[170:173], v[118:121]
	v_mfma_i32_16x16x64_i8 v[114:117], v[154:157], v[170:173], v[114:117]
	v_mfma_i32_16x16x64_i8 v[102:105], v[146:149], v[190:193], v[102:105]
	v_mfma_i32_16x16x64_i8 v[98:101], v[154:157], v[190:193], v[98:101]
	v_mfma_i32_16x16x64_i8 v[86:89], v[146:149], v[198:201], v[86:89]
	v_mfma_i32_16x16x64_i8 v[82:85], v[154:157], v[198:201], v[82:85]
	s_setprio 0
	s_setprio 1
	v_mfma_i32_16x16x64_i8 v[134:137], v[150:153], v[166:169], v[134:137]
	v_mfma_i32_16x16x64_i8 v[130:133], v[158:161], v[166:169], v[130:133]
	v_mfma_i32_16x16x64_i8 v[118:121], v[150:153], v[186:189], v[118:121]
	v_mfma_i32_16x16x64_i8 v[114:117], v[158:161], v[186:189], v[114:117]
	v_mfma_i32_16x16x64_i8 v[102:105], v[150:153], v[194:197], v[102:105]
	v_mfma_i32_16x16x64_i8 v[98:101], v[158:161], v[194:197], v[98:101]
	v_mfma_i32_16x16x64_i8 v[86:89], v[150:153], v[202:205], v[86:89]
	v_mfma_i32_16x16x64_i8 v[82:85], v[158:161], v[202:205], v[82:85]
	s_setprio 0
	s_barrier
; #define PG8_STAGE(bufoff, gbase, voff) do { _Pragma("unroll") for (int _i = 0; _i < 2; ++_i) \
;         __builtin_amdgcn_global_load_lds((const unsigned*)((const char*)(gbase) + (voff)[_i]), (PG8_LAS unsigned*)(lds + (bufoff) + ldsw + _i * 8192), 16, 0, 0); } while (0)
; #define PG8_LDA(dst, b, h) do { _Pragma("unroll") for (int m = 0; m < 4; ++m) _Pragma("unroll") for (int k = 0; k < 2; ++k) dst[m][k] = *(const PG8_LAS bf16x8*)(lds + PG8_SA(b, h) + aoff + m * 2048 + k * 1024); } while (0)
; #define PG8_MMA(ai, bj, At, Bt) do { __builtin_amdgcn_s_setprio(1); _Pragma("unroll") for (int m = 0; m < 4; ++m) _Pragma("unroll") for (int n = 0; n < 2; ++n) _Pragma("unroll") for (int k = 0; k < 2; ++k) \
;         acc[ai][bj][m][n] = mma_<I8>(Bt[n][k], At[m][k], acc[ai][bj][m][n]); __builtin_amdgcn_s_setprio(0); } while (0)
; #define PG8_WAIT_V(n) asm volatile("s_waitcnt vmcnt(" #n ")" ::: "memory")
; #define PG8_WAIT_L(n) asm volatile("s_waitcnt lgkmcnt(" #n ")" ::: "memory")
; #define PG8_BAR __builtin_amdgcn_s_barrier()
; #define PG8_SCHED __builtin_amdgcn_sched_barrier(0)
; template <class Epi, class Sched, bool ALIGN_EPI = false, bool SP2 = false, bool I8 = false>
; __device__ __forceinline__ void gemm_phase(PG8_LAS unsigned char* lds, const Gemm g, const Sched& S, const Epi& E) {
;     ...
;             PG8_LDA(At, 1, 1); PG8_STAGE(PG8_SB(1, 0), b3, voffB); PG8_STAGE(PG8_SB(1, 1), b3 + hstepB, voffB); PG8_STAGE(PG8_SA(1, 0), a3, voffA);
;             PG8_WAIT_V(8); PG8_WAIT_L(0); PG8_BAR; PG8_MMA(1, 0, At, B0); PG8_MMA(1, 1, At, B1); PG8_BAR; PG8_SCHED;
;     ...
;         if constexpr (ALIGN_EPI) { if (wr == 0) PG8_BAR; }
	s_add_i32 s36, s56, s40
	v_lshl_add_u64 v[206:207], v[206:207], 0, s[18:19]
	s_mov_b32 m0, s36
	ds_read_b128 v[162:165], v235 offset:49152
	ds_read_b128 v[166:169], v235 offset:50176
	ds_read_b128 v[170:173], v235 offset:51200
	ds_read_b128 v[186:189], v235 offset:52224
	ds_read_b128 v[190:193], v235 offset:53248
	ds_read_b128 v[194:197], v235 offset:54272
	ds_read_b128 v[198:201], v235 offset:55296
	ds_read_b128 v[202:205], v235 offset:56320
	global_load_lds_dwordx4 v[206:207], off
	s_add_i32 m0, s36, 0x2000
	s_add_u32 s34, s34, 0x80080
	v_lshl_add_u64 v[206:207], v[208:209], 0, s[18:19]
	s_addc_u32 s35, s35, 0
	s_add_i32 s36, s57, s40
	global_load_lds_dwordx4 v[206:207], off
	v_lshl_add_u64 v[206:207], s[34:35], 0, v[174:175]
	s_mov_b32 m0, s36
	s_nop 0
	global_load_lds_dwordx4 v[206:207], off
	v_lshl_add_u64 v[206:207], s[34:35], 0, v[176:177]
	s_add_i32 m0, s36, 0x2000
	s_nop 0
	global_load_lds_dwordx4 v[206:207], off
	v_lshl_add_u64 v[206:207], v[210:211], 0, s[18:19]
	s_mov_b32 m0, s48
	s_nop 0
	global_load_lds_dwordx4 v[206:207], off
	v_lshl_add_u64 v[206:207], v[212:213], 0, s[18:19]
	s_mov_b32 m0, s49
	s_nop 0
	global_load_lds_dwordx4 v[206:207], off
	s_waitcnt vmcnt(8)
	s_waitcnt lgkmcnt(0)
	s_barrier
	s_setprio 1
	s_waitcnt lgkmcnt(0)
	v_mfma_i32_16x16x64_i8 v[78:81], v[50:53], v[162:165], v[78:81]
	v_mfma_i32_16x16x64_i8 v[74:77], v[66:69], v[162:165], v[74:77]
	v_mfma_i32_16x16x64_i8 v[58:61], v[50:53], v[170:173], v[58:61]
	v_mfma_i32_16x16x64_i8 v[54:57], v[66:69], v[170:173], v[54:57]
	v_mfma_i32_16x16x64_i8 v[30:33], v[50:53], v[190:193], v[30:33]
	v_mfma_i32_16x16x64_i8 v[26:29], v[66:69], v[190:193], v[26:29]
	v_mfma_i32_16x16x64_i8 v[14:17], v[50:53], v[198:201], v[14:17]
	v_mfma_i32_16x16x64_i8 v[10:13], v[66:69], v[198:201], v[10:13]
	s_setprio 0
	s_setprio 1
	v_mfma_i32_16x16x64_i8 v[78:81], v[62:65], v[166:169], v[78:81]
	v_mfma_i32_16x16x64_i8 v[74:77], v[70:73], v[166:169], v[74:77]
	v_mfma_i32_16x16x64_i8 v[58:61], v[62:65], v[186:189], v[58:61]
	v_mfma_i32_16x16x64_i8 v[54:57], v[70:73], v[186:189], v[54:57]
	v_mfma_i32_16x16x64_i8 v[30:33], v[62:65], v[194:197], v[30:33]
	v_mfma_i32_16x16x64_i8 v[26:29], v[70:73], v[194:197], v[26:29]
	v_mfma_i32_16x16x64_i8 v[14:17], v[62:65], v[202:205], v[14:17]
	v_mfma_i32_16x16x64_i8 v[10:13], v[70:73], v[202:205], v[10:13]
	s_setprio 0
	s_setprio 1
	v_mfma_i32_16x16x64_i8 v[34:37], v[146:149], v[162:165], v[34:37]
	v_mfma_i32_16x16x64_i8 v[70:73], v[150:153], v[166:169], v[34:37]
	v_mfma_i32_16x16x64_i8 v[34:37], v[154:157], v[162:165], v[38:41]
	v_mfma_i32_16x16x64_i8 v[66:69], v[158:161], v[166:169], v[34:37]
	v_mfma_i32_16x16x64_i8 v[34:37], v[146:149], v[170:173], v[42:45]
	v_mfma_i32_16x16x64_i8 v[50:53], v[150:153], v[186:189], v[34:37]
	v_mfma_i32_16x16x64_i8 v[34:37], v[154:157], v[170:173], v[46:49]
	v_mfma_i32_16x16x64_i8 v[22:25], v[146:149], v[190:193], v[22:25]
	s_setprio 0
	s_setprio 1
	v_mfma_i32_16x16x64_i8 v[18:21], v[154:157], v[190:193], v[18:21]
	v_mfma_i32_16x16x64_i8 v[6:9], v[146:149], v[198:201], v[6:9]
	v_mfma_i32_16x16x64_i8 v[2:5], v[154:157], v[198:201], v[2:5]
	v_mfma_i32_16x16x64_i8 v[46:49], v[158:161], v[186:189], v[34:37]
	v_mfma_i32_16x16x64_i8 v[22:25], v[150:153], v[194:197], v[22:25]
	v_mfma_i32_16x16x64_i8 v[18:21], v[158:161], v[194:197], v[18:21]
	v_mfma_i32_16x16x64_i8 v[6:9], v[150:153], v[202:205], v[6:9]
	v_mfma_i32_16x16x64_i8 v[2:5], v[158:161], v[202:205], v[2:5]
	s_setprio 0
	s_barrier
	s_add_i32 s55, s55, 2
	s_add_u32 s8, s8, 0x100
	s_addc_u32 s9, s9, 0
	s_add_u32 s33, s33, 0x100
	s_addc_u32 s54, s54, 0
	s_cmp_gt_u32 s55, 29
	s_cbranch_scc0 .LBB0_1721
	s_and_b64 vcc, exec, s[20:21]
	s_cbranch_vccz .LBB0_1724
	s_barrier

; #define PG8_STAGE(bufoff, gbase, voff) do { _Pragma("unroll") for (int _i = 0; _i < 2; ++_i) \
;         __builtin_amdgcn_global_load_lds((const unsigned*)((const char*)(gbase) + (voff)[_i]), (PG8_LAS unsigned*)(lds + (bufoff) + ldsw + _i * 8192), 16, 0, 0); } while (0)
; #define PG8_LDA(dst, b, h) do { _Pragma("unroll") for (int m = 0; m < 4; ++m) _Pragma("unroll") for (int k = 0; k < 2; ++k) dst[m][k] = *(const PG8_LAS bf16x8*)(lds + PG8_SA(b, h) + aoff + m * 2048 + k * 1024); } while (0)
; #define PG8_LDB(dst, b, h) do { _Pragma("unroll") for (int n = 0; n < 2; ++n) _Pragma("unroll") for (int k = 0; k < 2; ++k) dst[n][k] = *(const PG8_LAS bf16x8*)(lds + PG8_SB(b, h) + boff + n * 2048 + k * 1024); } while (0)
; #define PG8_MMA(ai, bj, At, Bt) do { __builtin_amdgcn_s_setprio(1); _Pragma("unroll") for (int m = 0; m < 4; ++m) _Pragma("unroll") for (int n = 0; n < 2; ++n) _Pragma("unroll") for (int k = 0; k < 2; ++k) \
;         acc[ai][bj][m][n] = mma_<I8>(Bt[n][k], At[m][k], acc[ai][bj][m][n]); __builtin_amdgcn_s_setprio(0); } while (0)
; #define PG8_WAIT_V(n) asm volatile("s_waitcnt vmcnt(" #n ")" ::: "memory")
; #define PG8_WAIT_L(n) asm volatile("s_waitcnt lgkmcnt(" #n ")" ::: "memory")
; #define PG8_BAR __builtin_amdgcn_s_barrier()
; template <class Epi, class Sched, bool ALIGN_EPI = false, bool SP2 = false, bool I8 = false>
; __device__ __forceinline__ void gemm_phase(PG8_LAS unsigned char* lds, const Gemm g, const Sched& S, const Epi& E) {
;     ...
;             const bool last = (t == nt - 2);
;             const char* a1 = cA + (size_t)(t + 1) * kstep;
;             const char* a2 = last ? nA : cA + (size_t)(t + 2) * kstep; const char* b2 = last ? nB : cB + (size_t)(t + 2) * kstep;
;             const char* a3 = a2 + kstep; const char* b3 = b2 + kstep;
;             if (last && has_next) S.a_ready(nxt);
;             if constexpr (SP2) {
;             PG8_LDB(B0, 0, 0); PG8_LDB(B1, 0, 1); PG8_SCHED; PG8_LDA(At, 0, 0); PG8_STAGE(PG8_SA(1, 1), a1 + hstepA, voffA);
;             PG8_WAIT_V(8); PG8_WAIT_L(0); PG8_BAR; PG8_MMA(0, 0, At, B0); PG8_MMA(0, 1, At, B1); PG8_BAR; PG8_SCHED;
;             PG8_LDA(At, 0, 1); PG8_STAGE(PG8_SB(0, 0), b2, voffB); PG8_STAGE(PG8_SB(0, 1), b2 + hstepB, voffB); PG8_STAGE(PG8_SA(0, 0), a2, voffA);
;             PG8_WAIT_V(8); PG8_WAIT_L(0); PG8_BAR; PG8_MMA(1, 0, At, B0); PG8_MMA(1, 1, At, B1); PG8_BAR; PG8_SCHED;
.LBB0_2014:
	ds_read_b128 v[118:121], v163
	ds_read_b128 v[126:129], v163 offset:1024
	ds_read_b128 v[130:133], v163 offset:2048
	ds_read_b128 v[134:137], v163 offset:3072
	ds_read_b128 v[168:171], v167
	ds_read_b128 v[176:179], v167 offset:1024
	ds_read_b128 v[180:183], v167 offset:2048
	ds_read_b128 v[184:187], v167 offset:3072
	s_add_u32 s38, s36, 0xfff80080
	s_addc_u32 s39, s37, -1
	s_cmp_eq_u32 s65, 28
	s_cselect_b32 s41, s27, s39
	s_cselect_b32 s40, s61, s38
	s_cselect_b32 s39, s25, s64
	s_cselect_b32 s38, s62, s63
	v_lshl_add_u64 v[164:165], s[36:37], 0, v[154:155]
	s_add_i32 m0, s35, 0xc000
	ds_read_b128 v[188:191], v173
	ds_read_b128 v[192:195], v173 offset:1024
	ds_read_b128 v[196:199], v173 offset:2048
	ds_read_b128 v[200:203], v173 offset:3072
	ds_read_b128 v[204:207], v173 offset:4096
	ds_read_b128 v[208:211], v173 offset:5120
	ds_read_b128 v[212:215], v173 offset:6144
	ds_read_b128 v[216:219], v173 offset:7168
	global_load_lds_dwordx4 v[164:165], off
	v_lshl_add_u64 v[164:165], s[36:37], 0, v[156:157]
	s_add_i32 m0, s35, 0xe000
	s_nop 0
	global_load_lds_dwordx4 v[164:165], off
	s_waitcnt vmcnt(8)
	s_waitcnt lgkmcnt(0)
	s_barrier
	s_setprio 1
	s_waitcnt lgkmcnt(0)
	v_mfma_i32_16x16x64_i8 v[142:145], v[118:121], v[188:191], v[142:145]
	v_mfma_i32_16x16x64_i8 v[138:141], v[130:133], v[188:191], v[138:141]
	v_mfma_i32_16x16x64_i8 v[110:113], v[118:121], v[196:199], v[110:113]
	v_mfma_i32_16x16x64_i8 v[106:109], v[130:133], v[196:199], v[106:109]
	v_mfma_i32_16x16x64_i8 v[94:97], v[118:121], v[204:207], v[94:97]
	v_mfma_i32_16x16x64_i8 v[90:93], v[130:133], v[204:207], v[90:93]
	v_mfma_i32_16x16x64_i8 v[78:81], v[118:121], v[212:215], v[78:81]
	v_mfma_i32_16x16x64_i8 v[74:77], v[130:133], v[212:215], v[74:77]
	s_setprio 0
	s_setprio 1
	v_mfma_i32_16x16x64_i8 v[142:145], v[126:129], v[192:195], v[142:145]
	v_mfma_i32_16x16x64_i8 v[138:141], v[134:137], v[192:195], v[138:141]
	v_mfma_i32_16x16x64_i8 v[110:113], v[126:129], v[200:203], v[110:113]
	v_mfma_i32_16x16x64_i8 v[106:109], v[134:137], v[200:203], v[106:109]
	v_mfma_i32_16x16x64_i8 v[94:97], v[126:129], v[208:211], v[94:97]
	v_mfma_i32_16x16x64_i8 v[90:93], v[134:137], v[208:211], v[90:93]
	v_mfma_i32_16x16x64_i8 v[78:81], v[126:129], v[216:219], v[78:81]
	v_mfma_i32_16x16x64_i8 v[74:77], v[134:137], v[216:219], v[74:77]
	s_setprio 0
	s_setprio 1
	v_mfma_i32_16x16x64_i8 v[122:125], v[168:171], v[188:191], v[122:125]
	v_mfma_i32_16x16x64_i8 v[114:117], v[180:183], v[188:191], v[114:117]
	v_mfma_i32_16x16x64_i8 v[102:105], v[168:171], v[196:199], v[102:105]
	v_mfma_i32_16x16x64_i8 v[98:101], v[180:183], v[196:199], v[98:101]
	v_mfma_i32_16x16x64_i8 v[86:89], v[168:171], v[204:207], v[86:89]
	v_mfma_i32_16x16x64_i8 v[82:85], v[180:183], v[204:207], v[82:85]
	v_mfma_i32_16x16x64_i8 v[70:73], v[168:171], v[212:215], v[70:73]
	v_mfma_i32_16x16x64_i8 v[66:69], v[180:183], v[212:215], v[66:69]
	s_setprio 0
	s_setprio 1
	v_mfma_i32_16x16x64_i8 v[122:125], v[176:179], v[192:195], v[122:125]
	v_mfma_i32_16x16x64_i8 v[114:117], v[184:187], v[192:195], v[114:117]
	v_mfma_i32_16x16x64_i8 v[102:105], v[176:179], v[200:203], v[102:105]
	v_mfma_i32_16x16x64_i8 v[98:101], v[184:187], v[200:203], v[98:101]
	v_mfma_i32_16x16x64_i8 v[86:89], v[176:179], v[208:211], v[86:89]
	v_mfma_i32_16x16x64_i8 v[82:85], v[184:187], v[208:211], v[82:85]
	v_mfma_i32_16x16x64_i8 v[70:73], v[176:179], v[216:219], v[70:73]
	v_mfma_i32_16x16x64_i8 v[66:69], v[184:187], v[216:219], v[66:69]
	s_setprio 0
	s_barrier
	s_add_i32 s66, s54, s46
	v_lshl_add_u64 v[164:165], s[38:39], 0, v[148:149]
	s_mov_b32 m0, s66
	ds_read_b128 v[188:191], v173 offset:16384
	ds_read_b128 v[192:195], v173 offset:17408
	ds_read_b128 v[196:199], v173 offset:18432
	ds_read_b128 v[200:203], v173 offset:19456
	ds_read_b128 v[204:207], v173 offset:20480
	ds_read_b128 v[208:211], v173 offset:21504
	ds_read_b128 v[212:215], v173 offset:22528
	ds_read_b128 v[216:219], v173 offset:23552
	global_load_lds_dwordx4 v[164:165], off
	s_add_i32 m0, s66, 0x2000
	s_add_u32 s66, s38, 0x80000
	v_lshl_add_u64 v[220:221], s[38:39], 0, v[152:153]
	s_addc_u32 s67, s39, 0
	s_add_i32 s68, s55, s46
	global_load_lds_dwordx4 v[220:221], off
	v_lshl_add_u64 v[222:223], s[66:67], 0, v[148:149]
	s_mov_b32 m0, s68
	v_lshl_add_u64 v[224:225], s[40:41], 0, v[150:151]
	global_load_lds_dwordx4 v[222:223], off
	v_lshl_add_u64 v[222:223], s[66:67], 0, v[152:153]
	s_add_i32 m0, s68, 0x2000
	s_nop 0
	global_load_lds_dwordx4 v[222:223], off
	v_lshl_add_u64 v[222:223], s[40:41], 0, v[146:147]
	s_mov_b32 m0, s35
	s_nop 0
	global_load_lds_dwordx4 v[222:223], off
	s_mov_b32 m0, s47
	s_nop 0
	global_load_lds_dwordx4 v[224:225], off
	s_waitcnt vmcnt(8)
	s_waitcnt lgkmcnt(0)
	s_barrier
; #define PG8_STAGE(bufoff, gbase, voff) do { _Pragma("unroll") for (int _i = 0; _i < 2; ++_i) \
;         __builtin_amdgcn_global_load_lds((const unsigned*)((const char*)(gbase) + (voff)[_i]), (PG8_LAS unsigned*)(lds + (bufoff) + ldsw + _i * 8192), 16, 0, 0); } while (0)
; #define PG8_LDA(dst, b, h) do { _Pragma("unroll") for (int m = 0; m < 4; ++m) _Pragma("unroll") for (int k = 0; k < 2; ++k) dst[m][k] = *(const PG8_LAS bf16x8*)(lds + PG8_SA(b, h) + aoff + m * 2048 + k * 1024); } while (0)
; #define PG8_LDB(dst, b, h) do { _Pragma("unroll") for (int n = 0; n < 2; ++n) _Pragma("unroll") for (int k = 0; k < 2; ++k) dst[n][k] = *(const PG8_LAS bf16x8*)(lds + PG8_SB(b, h) + boff + n * 2048 + k * 1024); } while (0)
; #define PG8_MMA(ai, bj, At, Bt) do { __builtin_amdgcn_s_setprio(1); _Pragma("unroll") for (int m = 0; m < 4; ++m) _Pragma("unroll") for (int n = 0; n < 2; ++n) _Pragma("unroll") for (int k = 0; k < 2; ++k) \
;         acc[ai][bj][m][n] = mma_<I8>(Bt[n][k], At[m][k], acc[ai][bj][m][n]); __builtin_amdgcn_s_setprio(0); } while (0)
; #define PG8_WAIT_V(n) asm volatile("s_waitcnt vmcnt(" #n ")" ::: "memory")
; #define PG8_WAIT_L(n) asm volatile("s_waitcnt lgkmcnt(" #n ")" ::: "memory")
; #define PG8_BAR __builtin_amdgcn_s_barrier()
; #define PG8_SCHED __builtin_amdgcn_sched_barrier(0)
; template <class Epi, class Sched, bool ALIGN_EPI = false, bool SP2 = false, bool I8 = false>
; __device__ __forceinline__ void gemm_phase(PG8_LAS unsigned char* lds, const Gemm g, const Sched& S, const Epi& E) {
;     ...
;             PG8_WAIT_V(8); PG8_WAIT_L(0); PG8_BAR; PG8_MMA(1, 0, At, B0); PG8_MMA(1, 1, At, B1); PG8_BAR; PG8_SCHED;
;             PG8_LDB(B0, 1, 0); PG8_LDB(B1, 1, 1); PG8_SCHED; PG8_LDA(At, 1, 0); PG8_STAGE(PG8_SA(0, 1), a2 + hstepA, voffA);
;             PG8_WAIT_V(8); PG8_WAIT_L(0); PG8_BAR; PG8_MMA(0, 0, At, B0); PG8_MMA(0, 1, At, B1); PG8_BAR; PG8_SCHED;
	s_setprio 1
	s_waitcnt lgkmcnt(0)
	v_mfma_i32_16x16x64_i8 v[62:65], v[118:121], v[188:191], v[62:65]
	v_mfma_i32_16x16x64_i8 v[58:61], v[130:133], v[188:191], v[58:61]
	v_mfma_i32_16x16x64_i8 v[46:49], v[118:121], v[196:199], v[46:49]
	v_mfma_i32_16x16x64_i8 v[42:45], v[130:133], v[196:199], v[42:45]
	v_mfma_i32_16x16x64_i8 v[30:33], v[118:121], v[204:207], v[30:33]
	v_mfma_i32_16x16x64_i8 v[26:29], v[130:133], v[204:207], v[26:29]
	v_mfma_i32_16x16x64_i8 v[14:17], v[118:121], v[212:215], v[14:17]
	v_mfma_i32_16x16x64_i8 v[10:13], v[130:133], v[212:215], v[10:13]
	s_setprio 0
	s_setprio 1
	v_mfma_i32_16x16x64_i8 v[62:65], v[126:129], v[192:195], v[62:65]
	v_mfma_i32_16x16x64_i8 v[58:61], v[134:137], v[192:195], v[58:61]
	v_mfma_i32_16x16x64_i8 v[46:49], v[126:129], v[200:203], v[46:49]
	v_mfma_i32_16x16x64_i8 v[42:45], v[134:137], v[200:203], v[42:45]
	v_mfma_i32_16x16x64_i8 v[30:33], v[126:129], v[208:211], v[30:33]
	v_mfma_i32_16x16x64_i8 v[26:29], v[134:137], v[208:211], v[26:29]
	v_mfma_i32_16x16x64_i8 v[14:17], v[126:129], v[216:219], v[14:17]
	v_mfma_i32_16x16x64_i8 v[10:13], v[134:137], v[216:219], v[10:13]
	s_setprio 0
	s_setprio 1
	v_mfma_i32_16x16x64_i8 v[54:57], v[168:171], v[188:191], v[54:57]
	v_mfma_i32_16x16x64_i8 v[50:53], v[180:183], v[188:191], v[50:53]
	v_mfma_i32_16x16x64_i8 v[38:41], v[168:171], v[196:199], v[38:41]
	v_mfma_i32_16x16x64_i8 v[34:37], v[180:183], v[196:199], v[34:37]
	v_mfma_i32_16x16x64_i8 v[22:25], v[168:171], v[204:207], v[22:25]
	v_mfma_i32_16x16x64_i8 v[18:21], v[180:183], v[204:207], v[18:21]
	v_mfma_i32_16x16x64_i8 v[6:9], v[168:171], v[212:215], v[6:9]
	v_mfma_i32_16x16x64_i8 v[2:5], v[180:183], v[212:215], v[2:5]
	s_setprio 0
	s_setprio 1
	v_mfma_i32_16x16x64_i8 v[54:57], v[176:179], v[192:195], v[54:57]
	v_mfma_i32_16x16x64_i8 v[50:53], v[184:187], v[192:195], v[50:53]
	v_mfma_i32_16x16x64_i8 v[38:41], v[176:179], v[200:203], v[38:41]
	v_mfma_i32_16x16x64_i8 v[34:37], v[184:187], v[200:203], v[34:37]
	v_mfma_i32_16x16x64_i8 v[22:25], v[176:179], v[208:211], v[22:25]
	v_mfma_i32_16x16x64_i8 v[18:21], v[184:187], v[208:211], v[18:21]
	v_mfma_i32_16x16x64_i8 v[6:9], v[176:179], v[216:219], v[6:9]
	v_mfma_i32_16x16x64_i8 v[2:5], v[184:187], v[216:219], v[2:5]
	s_setprio 0
	s_barrier
	s_add_i32 s66, 0, 0x18000
	s_add_i32 s67, 0, 0x1c000
	v_add_u32_e32 v134, s66, v1
	v_add_u32_e32 v162, s67, v1
	ds_read_b128 v[118:121], v134
	ds_read_b128 v[126:129], v134 offset:1024
	ds_read_b128 v[130:133], v134 offset:2048
	ds_read_b128 v[134:137], v134 offset:3072
	ds_read_b128 v[168:171], v162
	ds_read_b128 v[176:179], v162 offset:1024
	ds_read_b128 v[180:183], v162 offset:2048
	ds_read_b128 v[184:187], v162 offset:3072
	s_add_u32 s40, s40, 0x80000
	s_addc_u32 s41, s41, 0
	s_mov_b32 m0, s48
	v_lshl_add_u64 v[226:227], s[40:41], 0, v[146:147]
	ds_read_b128 v[188:191], v173 offset:32768
	ds_read_b128 v[192:195], v173 offset:33792
	ds_read_b128 v[196:199], v173 offset:34816
	ds_read_b128 v[200:203], v173 offset:35840
	ds_read_b128 v[204:207], v173 offset:36864
	ds_read_b128 v[208:211], v173 offset:37888
	ds_read_b128 v[212:215], v173 offset:38912
	ds_read_b128 v[216:219], v173 offset:39936
	global_load_lds_dwordx4 v[226:227], off
	v_lshl_add_u64 v[226:227], s[40:41], 0, v[150:151]
	s_mov_b32 m0, s49
	s_nop 0
	global_load_lds_dwordx4 v[226:227], off
	s_waitcnt vmcnt(8)
	s_waitcnt lgkmcnt(0)
	s_barrier
	s_setprio 1
	s_waitcnt lgkmcnt(0)
	v_mfma_i32_16x16x64_i8 v[142:145], v[118:121], v[188:191], v[142:145]
	v_mfma_i32_16x16x64_i8 v[138:141], v[130:133], v[188:191], v[138:141]
	v_mfma_i32_16x16x64_i8 v[110:113], v[118:121], v[196:199], v[110:113]
	v_mfma_i32_16x16x64_i8 v[106:109], v[130:133], v[196:199], v[106:109]
	v_mfma_i32_16x16x64_i8 v[94:97], v[118:121], v[204:207], v[94:97]
	v_mfma_i32_16x16x64_i8 v[90:93], v[130:133], v[204:207], v[90:93]
	v_mfma_i32_16x16x64_i8 v[78:81], v[118:121], v[212:215], v[78:81]
	v_mfma_i32_16x16x64_i8 v[74:77], v[130:133], v[212:215], v[74:77]
	s_setprio 0
	s_setprio 1
	v_mfma_i32_16x16x64_i8 v[142:145], v[126:129], v[192:195], v[142:145]
	v_mfma_i32_16x16x64_i8 v[138:141], v[134:137], v[192:195], v[138:141]
	v_mfma_i32_16x16x64_i8 v[110:113], v[126:129], v[200:203], v[110:113]
	v_mfma_i32_16x16x64_i8 v[106:109], v[134:137], v[200:203], v[106:109]
	v_mfma_i32_16x16x64_i8 v[94:97], v[126:129], v[208:211], v[94:97]
	v_mfma_i32_16x16x64_i8 v[90:93], v[134:137], v[208:211], v[90:93]
	v_mfma_i32_16x16x64_i8 v[78:81], v[126:129], v[216:219], v[78:81]
	v_mfma_i32_16x16x64_i8 v[74:77], v[134:137], v[216:219], v[74:77]
	s_setprio 0
	s_setprio 1
	v_mfma_i32_16x16x64_i8 v[122:125], v[168:171], v[188:191], v[122:125]
	v_mfma_i32_16x16x64_i8 v[114:117], v[180:183], v[188:191], v[114:117]
	v_mfma_i32_16x16x64_i8 v[102:105], v[168:171], v[196:199], v[102:105]
	v_mfma_i32_16x16x64_i8 v[98:101], v[180:183], v[196:199], v[98:101]
	v_mfma_i32_16x16x64_i8 v[86:89], v[168:171], v[204:207], v[86:89]
	v_mfma_i32_16x16x64_i8 v[82:85], v[180:183], v[204:207], v[82:85]
	v_mfma_i32_16x16x64_i8 v[70:73], v[168:171], v[212:215], v[70:73]
	v_mfma_i32_16x16x64_i8 v[66:69], v[180:183], v[212:215], v[66:69]
	s_setprio 0
	s_setprio 1
	v_mfma_i32_16x16x64_i8 v[122:125], v[176:179], v[192:195], v[122:125]
	v_mfma_i32_16x16x64_i8 v[114:117], v[184:187], v[192:195], v[114:117]
	v_mfma_i32_16x16x64_i8 v[102:105], v[176:179], v[200:203], v[102:105]
	v_mfma_i32_16x16x64_i8 v[98:101], v[184:187], v[200:203], v[98:101]
	v_mfma_i32_16x16x64_i8 v[86:89], v[176:179], v[208:211], v[86:89]
	v_mfma_i32_16x16x64_i8 v[82:85], v[184:187], v[208:211], v[82:85]
	v_mfma_i32_16x16x64_i8 v[70:73], v[176:179], v[216:219], v[70:73]
	v_mfma_i32_16x16x64_i8 v[66:69], v[184:187], v[216:219], v[66:69]
	s_setprio 0
	s_barrier
; #define PG8_STAGE(bufoff, gbase, voff) do { _Pragma("unroll") for (int _i = 0; _i < 2; ++_i) \
;         __builtin_amdgcn_global_load_lds((const unsigned*)((const char*)(gbase) + (voff)[_i]), (PG8_LAS unsigned*)(lds + (bufoff) + ldsw + _i * 8192), 16, 0, 0); } while (0)
; #define PG8_LDA(dst, b, h) do { _Pragma("unroll") for (int m = 0; m < 4; ++m) _Pragma("unroll") for (int k = 0; k < 2; ++k) dst[m][k] = *(const PG8_LAS bf16x8*)(lds + PG8_SA(b, h) + aoff + m * 2048 + k * 1024); } while (0)
; #define PG8_MMA(ai, bj, At, Bt) do { __builtin_amdgcn_s_setprio(1); _Pragma("unroll") for (int m = 0; m < 4; ++m) _Pragma("unroll") for (int n = 0; n < 2; ++n) _Pragma("unroll") for (int k = 0; k < 2; ++k) \
;         acc[ai][bj][m][n] = mma_<I8>(Bt[n][k], At[m][k], acc[ai][bj][m][n]); __builtin_amdgcn_s_setprio(0); } while (0)
; #define PG8_WAIT_V(n) asm volatile("s_waitcnt vmcnt(" #n ")" ::: "memory")
; #define PG8_WAIT_L(n) asm volatile("s_waitcnt lgkmcnt(" #n ")" ::: "memory")
; #define PG8_BAR __builtin_amdgcn_s_barrier()
; #define PG8_SCHED __builtin_amdgcn_sched_barrier(0)
; template <class Epi, class Sched, bool ALIGN_EPI = false, bool SP2 = false, bool I8 = false>
; __device__ __forceinline__ void gemm_phase(PG8_LAS unsigned char* lds, const Gemm g, const Sched& S, const Epi& E) {
;     ...
;             PG8_LDA(At, 1, 1); PG8_STAGE(PG8_SB(1, 0), b3, voffB); PG8_STAGE(PG8_SB(1, 1), b3 + hstepB, voffB); PG8_STAGE(PG8_SA(1, 0), a3, voffA);
;             PG8_WAIT_V(8); PG8_WAIT_L(0); PG8_BAR; PG8_MMA(1, 0, At, B0); PG8_MMA(1, 1, At, B1); PG8_BAR; PG8_SCHED;
;     ...
;         if constexpr (ALIGN_EPI) { if (wr == 0) PG8_BAR; }
	s_add_i32 s40, s66, s46
	v_lshl_add_u64 v[164:165], v[164:165], 0, s[12:13]
	s_mov_b32 m0, s40
	ds_read_b128 v[188:191], v173 offset:49152
	ds_read_b128 v[192:195], v173 offset:50176
	ds_read_b128 v[196:199], v173 offset:51200
	ds_read_b128 v[200:203], v173 offset:52224
	ds_read_b128 v[204:207], v173 offset:53248
	ds_read_b128 v[208:211], v173 offset:54272
	ds_read_b128 v[212:215], v173 offset:55296
	ds_read_b128 v[216:219], v173 offset:56320
	global_load_lds_dwordx4 v[164:165], off
	s_add_i32 m0, s40, 0x2000
	s_add_u32 s38, s38, 0x80080
	v_lshl_add_u64 v[164:165], v[220:221], 0, s[12:13]
	s_addc_u32 s39, s39, 0
	s_add_i32 s40, s67, s46
	global_load_lds_dwordx4 v[164:165], off
	v_lshl_add_u64 v[164:165], s[38:39], 0, v[148:149]
	s_mov_b32 m0, s40
	s_nop 0
	global_load_lds_dwordx4 v[164:165], off
	v_lshl_add_u64 v[164:165], s[38:39], 0, v[152:153]
	s_add_i32 m0, s40, 0x2000
	s_nop 0
	global_load_lds_dwordx4 v[164:165], off
	v_lshl_add_u64 v[164:165], v[222:223], 0, s[12:13]
	s_mov_b32 m0, s51
	s_nop 0
	global_load_lds_dwordx4 v[164:165], off
	v_lshl_add_u64 v[164:165], v[224:225], 0, s[12:13]
	s_mov_b32 m0, s52
	s_nop 0
	global_load_lds_dwordx4 v[164:165], off
	s_waitcnt vmcnt(8)
	s_waitcnt lgkmcnt(0)
	s_barrier
	s_setprio 1
	s_waitcnt lgkmcnt(0)
	v_mfma_i32_16x16x64_i8 v[62:65], v[118:121], v[188:191], v[62:65]
	v_mfma_i32_16x16x64_i8 v[58:61], v[130:133], v[188:191], v[58:61]
	v_mfma_i32_16x16x64_i8 v[46:49], v[118:121], v[196:199], v[46:49]
	v_mfma_i32_16x16x64_i8 v[42:45], v[130:133], v[196:199], v[42:45]
	v_mfma_i32_16x16x64_i8 v[30:33], v[118:121], v[204:207], v[30:33]
	v_mfma_i32_16x16x64_i8 v[26:29], v[130:133], v[204:207], v[26:29]
	v_mfma_i32_16x16x64_i8 v[14:17], v[118:121], v[212:215], v[14:17]
	v_mfma_i32_16x16x64_i8 v[10:13], v[130:133], v[212:215], v[10:13]
	s_setprio 0
	s_setprio 1
	v_mfma_i32_16x16x64_i8 v[62:65], v[126:129], v[192:195], v[62:65]
	v_mfma_i32_16x16x64_i8 v[58:61], v[134:137], v[192:195], v[58:61]
	v_mfma_i32_16x16x64_i8 v[46:49], v[126:129], v[200:203], v[46:49]
	v_mfma_i32_16x16x64_i8 v[42:45], v[134:137], v[200:203], v[42:45]
	v_mfma_i32_16x16x64_i8 v[30:33], v[126:129], v[208:211], v[30:33]
	v_mfma_i32_16x16x64_i8 v[26:29], v[134:137], v[208:211], v[26:29]
	v_mfma_i32_16x16x64_i8 v[14:17], v[126:129], v[216:219], v[14:17]
	v_mfma_i32_16x16x64_i8 v[10:13], v[134:137], v[216:219], v[10:13]
	s_setprio 0
	s_setprio 1
	v_mfma_i32_16x16x64_i8 v[54:57], v[168:171], v[188:191], v[54:57]
	v_mfma_i32_16x16x64_i8 v[50:53], v[180:183], v[188:191], v[50:53]
	v_mfma_i32_16x16x64_i8 v[38:41], v[168:171], v[196:199], v[38:41]
	v_mfma_i32_16x16x64_i8 v[34:37], v[180:183], v[196:199], v[34:37]
	v_mfma_i32_16x16x64_i8 v[22:25], v[168:171], v[204:207], v[22:25]
	v_mfma_i32_16x16x64_i8 v[18:21], v[180:183], v[204:207], v[18:21]
	v_mfma_i32_16x16x64_i8 v[6:9], v[168:171], v[212:215], v[6:9]
	v_mfma_i32_16x16x64_i8 v[2:5], v[180:183], v[212:215], v[2:5]
	s_setprio 0
	s_setprio 1
	v_mfma_i32_16x16x64_i8 v[54:57], v[176:179], v[192:195], v[54:57]
	v_mfma_i32_16x16x64_i8 v[50:53], v[184:187], v[192:195], v[50:53]
	v_mfma_i32_16x16x64_i8 v[38:41], v[176:179], v[200:203], v[38:41]
	v_mfma_i32_16x16x64_i8 v[34:37], v[184:187], v[200:203], v[34:37]
	v_mfma_i32_16x16x64_i8 v[22:25], v[176:179], v[208:211], v[22:25]
	v_mfma_i32_16x16x64_i8 v[18:21], v[184:187], v[208:211], v[18:21]
	v_mfma_i32_16x16x64_i8 v[6:9], v[176:179], v[216:219], v[6:9]
	v_mfma_i32_16x16x64_i8 v[2:5], v[184:187], v[216:219], v[2:5]
	s_setprio 0
	s_barrier
	s_add_i32 s65, s65, 2
	s_add_u32 s36, s36, 0x100
	s_addc_u32 s37, s37, 0
	s_add_u32 s63, s63, 0x100
	s_addc_u32 s64, s64, 0
	s_cmp_gt_u32 s65, 29
	s_cbranch_scc0 .LBB0_2014
	s_and_b64 vcc, exec, s[14:15]
	s_cbranch_vccz .LBB0_2017
	s_barrier

; #define PG8_STAGE(bufoff, gbase, voff) do { _Pragma("unroll") for (int _i = 0; _i < 2; ++_i) \
;         __builtin_amdgcn_global_load_lds((const unsigned*)((const char*)(gbase) + (voff)[_i]), (PG8_LAS unsigned*)(lds + (bufoff) + ldsw + _i * 8192), 16, 0, 0); } while (0)
; #define PG8_LDA(dst, b, h) do { _Pragma("unroll") for (int m = 0; m < 4; ++m) _Pragma("unroll") for (int k = 0; k < 2; ++k) dst[m][k] = *(const PG8_LAS bf16x8*)(lds + PG8_SA(b, h) + aoff + m * 2048 + k * 1024); } while (0)
; #define PG8_LDB(dst, b, h) do { _Pragma("unroll") for (int n = 0; n < 2; ++n) _Pragma("unroll") for (int k = 0; k < 2; ++k) dst[n][k] = *(const PG8_LAS bf16x8*)(lds + PG8_SB(b, h) + boff + n * 2048 + k * 1024); } while (0)
; #define PG8_MMA(ai, bj, At, Bt) do { __builtin_amdgcn_s_setprio(1); _Pragma("unroll") for (int m = 0; m < 4; ++m) _Pragma("unroll") for (int n = 0; n < 2; ++n) _Pragma("unroll") for (int k = 0; k < 2; ++k) \
;         acc[ai][bj][m][n] = mma_<I8>(Bt[n][k], At[m][k], acc[ai][bj][m][n]); __builtin_amdgcn_s_setprio(0); } while (0)
; #define PG8_WAIT_V(n) asm volatile("s_waitcnt vmcnt(" #n ")" ::: "memory")
; #define PG8_WAIT_L(n) asm volatile("s_waitcnt lgkmcnt(" #n ")" ::: "memory")
; #define PG8_BAR __builtin_amdgcn_s_barrier()
; template <class Epi, class Sched, bool ALIGN_EPI = false, bool SP2 = false, bool I8 = false>
; __device__ __forceinline__ void gemm_phase(PG8_LAS unsigned char* lds, const Gemm g, const Sched& S, const Epi& E) {
;     ...
;             const bool last = (t == nt - 2);
;             const char* a1 = cA + (size_t)(t + 1) * kstep;
;             const char* a2 = last ? nA : cA + (size_t)(t + 2) * kstep; const char* b2 = last ? nB : cB + (size_t)(t + 2) * kstep;
;             const char* a3 = a2 + kstep; const char* b3 = b2 + kstep;
;             if (last && has_next) S.a_ready(nxt);
;             if constexpr (SP2) {
;             PG8_LDB(B0, 0, 0); PG8_LDB(B1, 0, 1); PG8_SCHED; PG8_LDA(At, 0, 0); PG8_STAGE(PG8_SA(1, 1), a1 + hstepA, voffA);
;             PG8_WAIT_V(8); PG8_WAIT_L(0); PG8_BAR; PG8_MMA(0, 0, At, B0); PG8_MMA(0, 1, At, B1); PG8_BAR; PG8_SCHED;
;             PG8_LDA(At, 0, 1); PG8_STAGE(PG8_SB(0, 0), b2, voffB); PG8_STAGE(PG8_SB(0, 1), b2 + hstepB, voffB); PG8_STAGE(PG8_SA(0, 0), a2, voffA);
;             PG8_WAIT_V(8); PG8_WAIT_L(0); PG8_BAR; PG8_MMA(1, 0, At, B0); PG8_MMA(1, 1, At, B1); PG8_BAR; PG8_SCHED;
.LBB0_2092:
	ds_read_b128 v[130:133], v192
	ds_read_b128 v[134:137], v192 offset:1024
	ds_read_b128 v[138:141], v192 offset:2048
	ds_read_b128 v[142:145], v192 offset:3072
	ds_read_b128 v[146:149], v193
	ds_read_b128 v[150:153], v193 offset:1024
	ds_read_b128 v[154:157], v193 offset:2048
	ds_read_b128 v[158:161], v193 offset:3072
	s_add_u32 s28, s8, 0xffc00080
	s_addc_u32 s29, s9, -1
	s_cmpk_eq_i32 s51, 0xfc
	s_cselect_b32 s31, s3, s29
	s_cselect_b32 s30, s7, s28
	s_cselect_b32 s29, s21, s50
	s_cselect_b32 s28, s23, s49
	v_lshl_add_u64 v[190:191], s[8:9], 0, v[174:175]
	s_add_i32 m0, s38, 0xc000
	ds_read_b128 v[162:165], v194
	ds_read_b128 v[166:169], v194 offset:1024
	ds_read_b128 v[182:185], v194 offset:2048
	ds_read_b128 v[186:189], v194 offset:3072
	ds_read_b128 v[196:199], v194 offset:4096
	ds_read_b128 v[200:203], v194 offset:5120
	ds_read_b128 v[204:207], v194 offset:6144
	ds_read_b128 v[208:211], v194 offset:7168
	global_load_lds_dwordx4 v[190:191], off
	v_lshl_add_u64 v[190:191], s[8:9], 0, v[176:177]
	s_add_i32 m0, s38, 0xe000
	s_nop 0
	global_load_lds_dwordx4 v[190:191], off
	s_waitcnt vmcnt(8)
	s_waitcnt lgkmcnt(0)
	s_barrier
	s_setprio 1
	s_waitcnt lgkmcnt(0)
	v_mfma_f32_16x16x32_bf16 v[126:129], v[130:133], v[162:165], v[126:129]
	v_mfma_f32_16x16x32_bf16 v[122:125], v[138:141], v[162:165], v[122:125]
	v_mfma_f32_16x16x32_bf16 v[110:113], v[130:133], v[182:185], v[110:113]
	v_mfma_f32_16x16x32_bf16 v[106:109], v[138:141], v[182:185], v[106:109]
	v_mfma_f32_16x16x32_bf16 v[94:97], v[130:133], v[196:199], v[94:97]
	v_mfma_f32_16x16x32_bf16 v[90:93], v[138:141], v[196:199], v[90:93]
	v_mfma_f32_16x16x32_bf16 v[78:81], v[130:133], v[204:207], v[78:81]
	v_mfma_f32_16x16x32_bf16 v[74:77], v[138:141], v[204:207], v[74:77]
	s_setprio 0
	s_setprio 1
	v_mfma_f32_16x16x32_bf16 v[126:129], v[134:137], v[166:169], v[126:129]
	v_mfma_f32_16x16x32_bf16 v[122:125], v[142:145], v[166:169], v[122:125]
	v_mfma_f32_16x16x32_bf16 v[110:113], v[134:137], v[186:189], v[110:113]
	v_mfma_f32_16x16x32_bf16 v[106:109], v[142:145], v[186:189], v[106:109]
	v_mfma_f32_16x16x32_bf16 v[94:97], v[134:137], v[200:203], v[94:97]
	v_mfma_f32_16x16x32_bf16 v[90:93], v[142:145], v[200:203], v[90:93]
	v_mfma_f32_16x16x32_bf16 v[78:81], v[134:137], v[208:211], v[78:81]
	v_mfma_f32_16x16x32_bf16 v[74:77], v[142:145], v[208:211], v[74:77]
	s_setprio 0
	s_setprio 1
	v_mfma_f32_16x16x32_bf16 v[118:121], v[146:149], v[162:165], v[118:121]
	v_mfma_f32_16x16x32_bf16 v[114:117], v[154:157], v[162:165], v[114:117]
	v_mfma_f32_16x16x32_bf16 v[102:105], v[146:149], v[182:185], v[102:105]
	v_mfma_f32_16x16x32_bf16 v[98:101], v[154:157], v[182:185], v[98:101]
	v_mfma_f32_16x16x32_bf16 v[86:89], v[146:149], v[196:199], v[86:89]
	v_mfma_f32_16x16x32_bf16 v[82:85], v[154:157], v[196:199], v[82:85]
	v_mfma_f32_16x16x32_bf16 v[70:73], v[146:149], v[204:207], v[70:73]
	v_mfma_f32_16x16x32_bf16 v[66:69], v[154:157], v[204:207], v[66:69]
	s_setprio 0
	s_setprio 1
	v_mfma_f32_16x16x32_bf16 v[118:121], v[150:153], v[166:169], v[118:121]
	v_mfma_f32_16x16x32_bf16 v[114:117], v[158:161], v[166:169], v[114:117]
	v_mfma_f32_16x16x32_bf16 v[102:105], v[150:153], v[186:189], v[102:105]
	v_mfma_f32_16x16x32_bf16 v[98:101], v[158:161], v[186:189], v[98:101]
	v_mfma_f32_16x16x32_bf16 v[86:89], v[150:153], v[200:203], v[86:89]
	v_mfma_f32_16x16x32_bf16 v[82:85], v[158:161], v[200:203], v[82:85]
	v_mfma_f32_16x16x32_bf16 v[70:73], v[150:153], v[208:211], v[70:73]
	v_mfma_f32_16x16x32_bf16 v[66:69], v[158:161], v[208:211], v[66:69]
	s_setprio 0
	s_barrier
	s_add_i32 s52, s47, s33
	v_lshl_add_u64 v[190:191], s[28:29], 0, v[170:171]
	s_mov_b32 m0, s52
	ds_read_b128 v[162:165], v194 offset:16384
	ds_read_b128 v[166:169], v194 offset:17408
	ds_read_b128 v[182:185], v194 offset:18432
	ds_read_b128 v[186:189], v194 offset:19456
	ds_read_b128 v[196:199], v194 offset:20480
	ds_read_b128 v[200:203], v194 offset:21504
	ds_read_b128 v[204:207], v194 offset:22528
	ds_read_b128 v[208:211], v194 offset:23552
	global_load_lds_dwordx4 v[190:191], off
	s_add_i32 m0, s52, 0x2000
	s_add_u32 s52, s28, 0x400000
	v_lshl_add_u64 v[212:213], s[28:29], 0, v[172:173]
	s_addc_u32 s53, s29, 0
	s_add_i32 s54, s48, s33
	global_load_lds_dwordx4 v[212:213], off
	v_lshl_add_u64 v[214:215], s[52:53], 0, v[170:171]
	s_mov_b32 m0, s54
	v_lshl_add_u64 v[216:217], s[30:31], 0, v[172:173]
	global_load_lds_dwordx4 v[214:215], off
	v_lshl_add_u64 v[214:215], s[52:53], 0, v[172:173]
	s_add_i32 m0, s54, 0x2000
	s_nop 0
	global_load_lds_dwordx4 v[214:215], off
	v_lshl_add_u64 v[214:215], s[30:31], 0, v[170:171]
	s_mov_b32 m0, s38
	s_nop 0
	global_load_lds_dwordx4 v[214:215], off
	s_mov_b32 m0, s39
	s_nop 0
	global_load_lds_dwordx4 v[216:217], off
	s_waitcnt vmcnt(8)
	s_waitcnt lgkmcnt(0)
	s_barrier
; #define PG8_STAGE(bufoff, gbase, voff) do { _Pragma("unroll") for (int _i = 0; _i < 2; ++_i) \
;         __builtin_amdgcn_global_load_lds((const unsigned*)((const char*)(gbase) + (voff)[_i]), (PG8_LAS unsigned*)(lds + (bufoff) + ldsw + _i * 8192), 16, 0, 0); } while (0)
; #define PG8_LDA(dst, b, h) do { _Pragma("unroll") for (int m = 0; m < 4; ++m) _Pragma("unroll") for (int k = 0; k < 2; ++k) dst[m][k] = *(const PG8_LAS bf16x8*)(lds + PG8_SA(b, h) + aoff + m * 2048 + k * 1024); } while (0)
; #define PG8_LDB(dst, b, h) do { _Pragma("unroll") for (int n = 0; n < 2; ++n) _Pragma("unroll") for (int k = 0; k < 2; ++k) dst[n][k] = *(const PG8_LAS bf16x8*)(lds + PG8_SB(b, h) + boff + n * 2048 + k * 1024); } while (0)
; #define PG8_MMA(ai, bj, At, Bt) do { __builtin_amdgcn_s_setprio(1); _Pragma("unroll") for (int m = 0; m < 4; ++m) _Pragma("unroll") for (int n = 0; n < 2; ++n) _Pragma("unroll") for (int k = 0; k < 2; ++k) \
;         acc[ai][bj][m][n] = mma_<I8>(Bt[n][k], At[m][k], acc[ai][bj][m][n]); __builtin_amdgcn_s_setprio(0); } while (0)
; #define PG8_WAIT_V(n) asm volatile("s_waitcnt vmcnt(" #n ")" ::: "memory")
; #define PG8_WAIT_L(n) asm volatile("s_waitcnt lgkmcnt(" #n ")" ::: "memory")
; #define PG8_BAR __builtin_amdgcn_s_barrier()
; #define PG8_SCHED __builtin_amdgcn_sched_barrier(0)
; template <class Epi, class Sched, bool ALIGN_EPI = false, bool SP2 = false, bool I8 = false>
; __device__ __forceinline__ void gemm_phase(PG8_LAS unsigned char* lds, const Gemm g, const Sched& S, const Epi& E) {
;     ...
;             PG8_WAIT_V(8); PG8_WAIT_L(0); PG8_BAR; PG8_MMA(1, 0, At, B0); PG8_MMA(1, 1, At, B1); PG8_BAR; PG8_SCHED;
;             PG8_LDB(B0, 1, 0); PG8_LDB(B1, 1, 1); PG8_SCHED; PG8_LDA(At, 1, 0); PG8_STAGE(PG8_SA(0, 1), a2 + hstepA, voffA);
;             PG8_WAIT_V(8); PG8_WAIT_L(0); PG8_BAR; PG8_MMA(0, 0, At, B0); PG8_MMA(0, 1, At, B1); PG8_BAR; PG8_SCHED;
	s_setprio 1
	s_waitcnt lgkmcnt(0)
	v_mfma_f32_16x16x32_bf16 v[62:65], v[130:133], v[162:165], v[62:65]
	v_mfma_f32_16x16x32_bf16 v[58:61], v[138:141], v[162:165], v[58:61]
	v_mfma_f32_16x16x32_bf16 v[46:49], v[130:133], v[182:185], v[46:49]
	v_mfma_f32_16x16x32_bf16 v[42:45], v[138:141], v[182:185], v[42:45]
	v_mfma_f32_16x16x32_bf16 v[30:33], v[130:133], v[196:199], v[30:33]
	v_mfma_f32_16x16x32_bf16 v[26:29], v[138:141], v[196:199], v[26:29]
	v_mfma_f32_16x16x32_bf16 v[22:25], v[130:133], v[204:207], v[22:25]
	v_mfma_f32_16x16x32_bf16 v[10:13], v[138:141], v[204:207], v[10:13]
	s_setprio 0
	s_setprio 1
	v_mfma_f32_16x16x32_bf16 v[62:65], v[134:137], v[166:169], v[62:65]
	v_mfma_f32_16x16x32_bf16 v[58:61], v[142:145], v[166:169], v[58:61]
	v_mfma_f32_16x16x32_bf16 v[46:49], v[134:137], v[186:189], v[46:49]
	v_mfma_f32_16x16x32_bf16 v[42:45], v[142:145], v[186:189], v[42:45]
	v_mfma_f32_16x16x32_bf16 v[30:33], v[134:137], v[200:203], v[30:33]
	v_mfma_f32_16x16x32_bf16 v[26:29], v[142:145], v[200:203], v[26:29]
	v_mfma_f32_16x16x32_bf16 v[22:25], v[134:137], v[208:211], v[22:25]
	v_mfma_f32_16x16x32_bf16 v[10:13], v[142:145], v[208:211], v[10:13]
	s_setprio 0
	s_setprio 1
	v_mfma_f32_16x16x32_bf16 v[54:57], v[146:149], v[162:165], v[54:57]
	v_mfma_f32_16x16x32_bf16 v[50:53], v[154:157], v[162:165], v[50:53]
	v_mfma_f32_16x16x32_bf16 v[38:41], v[146:149], v[182:185], v[38:41]
	v_mfma_f32_16x16x32_bf16 v[34:37], v[154:157], v[182:185], v[34:37]
	v_mfma_f32_16x16x32_bf16 v[18:21], v[146:149], v[196:199], v[18:21]
	v_mfma_f32_16x16x32_bf16 v[14:17], v[154:157], v[196:199], v[14:17]
	v_mfma_f32_16x16x32_bf16 v[6:9], v[146:149], v[204:207], v[6:9]
	v_mfma_f32_16x16x32_bf16 v[2:5], v[154:157], v[204:207], v[2:5]
	s_setprio 0
	s_setprio 1
	v_mfma_f32_16x16x32_bf16 v[54:57], v[150:153], v[166:169], v[54:57]
	v_mfma_f32_16x16x32_bf16 v[50:53], v[158:161], v[166:169], v[50:53]
	v_mfma_f32_16x16x32_bf16 v[38:41], v[150:153], v[186:189], v[38:41]
	v_mfma_f32_16x16x32_bf16 v[34:37], v[158:161], v[186:189], v[34:37]
	v_mfma_f32_16x16x32_bf16 v[18:21], v[150:153], v[200:203], v[18:21]
	v_mfma_f32_16x16x32_bf16 v[14:17], v[158:161], v[200:203], v[14:17]
	v_mfma_f32_16x16x32_bf16 v[6:9], v[150:153], v[208:211], v[6:9]
	v_mfma_f32_16x16x32_bf16 v[2:5], v[158:161], v[208:211], v[2:5]
	s_setprio 0
	s_barrier
	s_add_i32 s52, 0, 0x18000
	s_add_i32 s53, 0, 0x1c000
	v_add_u32_e32 v142, s52, v1
	v_add_u32_e32 v158, s53, v1
	ds_read_b128 v[130:133], v142
	ds_read_b128 v[134:137], v142 offset:1024
	ds_read_b128 v[138:141], v142 offset:2048
	ds_read_b128 v[142:145], v142 offset:3072
	ds_read_b128 v[146:149], v158
	ds_read_b128 v[150:153], v158 offset:1024
	ds_read_b128 v[154:157], v158 offset:2048
	ds_read_b128 v[158:161], v158 offset:3072
	s_add_u32 s30, s30, 0x400000
	s_addc_u32 s31, s31, 0
	s_mov_b32 m0, s40
	v_lshl_add_u64 v[218:219], s[30:31], 0, v[170:171]
	ds_read_b128 v[162:165], v194 offset:32768
	ds_read_b128 v[166:169], v194 offset:33792
	ds_read_b128 v[182:185], v194 offset:34816
	ds_read_b128 v[186:189], v194 offset:35840
	ds_read_b128 v[196:199], v194 offset:36864
	ds_read_b128 v[200:203], v194 offset:37888
	ds_read_b128 v[204:207], v194 offset:38912
	ds_read_b128 v[208:211], v194 offset:39936
	global_load_lds_dwordx4 v[218:219], off
	v_lshl_add_u64 v[218:219], s[30:31], 0, v[172:173]
	s_mov_b32 m0, s41
	s_nop 0
	global_load_lds_dwordx4 v[218:219], off
	s_waitcnt vmcnt(8)
	s_waitcnt lgkmcnt(0)
	s_barrier
	s_setprio 1
	s_waitcnt lgkmcnt(0)
	v_mfma_f32_16x16x32_bf16 v[126:129], v[130:133], v[162:165], v[126:129]
	v_mfma_f32_16x16x32_bf16 v[122:125], v[138:141], v[162:165], v[122:125]
	v_mfma_f32_16x16x32_bf16 v[110:113], v[130:133], v[182:185], v[110:113]
	v_mfma_f32_16x16x32_bf16 v[106:109], v[138:141], v[182:185], v[106:109]
	v_mfma_f32_16x16x32_bf16 v[94:97], v[130:133], v[196:199], v[94:97]
	v_mfma_f32_16x16x32_bf16 v[90:93], v[138:141], v[196:199], v[90:93]
	v_mfma_f32_16x16x32_bf16 v[78:81], v[130:133], v[204:207], v[78:81]
	v_mfma_f32_16x16x32_bf16 v[74:77], v[138:141], v[204:207], v[74:77]
	s_setprio 0
	s_setprio 1
	v_mfma_f32_16x16x32_bf16 v[126:129], v[134:137], v[166:169], v[126:129]
	v_mfma_f32_16x16x32_bf16 v[122:125], v[142:145], v[166:169], v[122:125]
	v_mfma_f32_16x16x32_bf16 v[110:113], v[134:137], v[186:189], v[110:113]
	v_mfma_f32_16x16x32_bf16 v[106:109], v[142:145], v[186:189], v[106:109]
	v_mfma_f32_16x16x32_bf16 v[94:97], v[134:137], v[200:203], v[94:97]
	v_mfma_f32_16x16x32_bf16 v[90:93], v[142:145], v[200:203], v[90:93]
	v_mfma_f32_16x16x32_bf16 v[78:81], v[134:137], v[208:211], v[78:81]
	v_mfma_f32_16x16x32_bf16 v[74:77], v[142:145], v[208:211], v[74:77]
	s_setprio 0
	s_setprio 1
	v_mfma_f32_16x16x32_bf16 v[118:121], v[146:149], v[162:165], v[118:121]
	v_mfma_f32_16x16x32_bf16 v[114:117], v[154:157], v[162:165], v[114:117]
	v_mfma_f32_16x16x32_bf16 v[102:105], v[146:149], v[182:185], v[102:105]
	v_mfma_f32_16x16x32_bf16 v[98:101], v[154:157], v[182:185], v[98:101]
	v_mfma_f32_16x16x32_bf16 v[86:89], v[146:149], v[196:199], v[86:89]
	v_mfma_f32_16x16x32_bf16 v[82:85], v[154:157], v[196:199], v[82:85]
	v_mfma_f32_16x16x32_bf16 v[70:73], v[146:149], v[204:207], v[70:73]
	v_mfma_f32_16x16x32_bf16 v[66:69], v[154:157], v[204:207], v[66:69]
	s_setprio 0
	s_setprio 1
	v_mfma_f32_16x16x32_bf16 v[118:121], v[150:153], v[166:169], v[118:121]
	v_mfma_f32_16x16x32_bf16 v[114:117], v[158:161], v[166:169], v[114:117]
	v_mfma_f32_16x16x32_bf16 v[102:105], v[150:153], v[186:189], v[102:105]
	v_mfma_f32_16x16x32_bf16 v[98:101], v[158:161], v[186:189], v[98:101]
	v_mfma_f32_16x16x32_bf16 v[86:89], v[150:153], v[200:203], v[86:89]
	v_mfma_f32_16x16x32_bf16 v[82:85], v[158:161], v[200:203], v[82:85]
	v_mfma_f32_16x16x32_bf16 v[70:73], v[150:153], v[208:211], v[70:73]
	v_mfma_f32_16x16x32_bf16 v[66:69], v[158:161], v[208:211], v[66:69]
	s_setprio 0
	s_barrier
; #define PG8_STAGE(bufoff, gbase, voff) do { _Pragma("unroll") for (int _i = 0; _i < 2; ++_i) \
;         __builtin_amdgcn_global_load_lds((const unsigned*)((const char*)(gbase) + (voff)[_i]), (PG8_LAS unsigned*)(lds + (bufoff) + ldsw + _i * 8192), 16, 0, 0); } while (0)
; #define PG8_LDA(dst, b, h) do { _Pragma("unroll") for (int m = 0; m < 4; ++m) _Pragma("unroll") for (int k = 0; k < 2; ++k) dst[m][k] = *(const PG8_LAS bf16x8*)(lds + PG8_SA(b, h) + aoff + m * 2048 + k * 1024); } while (0)
; #define PG8_MMA(ai, bj, At, Bt) do { __builtin_amdgcn_s_setprio(1); _Pragma("unroll") for (int m = 0; m < 4; ++m) _Pragma("unroll") for (int n = 0; n < 2; ++n) _Pragma("unroll") for (int k = 0; k < 2; ++k) \
;         acc[ai][bj][m][n] = mma_<I8>(Bt[n][k], At[m][k], acc[ai][bj][m][n]); __builtin_amdgcn_s_setprio(0); } while (0)
; #define PG8_WAIT_V(n) asm volatile("s_waitcnt vmcnt(" #n ")" ::: "memory")
; #define PG8_WAIT_L(n) asm volatile("s_waitcnt lgkmcnt(" #n ")" ::: "memory")
; #define PG8_BAR __builtin_amdgcn_s_barrier()
; #define PG8_SCHED __builtin_amdgcn_sched_barrier(0)
; template <class Epi, class Sched, bool ALIGN_EPI = false, bool SP2 = false, bool I8 = false>
; __device__ __forceinline__ void gemm_phase(PG8_LAS unsigned char* lds, const Gemm g, const Sched& S, const Epi& E) {
;     ...
;             PG8_LDA(At, 1, 1); PG8_STAGE(PG8_SB(1, 0), b3, voffB); PG8_STAGE(PG8_SB(1, 1), b3 + hstepB, voffB); PG8_STAGE(PG8_SA(1, 0), a3, voffA);
;             PG8_WAIT_V(8); PG8_WAIT_L(0); PG8_BAR; PG8_MMA(1, 0, At, B0); PG8_MMA(1, 1, At, B1); PG8_BAR; PG8_SCHED;
;     ...
;         if constexpr (ALIGN_EPI) { if (wr == 0) PG8_BAR; }
	s_add_i32 s30, s52, s33
	v_lshl_add_u64 v[190:191], v[190:191], 0, s[14:15]
	s_mov_b32 m0, s30
	ds_read_b128 v[162:165], v194 offset:49152
	ds_read_b128 v[166:169], v194 offset:50176
	ds_read_b128 v[182:185], v194 offset:51200
	ds_read_b128 v[186:189], v194 offset:52224
	ds_read_b128 v[196:199], v194 offset:53248
	ds_read_b128 v[200:203], v194 offset:54272
	ds_read_b128 v[204:207], v194 offset:55296
	ds_read_b128 v[208:211], v194 offset:56320
	global_load_lds_dwordx4 v[190:191], off
	s_add_i32 m0, s30, 0x2000
	s_add_u32 s28, s28, 0x400080
	v_lshl_add_u64 v[190:191], v[212:213], 0, s[14:15]
	s_addc_u32 s29, s29, 0
	s_add_i32 s30, s53, s33
	global_load_lds_dwordx4 v[190:191], off
	v_lshl_add_u64 v[190:191], s[28:29], 0, v[170:171]
	s_mov_b32 m0, s30
	s_nop 0
	global_load_lds_dwordx4 v[190:191], off
	v_lshl_add_u64 v[190:191], s[28:29], 0, v[172:173]
	s_add_i32 m0, s30, 0x2000
	s_nop 0
	global_load_lds_dwordx4 v[190:191], off
	v_lshl_add_u64 v[190:191], v[214:215], 0, s[14:15]
	s_mov_b32 m0, s43
	s_nop 0
	global_load_lds_dwordx4 v[190:191], off
	v_lshl_add_u64 v[190:191], v[216:217], 0, s[14:15]
	s_mov_b32 m0, s44
	s_nop 0
	global_load_lds_dwordx4 v[190:191], off
	s_waitcnt vmcnt(8)
	s_waitcnt lgkmcnt(0)
	s_barrier
	s_setprio 1
	s_waitcnt lgkmcnt(0)
	v_mfma_f32_16x16x32_bf16 v[62:65], v[130:133], v[162:165], v[62:65]
	v_mfma_f32_16x16x32_bf16 v[58:61], v[138:141], v[162:165], v[58:61]
	v_mfma_f32_16x16x32_bf16 v[46:49], v[130:133], v[182:185], v[46:49]
	v_mfma_f32_16x16x32_bf16 v[42:45], v[138:141], v[182:185], v[42:45]
	v_mfma_f32_16x16x32_bf16 v[30:33], v[130:133], v[196:199], v[30:33]
	v_mfma_f32_16x16x32_bf16 v[26:29], v[138:141], v[196:199], v[26:29]
	v_mfma_f32_16x16x32_bf16 v[22:25], v[130:133], v[204:207], v[22:25]
	v_mfma_f32_16x16x32_bf16 v[10:13], v[138:141], v[204:207], v[10:13]
	s_setprio 0
	s_setprio 1
	v_mfma_f32_16x16x32_bf16 v[62:65], v[134:137], v[166:169], v[62:65]
	v_mfma_f32_16x16x32_bf16 v[58:61], v[142:145], v[166:169], v[58:61]
	v_mfma_f32_16x16x32_bf16 v[46:49], v[134:137], v[186:189], v[46:49]
	v_mfma_f32_16x16x32_bf16 v[42:45], v[142:145], v[186:189], v[42:45]
	v_mfma_f32_16x16x32_bf16 v[30:33], v[134:137], v[200:203], v[30:33]
	v_mfma_f32_16x16x32_bf16 v[26:29], v[142:145], v[200:203], v[26:29]
	v_mfma_f32_16x16x32_bf16 v[22:25], v[134:137], v[208:211], v[22:25]
	v_mfma_f32_16x16x32_bf16 v[10:13], v[142:145], v[208:211], v[10:13]
	s_setprio 0
	s_setprio 1
	v_mfma_f32_16x16x32_bf16 v[54:57], v[146:149], v[162:165], v[54:57]
	v_mfma_f32_16x16x32_bf16 v[50:53], v[154:157], v[162:165], v[50:53]
	v_mfma_f32_16x16x32_bf16 v[38:41], v[146:149], v[182:185], v[38:41]
	v_mfma_f32_16x16x32_bf16 v[34:37], v[154:157], v[182:185], v[34:37]
	v_mfma_f32_16x16x32_bf16 v[18:21], v[146:149], v[196:199], v[18:21]
	v_mfma_f32_16x16x32_bf16 v[14:17], v[154:157], v[196:199], v[14:17]
	v_mfma_f32_16x16x32_bf16 v[6:9], v[146:149], v[204:207], v[6:9]
	v_mfma_f32_16x16x32_bf16 v[2:5], v[154:157], v[204:207], v[2:5]
	s_setprio 0
	s_setprio 1
	v_mfma_f32_16x16x32_bf16 v[54:57], v[150:153], v[166:169], v[54:57]
	v_mfma_f32_16x16x32_bf16 v[50:53], v[158:161], v[166:169], v[50:53]
	v_mfma_f32_16x16x32_bf16 v[38:41], v[150:153], v[186:189], v[38:41]
	v_mfma_f32_16x16x32_bf16 v[34:37], v[158:161], v[186:189], v[34:37]
	v_mfma_f32_16x16x32_bf16 v[18:21], v[150:153], v[200:203], v[18:21]
	v_mfma_f32_16x16x32_bf16 v[14:17], v[158:161], v[200:203], v[14:17]
	v_mfma_f32_16x16x32_bf16 v[6:9], v[150:153], v[208:211], v[6:9]
	v_mfma_f32_16x16x32_bf16 v[2:5], v[158:161], v[208:211], v[2:5]
	s_setprio 0
	s_barrier
	s_add_i32 s51, s51, 2
	s_add_u32 s8, s8, 0x100
	s_addc_u32 s9, s9, 0
	s_add_u32 s49, s49, 0x100
	s_addc_u32 s50, s50, 0
	s_cmpk_gt_u32 s51, 0xfd
	s_cbranch_scc0 .LBB0_2092
	s_and_b64 vcc, exec, s[16:17]
	s_cbranch_vccz .LBB0_2095
	s_barrier

; #define PG8_STAGE(bufoff, gbase, voff) do { _Pragma("unroll") for (int _i = 0; _i < 2; ++_i) \
;         __builtin_amdgcn_global_load_lds((const unsigned*)((const char*)(gbase) + (voff)[_i]), (PG8_LAS unsigned*)(lds + (bufoff) + ldsw + _i * 8192), 16, 0, 0); } while (0)
; #define PG8_LDA(dst, b, h) do { _Pragma("unroll") for (int m = 0; m < 4; ++m) _Pragma("unroll") for (int k = 0; k < 2; ++k) dst[m][k] = *(const PG8_LAS bf16x8*)(lds + PG8_SA(b, h) + aoff + m * 2048 + k * 1024); } while (0)
; #define PG8_WAIT_V(n) asm volatile("s_waitcnt vmcnt(" #n ")" ::: "memory")
; #define PG8_WAIT_L(n) asm volatile("s_waitcnt lgkmcnt(" #n ")" ::: "memory")
; template <class Epi, class Sched, bool ALIGN_EPI = false, bool SP2 = false, bool I8 = false>
; __device__ __forceinline__ void gemm_phase(PG8_LAS unsigned char* lds, const Gemm g, const Sched& S, const Epi& E) {
;     ...
; #pragma unroll
;     for (int a = 0; a < 2; ++a)
; #pragma unroll
;         for (int b = 0; b < 2; ++b)
; #pragma unroll
;             for (int m = 0; m < 4; ++m)
; #pragma unroll
;                 for (int n = 0; n < 2; ++n) acc[a][b][m][n] = (typename AccT<I8>::type){0, 0, 0, 0};
;     ...
;         const bool has_next = S.next(ui + 1, nxt);
;         const char* nA = has_next ? (const char*)g.A + (size_t)nxt.pm * tstepA + PG8_K0B(nxt) : cA; const char* nB = has_next ? (const char*)g.Bt + (size_t)nxt.pn * tstepB + PG8_K0B(nxt) : cB;
;         for (int t = 0; t < nt; t += 2) {
;             const bool last = (t == nt - 2);
;             const char* a1 = cA + (size_t)(t + 1) * kstep;
;             const char* a2 = last ? nA : cA + (size_t)(t + 2) * kstep; const char* b2 = last ? nB : cB + (size_t)(t + 2) * kstep;
;             const char* a3 = a2 + kstep; const char* b3 = b2 + kstep;
;             if (last && has_next) S.a_ready(nxt);
;             if constexpr (SP2) {
;             PG8_LDB(B0, 0, 0); PG8_LDB(B1, 0, 1); PG8_SCHED; PG8_LDA(At, 0, 0); PG8_STAGE(PG8_SA(1, 1), a1 + hstepA, voffA);
;             PG8_WAIT_V(8); PG8_WAIT_L(0); PG8_BAR; PG8_MMA(0, 0, At, B0); PG8_MMA(0, 1, At, B1); PG8_BAR; PG8_SCHED;
;             PG8_LDA(At, 0, 1); PG8_STAGE(PG8_SB(0, 0), b2, voffB); PG8_STAGE(PG8_SB(0, 1), b2 + hstepB, voffB); PG8_STAGE(PG8_SA(0, 0), a2, voffA);
;             PG8_WAIT_V(8); PG8_WAIT_L(0); PG8_BAR; PG8_MMA(1, 0, At, B0); PG8_MMA(1, 1, At, B1); PG8_BAR; PG8_SCHED;
.LBB0_2244:
	ds_read_b128 v[2:5], v146
	ds_read_b128 v[6:9], v146 offset:1024
	ds_read_b128 v[10:13], v146 offset:2048
	ds_read_b128 v[14:17], v146 offset:3072
	ds_read_b128 v[18:21], v147
	ds_read_b128 v[22:25], v147 offset:1024
	ds_read_b128 v[26:29], v147 offset:2048
	ds_read_b128 v[30:33], v147 offset:3072
	s_ashr_i32 s21, s20, 31
	s_lshl_b64 s[22:23], s[20:21], 17
	s_add_u32 s22, s33, s22
	s_addc_u32 s23, s38, s23
	s_and_b64 s[24:25], s[4:5], exec
	s_cselect_b32 s37, s23, s29
	s_cselect_b32 s36, s22, s28
	s_ashr_i32 s19, s18, 31
	s_lshl_b64 s[24:25], s[18:19], 17
	s_add_u32 s24, s39, s24
	s_addc_u32 s25, s40, s25
	s_and_b64 s[34:35], s[4:5], exec
	s_cselect_b32 s35, s25, s31
	s_cselect_b32 s34, s24, s30
	s_add_u32 s52, s28, 0x10080
	s_addc_u32 s53, s29, 0
	s_add_i32 s56, s27, 0xc000
	v_lshl_add_u64 v[66:67], s[52:53], 0, v[130:131]
	s_mov_b32 m0, s56
	s_add_i32 s19, s27, 0xe000
	ds_read_b128 v[34:37], v148
	ds_read_b128 v[38:41], v148 offset:1024
	ds_read_b128 v[42:45], v148 offset:2048
	ds_read_b128 v[46:49], v148 offset:3072
	ds_read_b128 v[50:53], v148 offset:4096
	ds_read_b128 v[54:57], v148 offset:5120
	ds_read_b128 v[58:61], v148 offset:6144
	ds_read_b128 v[62:65], v148 offset:7168
	global_load_lds_dwordx4 v[66:67], off
	v_lshl_add_u64 v[66:67], s[52:53], 0, v[134:135]
	s_mov_b32 m0, s19
	s_nop 0
	global_load_lds_dwordx4 v[66:67], off
	s_waitcnt vmcnt(8)
	s_waitcnt lgkmcnt(0)
	s_barrier
	s_setprio 1
	s_waitcnt lgkmcnt(0)
	v_mfma_f32_16x16x32_bf16 v[66:69], v[2:5], v[34:37], 0
	v_mfma_f32_16x16x32_bf16 v[70:73], v[10:13], v[34:37], 0
	v_mfma_f32_16x16x32_bf16 v[74:77], v[2:5], v[42:45], 0
	v_mfma_f32_16x16x32_bf16 v[78:81], v[10:13], v[42:45], 0
	v_mfma_f32_16x16x32_bf16 v[82:85], v[2:5], v[50:53], 0
	v_mfma_f32_16x16x32_bf16 v[86:89], v[10:13], v[50:53], 0
	v_mfma_f32_16x16x32_bf16 v[90:93], v[2:5], v[58:61], 0
	v_mfma_f32_16x16x32_bf16 v[94:97], v[10:13], v[58:61], 0
	s_setprio 0
	s_setprio 1
	v_mfma_f32_16x16x32_bf16 v[66:69], v[6:9], v[38:41], v[66:69]
	v_mfma_f32_16x16x32_bf16 v[70:73], v[14:17], v[38:41], v[70:73]
	v_mfma_f32_16x16x32_bf16 v[74:77], v[6:9], v[46:49], v[74:77]
	v_mfma_f32_16x16x32_bf16 v[78:81], v[14:17], v[46:49], v[78:81]
	v_mfma_f32_16x16x32_bf16 v[82:85], v[6:9], v[54:57], v[82:85]
	v_mfma_f32_16x16x32_bf16 v[86:89], v[14:17], v[54:57], v[86:89]
	v_mfma_f32_16x16x32_bf16 v[90:93], v[6:9], v[62:65], v[90:93]
	v_mfma_f32_16x16x32_bf16 v[94:97], v[14:17], v[62:65], v[94:97]
	s_setprio 0
	s_setprio 1
	v_mfma_f32_16x16x32_bf16 v[98:101], v[18:21], v[34:37], 0
	v_mfma_f32_16x16x32_bf16 v[34:37], v[26:29], v[34:37], 0
	v_mfma_f32_16x16x32_bf16 v[98:101], v[22:25], v[38:41], v[98:101]
	v_mfma_f32_16x16x32_bf16 v[34:37], v[30:33], v[38:41], v[34:37]
	v_mfma_f32_16x16x32_bf16 v[38:41], v[18:21], v[42:45], 0
	v_mfma_f32_16x16x32_bf16 v[42:45], v[26:29], v[42:45], 0
	v_mfma_f32_16x16x32_bf16 v[38:41], v[22:25], v[46:49], v[38:41]
	v_mfma_f32_16x16x32_bf16 v[42:45], v[30:33], v[46:49], v[42:45]
	s_setprio 0
	s_setprio 1
	v_mfma_f32_16x16x32_bf16 v[46:49], v[18:21], v[50:53], 0
	v_mfma_f32_16x16x32_bf16 v[50:53], v[26:29], v[50:53], 0
	v_mfma_f32_16x16x32_bf16 v[46:49], v[22:25], v[54:57], v[46:49]
	v_mfma_f32_16x16x32_bf16 v[50:53], v[30:33], v[54:57], v[50:53]
	v_mfma_f32_16x16x32_bf16 v[54:57], v[18:21], v[58:61], 0
	v_mfma_f32_16x16x32_bf16 v[58:61], v[26:29], v[58:61], 0
	v_mfma_f32_16x16x32_bf16 v[54:57], v[22:25], v[62:65], v[54:57]
	v_mfma_f32_16x16x32_bf16 v[58:61], v[30:33], v[62:65], v[58:61]
	s_setprio 0
	s_barrier
	s_add_i32 s54, s48, s41
	v_lshl_add_u64 v[210:211], s[30:31], 0, v[132:133]
	s_add_i32 s21, s54, 0x2000
	v_lshl_add_u64 v[142:143], v[210:211], 0, s[12:13]
	s_mov_b32 m0, s54
	v_lshl_add_u64 v[212:213], s[30:31], 0, v[136:137]
	s_add_u32 s58, s30, 0x10100
	ds_read_b128 v[62:65], v148 offset:16384
	ds_read_b128 v[102:105], v148 offset:17408
	ds_read_b128 v[106:109], v148 offset:18432
	ds_read_b128 v[110:113], v148 offset:19456
	ds_read_b128 v[114:117], v148 offset:20480
	ds_read_b128 v[118:121], v148 offset:21504
	ds_read_b128 v[122:125], v148 offset:22528
	ds_read_b128 v[126:129], v148 offset:23552
	global_load_lds_dwordx4 v[142:143], off
	v_lshl_add_u64 v[142:143], v[212:213], 0, s[12:13]
	s_mov_b32 m0, s21
	s_addc_u32 s59, s31, 0
	s_add_i32 s52, s49, s41
	global_load_lds_dwordx4 v[142:143], off
	v_lshl_add_u64 v[142:143], s[58:59], 0, v[132:133]
	s_mov_b32 m0, s52
	s_add_i32 s53, s52, 0x2000
	global_load_lds_dwordx4 v[142:143], off
	v_lshl_add_u64 v[142:143], s[58:59], 0, v[136:137]
	s_mov_b32 m0, s53
	v_lshl_add_u64 v[214:215], s[28:29], 0, v[130:131]
	global_load_lds_dwordx4 v[142:143], off
	v_lshl_add_u64 v[142:143], v[214:215], 0, s[12:13]
	s_mov_b32 m0, s27
	v_lshl_add_u64 v[216:217], s[28:29], 0, v[134:135]
	global_load_lds_dwordx4 v[142:143], off
	v_lshl_add_u64 v[142:143], v[216:217], 0, s[12:13]
	s_mov_b32 m0, s42
	s_nop 0
	global_load_lds_dwordx4 v[142:143], off
	s_waitcnt vmcnt(8)
	s_waitcnt lgkmcnt(0)
	s_barrier
; #define PG8_STAGE(bufoff, gbase, voff) do { _Pragma("unroll") for (int _i = 0; _i < 2; ++_i) \
;         __builtin_amdgcn_global_load_lds((const unsigned*)((const char*)(gbase) + (voff)[_i]), (PG8_LAS unsigned*)(lds + (bufoff) + ldsw + _i * 8192), 16, 0, 0); } while (0)
; #define PG8_LDA(dst, b, h) do { _Pragma("unroll") for (int m = 0; m < 4; ++m) _Pragma("unroll") for (int k = 0; k < 2; ++k) dst[m][k] = *(const PG8_LAS bf16x8*)(lds + PG8_SA(b, h) + aoff + m * 2048 + k * 1024); } while (0)
; #define PG8_LDB(dst, b, h) do { _Pragma("unroll") for (int n = 0; n < 2; ++n) _Pragma("unroll") for (int k = 0; k < 2; ++k) dst[n][k] = *(const PG8_LAS bf16x8*)(lds + PG8_SB(b, h) + boff + n * 2048 + k * 1024); } while (0)
; #define PG8_MMA(ai, bj, At, Bt) do { __builtin_amdgcn_s_setprio(1); _Pragma("unroll") for (int m = 0; m < 4; ++m) _Pragma("unroll") for (int n = 0; n < 2; ++n) _Pragma("unroll") for (int k = 0; k < 2; ++k) \
;         acc[ai][bj][m][n] = mma_<I8>(Bt[n][k], At[m][k], acc[ai][bj][m][n]); __builtin_amdgcn_s_setprio(0); } while (0)
; #define PG8_WAIT_V(n) asm volatile("s_waitcnt vmcnt(" #n ")" ::: "memory")
; template <class Epi, class Sched, bool ALIGN_EPI = false, bool SP2 = false, bool I8 = false>
; __device__ __forceinline__ void gemm_phase(PG8_LAS unsigned char* lds, const Gemm g, const Sched& S, const Epi& E) {
;     ...
;             PG8_LDB(B0, 0, 0); PG8_LDB(B1, 0, 1); PG8_SCHED; PG8_LDA(At, 0, 0); PG8_STAGE(PG8_SA(1, 1), a1 + hstepA, voffA);
;             PG8_WAIT_V(8); PG8_WAIT_L(0); PG8_BAR; PG8_MMA(0, 0, At, B0); PG8_MMA(0, 1, At, B1); PG8_BAR; PG8_SCHED;
;             PG8_LDA(At, 0, 1); PG8_STAGE(PG8_SB(0, 0), b2, voffB); PG8_STAGE(PG8_SB(0, 1), b2 + hstepB, voffB); PG8_STAGE(PG8_SA(0, 0), a2, voffA);
;             PG8_WAIT_V(8); PG8_WAIT_L(0); PG8_BAR; PG8_MMA(1, 0, At, B0); PG8_MMA(1, 1, At, B1); PG8_BAR; PG8_SCHED;
;             PG8_LDB(B0, 1, 0); PG8_LDB(B1, 1, 1); PG8_SCHED; PG8_LDA(At, 1, 0); PG8_STAGE(PG8_SA(0, 1), a2 + hstepA, voffA);
;             PG8_WAIT_V(8); PG8_WAIT_L(0); PG8_BAR; PG8_MMA(0, 0, At, B0); PG8_MMA(0, 1, At, B1); PG8_BAR; PG8_SCHED;
;             PG8_LDA(At, 1, 1); PG8_STAGE(PG8_SB(1, 0), b3, voffB); PG8_STAGE(PG8_SB(1, 1), b3 + hstepB, voffB); PG8_STAGE(PG8_SA(1, 0), a3, voffA);
;             PG8_WAIT_V(8); PG8_WAIT_L(0); PG8_BAR; PG8_MMA(1, 0, At, B0); PG8_MMA(1, 1, At, B1); PG8_BAR; PG8_SCHED;
	s_setprio 1
	s_waitcnt lgkmcnt(0)
	v_mfma_f32_16x16x32_bf16 v[142:145], v[2:5], v[62:65], 0
	v_mfma_f32_16x16x32_bf16 v[154:157], v[2:5], v[106:109], 0
	v_mfma_f32_16x16x32_bf16 v[162:165], v[2:5], v[114:117], 0
	v_mfma_f32_16x16x32_bf16 v[2:5], v[2:5], v[122:125], 0
	v_mfma_f32_16x16x32_bf16 v[142:145], v[6:9], v[102:105], v[142:145]
	v_mfma_f32_16x16x32_bf16 v[154:157], v[6:9], v[110:113], v[154:157]
	v_mfma_f32_16x16x32_bf16 v[162:165], v[6:9], v[118:121], v[162:165]
	v_mfma_f32_16x16x32_bf16 v[2:5], v[6:9], v[126:129], v[2:5]
	s_setprio 0
	s_setprio 1
	v_mfma_f32_16x16x32_bf16 v[6:9], v[10:13], v[122:125], 0
	v_mfma_f32_16x16x32_bf16 v[150:153], v[10:13], v[62:65], 0
	v_mfma_f32_16x16x32_bf16 v[158:161], v[10:13], v[106:109], 0
	v_mfma_f32_16x16x32_bf16 v[166:169], v[10:13], v[114:117], 0
	v_mfma_f32_16x16x32_bf16 v[6:9], v[14:17], v[126:129], v[6:9]
	v_mfma_f32_16x16x32_bf16 v[150:153], v[14:17], v[102:105], v[150:153]
	v_mfma_f32_16x16x32_bf16 v[158:161], v[14:17], v[110:113], v[158:161]
	v_mfma_f32_16x16x32_bf16 v[166:169], v[14:17], v[118:121], v[166:169]
	s_setprio 0
	s_setprio 1
	v_mfma_f32_16x16x32_bf16 v[10:13], v[18:21], v[62:65], 0
	v_mfma_f32_16x16x32_bf16 v[14:17], v[26:29], v[62:65], 0
	v_mfma_f32_16x16x32_bf16 v[10:13], v[22:25], v[102:105], v[10:13]
	v_mfma_f32_16x16x32_bf16 v[14:17], v[30:33], v[102:105], v[14:17]
	v_mfma_f32_16x16x32_bf16 v[62:65], v[18:21], v[106:109], 0
	v_mfma_f32_16x16x32_bf16 v[102:105], v[26:29], v[106:109], 0
	v_mfma_f32_16x16x32_bf16 v[106:109], v[18:21], v[114:117], 0
	v_mfma_f32_16x16x32_bf16 v[18:21], v[18:21], v[122:125], 0
	s_setprio 0
	s_setprio 1
	v_mfma_f32_16x16x32_bf16 v[62:65], v[22:25], v[110:113], v[62:65]
	v_mfma_f32_16x16x32_bf16 v[102:105], v[30:33], v[110:113], v[102:105]
	v_mfma_f32_16x16x32_bf16 v[106:109], v[22:25], v[118:121], v[106:109]
	v_mfma_f32_16x16x32_bf16 v[110:113], v[26:29], v[114:117], 0
	v_mfma_f32_16x16x32_bf16 v[18:21], v[22:25], v[126:129], v[18:21]
	v_mfma_f32_16x16x32_bf16 v[22:25], v[26:29], v[122:125], 0
	v_mfma_f32_16x16x32_bf16 v[110:113], v[30:33], v[118:121], v[110:113]
	v_mfma_f32_16x16x32_bf16 v[22:25], v[30:33], v[126:129], v[22:25]
	s_setprio 0
	s_barrier
	s_add_i32 s57, 0, 0x18000
	s_add_i32 s60, 0, 0x1c000
	v_add_u32_e32 v149, s57, v1
	v_add_u32_e32 v230, s60, v1
	ds_read_b128 v[26:29], v149
	ds_read_b128 v[30:33], v149 offset:1024
	ds_read_b128 v[114:117], v149 offset:2048
	ds_read_b128 v[118:121], v149 offset:3072
	ds_read_b128 v[122:125], v230
	ds_read_b128 v[126:129], v230 offset:1024
	ds_read_b128 v[170:173], v230 offset:2048
	ds_read_b128 v[174:177], v230 offset:3072
	s_add_u32 s58, s28, 0x10100
	s_addc_u32 s59, s29, 0
	s_mov_b32 m0, s43
	v_lshl_add_u64 v[218:219], s[58:59], 0, v[130:131]
	ds_read_b128 v[178:181], v148 offset:32768
	ds_read_b128 v[182:185], v148 offset:33792
	ds_read_b128 v[186:189], v148 offset:34816
	ds_read_b128 v[190:193], v148 offset:35840
	ds_read_b128 v[194:197], v148 offset:36864
	ds_read_b128 v[198:201], v148 offset:37888
	ds_read_b128 v[202:205], v148 offset:38912
	ds_read_b128 v[206:209], v148 offset:39936
	global_load_lds_dwordx4 v[218:219], off
	v_lshl_add_u64 v[218:219], s[58:59], 0, v[134:135]
	s_mov_b32 m0, s44
	s_nop 0
	global_load_lds_dwordx4 v[218:219], off
	s_waitcnt vmcnt(8)
	s_waitcnt lgkmcnt(0)
	s_barrier
	s_setprio 1
	s_waitcnt lgkmcnt(0)
	v_mfma_f32_16x16x32_bf16 v[66:69], v[26:29], v[178:181], v[66:69]
	v_mfma_f32_16x16x32_bf16 v[70:73], v[114:117], v[178:181], v[70:73]
	v_mfma_f32_16x16x32_bf16 v[74:77], v[26:29], v[186:189], v[74:77]
	v_mfma_f32_16x16x32_bf16 v[78:81], v[114:117], v[186:189], v[78:81]
	v_mfma_f32_16x16x32_bf16 v[82:85], v[26:29], v[194:197], v[82:85]
	v_mfma_f32_16x16x32_bf16 v[86:89], v[114:117], v[194:197], v[86:89]
	v_mfma_f32_16x16x32_bf16 v[90:93], v[26:29], v[202:205], v[90:93]
	v_mfma_f32_16x16x32_bf16 v[94:97], v[114:117], v[202:205], v[94:97]
	s_setprio 0
	s_setprio 1
	v_mfma_f32_16x16x32_bf16 v[66:69], v[30:33], v[182:185], v[66:69]
	v_mfma_f32_16x16x32_bf16 v[70:73], v[118:121], v[182:185], v[70:73]
	v_mfma_f32_16x16x32_bf16 v[74:77], v[30:33], v[190:193], v[74:77]
	v_mfma_f32_16x16x32_bf16 v[78:81], v[118:121], v[190:193], v[78:81]
	v_mfma_f32_16x16x32_bf16 v[82:85], v[30:33], v[198:201], v[82:85]
	v_mfma_f32_16x16x32_bf16 v[86:89], v[118:121], v[198:201], v[86:89]
	v_mfma_f32_16x16x32_bf16 v[90:93], v[30:33], v[206:209], v[90:93]
	v_mfma_f32_16x16x32_bf16 v[94:97], v[118:121], v[206:209], v[94:97]
	s_setprio 0
	s_setprio 1
	v_mfma_f32_16x16x32_bf16 v[98:101], v[122:125], v[178:181], v[98:101]
	v_mfma_f32_16x16x32_bf16 v[34:37], v[170:173], v[178:181], v[34:37]
	v_mfma_f32_16x16x32_bf16 v[38:41], v[122:125], v[186:189], v[38:41]
	v_mfma_f32_16x16x32_bf16 v[42:45], v[170:173], v[186:189], v[42:45]
	v_mfma_f32_16x16x32_bf16 v[46:49], v[122:125], v[194:197], v[46:49]
	v_mfma_f32_16x16x32_bf16 v[50:53], v[170:173], v[194:197], v[50:53]
	v_mfma_f32_16x16x32_bf16 v[54:57], v[122:125], v[202:205], v[54:57]
	v_mfma_f32_16x16x32_bf16 v[58:61], v[170:173], v[202:205], v[58:61]
	s_setprio 0
	s_setprio 1
	v_mfma_f32_16x16x32_bf16 v[98:101], v[126:129], v[182:185], v[98:101]
	v_mfma_f32_16x16x32_bf16 v[34:37], v[174:177], v[182:185], v[34:37]
	v_mfma_f32_16x16x32_bf16 v[38:41], v[126:129], v[190:193], v[38:41]
	v_mfma_f32_16x16x32_bf16 v[42:45], v[174:177], v[190:193], v[42:45]
	v_mfma_f32_16x16x32_bf16 v[46:49], v[126:129], v[198:201], v[46:49]
	v_mfma_f32_16x16x32_bf16 v[50:53], v[174:177], v[198:201], v[50:53]
	v_mfma_f32_16x16x32_bf16 v[54:57], v[126:129], v[206:209], v[54:57]
	v_mfma_f32_16x16x32_bf16 v[58:61], v[174:177], v[206:209], v[58:61]
	s_setprio 0
	s_barrier
; #define PG8_STAGE(bufoff, gbase, voff) do { _Pragma("unroll") for (int _i = 0; _i < 2; ++_i) \
;         __builtin_amdgcn_global_load_lds((const unsigned*)((const char*)(gbase) + (voff)[_i]), (PG8_LAS unsigned*)(lds + (bufoff) + ldsw + _i * 8192), 16, 0, 0); } while (0)
; #define PG8_LDA(dst, b, h) do { _Pragma("unroll") for (int m = 0; m < 4; ++m) _Pragma("unroll") for (int k = 0; k < 2; ++k) dst[m][k] = *(const PG8_LAS bf16x8*)(lds + PG8_SA(b, h) + aoff + m * 2048 + k * 1024); } while (0)
; #define PG8_LDB(dst, b, h) do { _Pragma("unroll") for (int n = 0; n < 2; ++n) _Pragma("unroll") for (int k = 0; k < 2; ++k) dst[n][k] = *(const PG8_LAS bf16x8*)(lds + PG8_SB(b, h) + boff + n * 2048 + k * 1024); } while (0)
; #define PG8_MMA(ai, bj, At, Bt) do { __builtin_amdgcn_s_setprio(1); _Pragma("unroll") for (int m = 0; m < 4; ++m) _Pragma("unroll") for (int n = 0; n < 2; ++n) _Pragma("unroll") for (int k = 0; k < 2; ++k) \
;         acc[ai][bj][m][n] = mma_<I8>(Bt[n][k], At[m][k], acc[ai][bj][m][n]); __builtin_amdgcn_s_setprio(0); } while (0)
; #define PG8_WAIT_V(n) asm volatile("s_waitcnt vmcnt(" #n ")" ::: "memory")
; template <class Epi, class Sched, bool ALIGN_EPI = false, bool SP2 = false, bool I8 = false>
; __device__ __forceinline__ void gemm_phase(PG8_LAS unsigned char* lds, const Gemm g, const Sched& S, const Epi& E) {
;     ...
;             PG8_LDB(B0, 0, 0); PG8_LDB(B1, 0, 1); PG8_SCHED; PG8_LDA(At, 0, 0); PG8_STAGE(PG8_SA(1, 1), a1 + hstepA, voffA);
;             PG8_WAIT_V(8); PG8_WAIT_L(0); PG8_BAR; PG8_MMA(0, 0, At, B0); PG8_MMA(0, 1, At, B1); PG8_BAR; PG8_SCHED;
;             PG8_LDA(At, 0, 1); PG8_STAGE(PG8_SB(0, 0), b2, voffB); PG8_STAGE(PG8_SB(0, 1), b2 + hstepB, voffB); PG8_STAGE(PG8_SA(0, 0), a2, voffA);
;             PG8_WAIT_V(8); PG8_WAIT_L(0); PG8_BAR; PG8_MMA(1, 0, At, B0); PG8_MMA(1, 1, At, B1); PG8_BAR; PG8_SCHED;
;             PG8_LDB(B0, 1, 0); PG8_LDB(B1, 1, 1); PG8_SCHED; PG8_LDA(At, 1, 0); PG8_STAGE(PG8_SA(0, 1), a2 + hstepA, voffA);
;             PG8_WAIT_V(8); PG8_WAIT_L(0); PG8_BAR; PG8_MMA(0, 0, At, B0); PG8_MMA(0, 1, At, B1); PG8_BAR; PG8_SCHED;
;             PG8_LDA(At, 1, 1); PG8_STAGE(PG8_SB(1, 0), b3, voffB); PG8_STAGE(PG8_SB(1, 1), b3 + hstepB, voffB); PG8_STAGE(PG8_SA(1, 0), a3, voffA);
;             PG8_WAIT_V(8); PG8_WAIT_L(0); PG8_BAR; PG8_MMA(1, 0, At, B0); PG8_MMA(1, 1, At, B1); PG8_BAR; PG8_SCHED;
	s_add_i32 s57, s57, s41
	s_add_i32 s55, s57, 0x2000
	v_lshl_add_u64 v[210:211], v[210:211], 0, s[14:15]
	s_mov_b32 m0, s57
	s_add_u32 s58, s30, 0x10180
	ds_read_b128 v[178:181], v148 offset:49152
	ds_read_b128 v[182:185], v148 offset:50176
	ds_read_b128 v[186:189], v148 offset:51200
	ds_read_b128 v[190:193], v148 offset:52224
	ds_read_b128 v[194:197], v148 offset:53248
	ds_read_b128 v[198:201], v148 offset:54272
	ds_read_b128 v[202:205], v148 offset:55296
	ds_read_b128 v[206:209], v148 offset:56320
	global_load_lds_dwordx4 v[210:211], off
	v_lshl_add_u64 v[210:211], v[212:213], 0, s[14:15]
	s_mov_b32 m0, s55
	s_addc_u32 s59, s31, 0
	s_add_i32 s30, s60, s41
	global_load_lds_dwordx4 v[210:211], off
	v_lshl_add_u64 v[210:211], s[58:59], 0, v[132:133]
	s_mov_b32 m0, s30
	s_add_i32 s31, s30, 0x2000
	global_load_lds_dwordx4 v[210:211], off
	v_lshl_add_u64 v[210:211], s[58:59], 0, v[136:137]
	s_mov_b32 m0, s31
	s_nop 0
	global_load_lds_dwordx4 v[210:211], off
	v_lshl_add_u64 v[210:211], v[214:215], 0, s[14:15]
	s_mov_b32 m0, s45
	s_nop 0
	global_load_lds_dwordx4 v[210:211], off
	v_lshl_add_u64 v[210:211], v[216:217], 0, s[14:15]
	s_mov_b32 m0, s46
	s_nop 0
	global_load_lds_dwordx4 v[210:211], off
	s_waitcnt vmcnt(8)
	s_waitcnt lgkmcnt(0)
	s_barrier
	s_setprio 1
	s_waitcnt lgkmcnt(0)
	v_mfma_f32_16x16x32_bf16 v[2:5], v[26:29], v[202:205], v[2:5]
	v_mfma_f32_16x16x32_bf16 v[6:9], v[114:117], v[202:205], v[6:9]
	v_mfma_f32_16x16x32_bf16 v[142:145], v[26:29], v[178:181], v[142:145]
	v_mfma_f32_16x16x32_bf16 v[150:153], v[114:117], v[178:181], v[150:153]
	v_mfma_f32_16x16x32_bf16 v[154:157], v[26:29], v[186:189], v[154:157]
	v_mfma_f32_16x16x32_bf16 v[158:161], v[114:117], v[186:189], v[158:161]
	v_mfma_f32_16x16x32_bf16 v[162:165], v[26:29], v[194:197], v[162:165]
	v_mfma_f32_16x16x32_bf16 v[166:169], v[114:117], v[194:197], v[166:169]
	s_setprio 0
	s_setprio 1
	v_mfma_f32_16x16x32_bf16 v[2:5], v[30:33], v[206:209], v[2:5]
	v_mfma_f32_16x16x32_bf16 v[6:9], v[118:121], v[206:209], v[6:9]
	v_mfma_f32_16x16x32_bf16 v[142:145], v[30:33], v[182:185], v[142:145]
	v_mfma_f32_16x16x32_bf16 v[150:153], v[118:121], v[182:185], v[150:153]
	v_mfma_f32_16x16x32_bf16 v[154:157], v[30:33], v[190:193], v[154:157]
	v_mfma_f32_16x16x32_bf16 v[158:161], v[118:121], v[190:193], v[158:161]
	v_mfma_f32_16x16x32_bf16 v[162:165], v[30:33], v[198:201], v[162:165]
	v_mfma_f32_16x16x32_bf16 v[166:169], v[118:121], v[198:201], v[166:169]
	s_setprio 0
	s_setprio 1
	v_mfma_f32_16x16x32_bf16 v[10:13], v[122:125], v[178:181], v[10:13]
	v_mfma_f32_16x16x32_bf16 v[14:17], v[170:173], v[178:181], v[14:17]
	v_mfma_f32_16x16x32_bf16 v[26:29], v[122:125], v[186:189], v[62:65]
	v_mfma_f32_16x16x32_bf16 v[30:33], v[170:173], v[186:189], v[102:105]
	v_mfma_f32_16x16x32_bf16 v[62:65], v[122:125], v[194:197], v[106:109]
	v_mfma_f32_16x16x32_bf16 v[102:105], v[170:173], v[194:197], v[110:113]
	v_mfma_f32_16x16x32_bf16 v[18:21], v[122:125], v[202:205], v[18:21]
	v_mfma_f32_16x16x32_bf16 v[22:25], v[170:173], v[202:205], v[22:25]
	s_setprio 0
	s_setprio 1
	v_mfma_f32_16x16x32_bf16 v[10:13], v[126:129], v[182:185], v[10:13]
	v_mfma_f32_16x16x32_bf16 v[14:17], v[174:177], v[182:185], v[14:17]
	v_mfma_f32_16x16x32_bf16 v[26:29], v[126:129], v[190:193], v[26:29]
	v_mfma_f32_16x16x32_bf16 v[30:33], v[174:177], v[190:193], v[30:33]
	v_mfma_f32_16x16x32_bf16 v[62:65], v[126:129], v[198:201], v[62:65]
	v_mfma_f32_16x16x32_bf16 v[102:105], v[174:177], v[198:201], v[102:105]
	v_mfma_f32_16x16x32_bf16 v[18:21], v[126:129], v[206:209], v[18:21]
	v_mfma_f32_16x16x32_bf16 v[22:25], v[174:177], v[206:209], v[22:25]
	s_setprio 0
	s_barrier
	ds_read_b128 v[106:109], v146
	ds_read_b128 v[110:113], v146 offset:1024
	ds_read_b128 v[114:117], v146 offset:2048
	ds_read_b128 v[118:121], v146 offset:3072
	ds_read_b128 v[122:125], v147
	ds_read_b128 v[126:129], v147 offset:1024
	ds_read_b128 v[170:173], v147 offset:2048
	ds_read_b128 v[174:177], v147 offset:3072
	s_add_u32 s28, s28, 0x10180
	s_addc_u32 s29, s29, 0
	s_mov_b32 m0, s56
	v_lshl_add_u64 v[210:211], s[28:29], 0, v[130:131]
	ds_read_b128 v[178:181], v148
	ds_read_b128 v[182:185], v148 offset:1024
	ds_read_b128 v[186:189], v148 offset:2048
	ds_read_b128 v[190:193], v148 offset:3072
	ds_read_b128 v[194:197], v148 offset:4096
	ds_read_b128 v[198:201], v148 offset:5120
	ds_read_b128 v[202:205], v148 offset:6144
	ds_read_b128 v[206:209], v148 offset:7168
	global_load_lds_dwordx4 v[210:211], off
	v_lshl_add_u64 v[210:211], s[28:29], 0, v[134:135]
	s_mov_b32 m0, s19
	s_nop 0
	global_load_lds_dwordx4 v[210:211], off
	s_waitcnt vmcnt(8)
	s_waitcnt lgkmcnt(0)
	s_barrier
; #define PG8_STAGE(bufoff, gbase, voff) do { _Pragma("unroll") for (int _i = 0; _i < 2; ++_i) \
;         __builtin_amdgcn_global_load_lds((const unsigned*)((const char*)(gbase) + (voff)[_i]), (PG8_LAS unsigned*)(lds + (bufoff) + ldsw + _i * 8192), 16, 0, 0); } while (0)
; #define PG8_LDA(dst, b, h) do { _Pragma("unroll") for (int m = 0; m < 4; ++m) _Pragma("unroll") for (int k = 0; k < 2; ++k) dst[m][k] = *(const PG8_LAS bf16x8*)(lds + PG8_SA(b, h) + aoff + m * 2048 + k * 1024); } while (0)
; #define PG8_LDB(dst, b, h) do { _Pragma("unroll") for (int n = 0; n < 2; ++n) _Pragma("unroll") for (int k = 0; k < 2; ++k) dst[n][k] = *(const PG8_LAS bf16x8*)(lds + PG8_SB(b, h) + boff + n * 2048 + k * 1024); } while (0)
; #define PG8_MMA(ai, bj, At, Bt) do { __builtin_amdgcn_s_setprio(1); _Pragma("unroll") for (int m = 0; m < 4; ++m) _Pragma("unroll") for (int n = 0; n < 2; ++n) _Pragma("unroll") for (int k = 0; k < 2; ++k) \
;         acc[ai][bj][m][n] = mma_<I8>(Bt[n][k], At[m][k], acc[ai][bj][m][n]); __builtin_amdgcn_s_setprio(0); } while (0)
; #define PG8_WAIT_V(n) asm volatile("s_waitcnt vmcnt(" #n ")" ::: "memory")
; template <class Epi, class Sched, bool ALIGN_EPI = false, bool SP2 = false, bool I8 = false>
; __device__ __forceinline__ void gemm_phase(PG8_LAS unsigned char* lds, const Gemm g, const Sched& S, const Epi& E) {
;     ...
;             PG8_LDB(B0, 0, 0); PG8_LDB(B1, 0, 1); PG8_SCHED; PG8_LDA(At, 0, 0); PG8_STAGE(PG8_SA(1, 1), a1 + hstepA, voffA);
;             PG8_WAIT_V(8); PG8_WAIT_L(0); PG8_BAR; PG8_MMA(0, 0, At, B0); PG8_MMA(0, 1, At, B1); PG8_BAR; PG8_SCHED;
;             PG8_LDA(At, 0, 1); PG8_STAGE(PG8_SB(0, 0), b2, voffB); PG8_STAGE(PG8_SB(0, 1), b2 + hstepB, voffB); PG8_STAGE(PG8_SA(0, 0), a2, voffA);
;             PG8_WAIT_V(8); PG8_WAIT_L(0); PG8_BAR; PG8_MMA(1, 0, At, B0); PG8_MMA(1, 1, At, B1); PG8_BAR; PG8_SCHED;
;             PG8_LDB(B0, 1, 0); PG8_LDB(B1, 1, 1); PG8_SCHED; PG8_LDA(At, 1, 0); PG8_STAGE(PG8_SA(0, 1), a2 + hstepA, voffA);
;             PG8_WAIT_V(8); PG8_WAIT_L(0); PG8_BAR; PG8_MMA(0, 0, At, B0); PG8_MMA(0, 1, At, B1); PG8_BAR; PG8_SCHED;
;             PG8_LDA(At, 1, 1); PG8_STAGE(PG8_SB(1, 0), b3, voffB); PG8_STAGE(PG8_SB(1, 1), b3 + hstepB, voffB); PG8_STAGE(PG8_SA(1, 0), a3, voffA);
;             PG8_WAIT_V(8); PG8_WAIT_L(0); PG8_BAR; PG8_MMA(1, 0, At, B0); PG8_MMA(1, 1, At, B1); PG8_BAR; PG8_SCHED;
	s_setprio 1
	s_waitcnt lgkmcnt(0)
	v_mfma_f32_16x16x32_bf16 v[90:93], v[106:109], v[202:205], v[90:93]
	v_mfma_f32_16x16x32_bf16 v[66:69], v[106:109], v[178:181], v[66:69]
	v_mfma_f32_16x16x32_bf16 v[70:73], v[114:117], v[178:181], v[70:73]
	v_mfma_f32_16x16x32_bf16 v[74:77], v[106:109], v[186:189], v[74:77]
	v_mfma_f32_16x16x32_bf16 v[78:81], v[114:117], v[186:189], v[78:81]
	v_mfma_f32_16x16x32_bf16 v[82:85], v[106:109], v[194:197], v[82:85]
	v_mfma_f32_16x16x32_bf16 v[86:89], v[114:117], v[194:197], v[86:89]
	v_mfma_f32_16x16x32_bf16 v[210:213], v[110:113], v[206:209], v[90:93]
	s_setprio 0
	s_setprio 1
	v_mfma_f32_16x16x32_bf16 v[90:93], v[114:117], v[202:205], v[94:97]
	v_mfma_f32_16x16x32_bf16 v[66:69], v[110:113], v[182:185], v[66:69]
	v_mfma_f32_16x16x32_bf16 v[70:73], v[118:121], v[182:185], v[70:73]
	v_mfma_f32_16x16x32_bf16 v[74:77], v[110:113], v[190:193], v[74:77]
	v_mfma_f32_16x16x32_bf16 v[78:81], v[118:121], v[190:193], v[78:81]
	v_mfma_f32_16x16x32_bf16 v[82:85], v[110:113], v[198:201], v[82:85]
	v_mfma_f32_16x16x32_bf16 v[86:89], v[118:121], v[198:201], v[86:89]
	v_mfma_f32_16x16x32_bf16 v[94:97], v[118:121], v[206:209], v[90:93]
	s_setprio 0
	s_setprio 1
	v_mfma_f32_16x16x32_bf16 v[50:53], v[170:173], v[194:197], v[50:53]
	v_mfma_f32_16x16x32_bf16 v[90:93], v[122:125], v[178:181], v[98:101]
	v_mfma_f32_16x16x32_bf16 v[34:37], v[170:173], v[178:181], v[34:37]
	v_mfma_f32_16x16x32_bf16 v[38:41], v[122:125], v[186:189], v[38:41]
	v_mfma_f32_16x16x32_bf16 v[42:45], v[170:173], v[186:189], v[42:45]
	v_mfma_f32_16x16x32_bf16 v[46:49], v[122:125], v[194:197], v[46:49]
	v_mfma_f32_16x16x32_bf16 v[178:181], v[174:177], v[198:201], v[50:53]
	v_mfma_f32_16x16x32_bf16 v[50:53], v[122:125], v[202:205], v[54:57]
	s_setprio 0
	s_setprio 1
	v_mfma_f32_16x16x32_bf16 v[34:37], v[174:177], v[182:185], v[34:37]
	v_mfma_f32_16x16x32_bf16 v[38:41], v[126:129], v[190:193], v[38:41]
	v_mfma_f32_16x16x32_bf16 v[42:45], v[174:177], v[190:193], v[42:45]
	v_mfma_f32_16x16x32_bf16 v[46:49], v[126:129], v[198:201], v[46:49]
	v_mfma_f32_16x16x32_bf16 v[54:57], v[126:129], v[206:209], v[50:53]
	v_mfma_f32_16x16x32_bf16 v[50:53], v[170:173], v[202:205], v[58:61]
	v_mfma_f32_16x16x32_bf16 v[214:217], v[126:129], v[182:185], v[90:93]
	v_mfma_f32_16x16x32_bf16 v[182:185], v[174:177], v[206:209], v[50:53]
	s_setprio 0
	s_barrier
	s_mov_b32 m0, s54
	v_lshl_add_u64 v[250:251], s[34:35], 0, v[132:133]
	s_add_u32 s28, s34, 0x10000
	s_nop 0
	ds_read_b128 v[50:53], v148 offset:16384
	ds_read_b128 v[58:61], v148 offset:17408
	ds_read_b128 v[90:93], v148 offset:18432
	ds_read_b128 v[98:101], v148 offset:19456
	ds_read_b128 v[186:189], v148 offset:20480
	ds_read_b128 v[190:193], v148 offset:21504
	ds_read_b128 v[194:197], v148 offset:22528
	ds_read_b128 v[198:201], v148 offset:23552
	global_load_lds_dwordx4 v[250:251], off
	v_lshl_add_u64 v[252:253], s[34:35], 0, v[136:137]
	s_mov_b32 m0, s21
	s_addc_u32 s29, s35, 0
	global_load_lds_dwordx4 v[252:253], off
	v_lshl_add_u64 v[202:203], s[28:29], 0, v[132:133]
	s_mov_b32 m0, s52
	v_lshl_add_u64 v[138:139], s[36:37], 0, v[130:131]
	global_load_lds_dwordx4 v[202:203], off
	v_lshl_add_u64 v[202:203], s[28:29], 0, v[136:137]
	s_mov_b32 m0, s53
	v_lshl_add_u64 v[140:141], s[36:37], 0, v[134:135]
	global_load_lds_dwordx4 v[202:203], off
	s_mov_b32 m0, s27
	s_nop 0
	global_load_lds_dwordx4 v[138:139], off
	s_mov_b32 m0, s42
	s_nop 0
	global_load_lds_dwordx4 v[140:141], off
	s_waitcnt vmcnt(8)
	s_waitcnt lgkmcnt(0)
	s_barrier
	s_setprio 1
	s_waitcnt lgkmcnt(0)
	v_mfma_f32_16x16x32_bf16 v[2:5], v[106:109], v[194:197], v[2:5]
	v_mfma_f32_16x16x32_bf16 v[6:9], v[114:117], v[194:197], v[6:9]
	v_mfma_f32_16x16x32_bf16 v[142:145], v[106:109], v[50:53], v[142:145]
	v_mfma_f32_16x16x32_bf16 v[150:153], v[114:117], v[50:53], v[150:153]
	v_mfma_f32_16x16x32_bf16 v[154:157], v[106:109], v[90:93], v[154:157]
	v_mfma_f32_16x16x32_bf16 v[158:161], v[114:117], v[90:93], v[158:161]
	v_mfma_f32_16x16x32_bf16 v[162:165], v[106:109], v[186:189], v[162:165]
	v_mfma_f32_16x16x32_bf16 v[166:169], v[114:117], v[186:189], v[166:169]
	s_setprio 0
	s_setprio 1
	v_mfma_f32_16x16x32_bf16 v[2:5], v[110:113], v[198:201], v[2:5]
	v_mfma_f32_16x16x32_bf16 v[6:9], v[118:121], v[198:201], v[6:9]
	v_mfma_f32_16x16x32_bf16 v[142:145], v[110:113], v[58:61], v[142:145]
	v_mfma_f32_16x16x32_bf16 v[150:153], v[118:121], v[58:61], v[150:153]
	v_mfma_f32_16x16x32_bf16 v[154:157], v[110:113], v[98:101], v[154:157]
	v_mfma_f32_16x16x32_bf16 v[158:161], v[118:121], v[98:101], v[158:161]
	v_mfma_f32_16x16x32_bf16 v[162:165], v[110:113], v[190:193], v[162:165]
	v_mfma_f32_16x16x32_bf16 v[166:169], v[118:121], v[190:193], v[166:169]
	s_setprio 0
	s_setprio 1
	v_mfma_f32_16x16x32_bf16 v[10:13], v[122:125], v[50:53], v[10:13]
	v_mfma_f32_16x16x32_bf16 v[202:205], v[126:129], v[58:61], v[10:13]
	v_mfma_f32_16x16x32_bf16 v[10:13], v[170:173], v[50:53], v[14:17]
	v_mfma_f32_16x16x32_bf16 v[14:17], v[174:177], v[58:61], v[10:13]
	v_mfma_f32_16x16x32_bf16 v[10:13], v[122:125], v[90:93], v[26:29]
	v_mfma_f32_16x16x32_bf16 v[206:209], v[126:129], v[98:101], v[10:13]
	v_mfma_f32_16x16x32_bf16 v[10:13], v[170:173], v[90:93], v[30:33]
	v_mfma_f32_16x16x32_bf16 v[30:33], v[174:177], v[98:101], v[10:13]
	s_setprio 0
	s_setprio 1
	v_mfma_f32_16x16x32_bf16 v[10:13], v[122:125], v[186:189], v[62:65]
	v_mfma_f32_16x16x32_bf16 v[218:221], v[126:129], v[190:193], v[10:13]
	v_mfma_f32_16x16x32_bf16 v[10:13], v[170:173], v[186:189], v[102:105]
	v_mfma_f32_16x16x32_bf16 v[186:189], v[174:177], v[190:193], v[10:13]
	v_mfma_f32_16x16x32_bf16 v[10:13], v[122:125], v[194:197], v[18:21]
	v_mfma_f32_16x16x32_bf16 v[190:193], v[126:129], v[198:201], v[10:13]
	v_mfma_f32_16x16x32_bf16 v[10:13], v[170:173], v[194:197], v[22:25]
	v_mfma_f32_16x16x32_bf16 v[170:173], v[174:177], v[198:201], v[10:13]
	s_setprio 0
	s_barrier
; #define PG8_STAGE(bufoff, gbase, voff) do { _Pragma("unroll") for (int _i = 0; _i < 2; ++_i) \
;         __builtin_amdgcn_global_load_lds((const unsigned*)((const char*)(gbase) + (voff)[_i]), (PG8_LAS unsigned*)(lds + (bufoff) + ldsw + _i * 8192), 16, 0, 0); } while (0)
; #define PG8_LDA(dst, b, h) do { _Pragma("unroll") for (int m = 0; m < 4; ++m) _Pragma("unroll") for (int k = 0; k < 2; ++k) dst[m][k] = *(const PG8_LAS bf16x8*)(lds + PG8_SA(b, h) + aoff + m * 2048 + k * 1024); } while (0)
; #define PG8_LDB(dst, b, h) do { _Pragma("unroll") for (int n = 0; n < 2; ++n) _Pragma("unroll") for (int k = 0; k < 2; ++k) dst[n][k] = *(const PG8_LAS bf16x8*)(lds + PG8_SB(b, h) + boff + n * 2048 + k * 1024); } while (0)
; #define PG8_MMA(ai, bj, At, Bt) do { __builtin_amdgcn_s_setprio(1); _Pragma("unroll") for (int m = 0; m < 4; ++m) _Pragma("unroll") for (int n = 0; n < 2; ++n) _Pragma("unroll") for (int k = 0; k < 2; ++k) \
;         acc[ai][bj][m][n] = mma_<I8>(Bt[n][k], At[m][k], acc[ai][bj][m][n]); __builtin_amdgcn_s_setprio(0); } while (0)
; #define PG8_WAIT_V(n) asm volatile("s_waitcnt vmcnt(" #n ")" ::: "memory")
; template <class Epi, class Sched, bool ALIGN_EPI = false, bool SP2 = false, bool I8 = false>
; __device__ __forceinline__ void gemm_phase(PG8_LAS unsigned char* lds, const Gemm g, const Sched& S, const Epi& E) {
;     ...
;             PG8_LDB(B0, 0, 0); PG8_LDB(B1, 0, 1); PG8_SCHED; PG8_LDA(At, 0, 0); PG8_STAGE(PG8_SA(1, 1), a1 + hstepA, voffA);
;             PG8_WAIT_V(8); PG8_WAIT_L(0); PG8_BAR; PG8_MMA(0, 0, At, B0); PG8_MMA(0, 1, At, B1); PG8_BAR; PG8_SCHED;
;             PG8_LDA(At, 0, 1); PG8_STAGE(PG8_SB(0, 0), b2, voffB); PG8_STAGE(PG8_SB(0, 1), b2 + hstepB, voffB); PG8_STAGE(PG8_SA(0, 0), a2, voffA);
;             PG8_WAIT_V(8); PG8_WAIT_L(0); PG8_BAR; PG8_MMA(1, 0, At, B0); PG8_MMA(1, 1, At, B1); PG8_BAR; PG8_SCHED;
;             PG8_LDB(B0, 1, 0); PG8_LDB(B1, 1, 1); PG8_SCHED; PG8_LDA(At, 1, 0); PG8_STAGE(PG8_SA(0, 1), a2 + hstepA, voffA);
;             PG8_WAIT_V(8); PG8_WAIT_L(0); PG8_BAR; PG8_MMA(0, 0, At, B0); PG8_MMA(0, 1, At, B1); PG8_BAR; PG8_SCHED;
;             PG8_LDA(At, 1, 1); PG8_STAGE(PG8_SB(1, 0), b3, voffB); PG8_STAGE(PG8_SB(1, 1), b3 + hstepB, voffB); PG8_STAGE(PG8_SA(1, 0), a3, voffA);
;             PG8_WAIT_V(8); PG8_WAIT_L(0); PG8_BAR; PG8_MMA(1, 0, At, B0); PG8_MMA(1, 1, At, B1); PG8_BAR; PG8_SCHED;
	s_nop 4
	ds_read_b128 v[10:13], v149
	ds_read_b128 v[22:25], v149 offset:1024
	ds_read_b128 v[174:177], v149 offset:2048
	ds_read_b128 v[194:197], v149 offset:3072
	ds_read_b128 v[198:201], v230
	ds_read_b128 v[222:225], v230 offset:1024
	ds_read_b128 v[226:229], v230 offset:2048
	ds_read_b128 v[230:233], v230 offset:3072
	s_add_u32 s28, s36, 0x10000
	s_addc_u32 s29, s37, 0
	s_mov_b32 m0, s43
	v_lshl_add_u64 v[50:51], s[28:29], 0, v[130:131]
	ds_read_b128 v[18:21], v148 offset:32768
	ds_read_b128 v[26:29], v148 offset:33792
	ds_read_b128 v[62:65], v148 offset:34816
	ds_read_b128 v[102:105], v148 offset:35840
	ds_read_b128 v[234:237], v148 offset:36864
	ds_read_b128 v[238:241], v148 offset:37888
	ds_read_b128 v[242:245], v148 offset:38912
	ds_read_b128 v[246:249], v148 offset:39936
	global_load_lds_dwordx4 v[50:51], off
	v_lshl_add_u64 v[50:51], s[28:29], 0, v[134:135]
	s_mov_b32 m0, s44
	s_nop 0
	global_load_lds_dwordx4 v[50:51], off
	s_waitcnt vmcnt(8)
	s_waitcnt lgkmcnt(0)
	s_barrier
	s_setprio 1
	s_waitcnt lgkmcnt(0)
	v_mfma_f32_16x16x32_bf16 v[50:53], v[10:13], v[18:21], v[66:69]
	v_mfma_f32_16x16x32_bf16 v[122:125], v[22:25], v[26:29], v[50:53]
	v_mfma_f32_16x16x32_bf16 v[50:53], v[174:177], v[18:21], v[70:73]
	v_mfma_f32_16x16x32_bf16 v[114:117], v[194:197], v[26:29], v[50:53]
	v_mfma_f32_16x16x32_bf16 v[50:53], v[10:13], v[62:65], v[74:77]
	v_mfma_f32_16x16x32_bf16 v[106:109], v[22:25], v[102:105], v[50:53]
	v_mfma_f32_16x16x32_bf16 v[50:53], v[174:177], v[62:65], v[78:81]
	v_mfma_f32_16x16x32_bf16 v[98:101], v[194:197], v[102:105], v[50:53]
	s_setprio 0
	s_setprio 1
	v_mfma_f32_16x16x32_bf16 v[50:53], v[10:13], v[234:237], v[82:85]
	v_mfma_f32_16x16x32_bf16 v[90:93], v[22:25], v[238:241], v[50:53]
	v_mfma_f32_16x16x32_bf16 v[50:53], v[174:177], v[234:237], v[86:89]
	v_mfma_f32_16x16x32_bf16 v[82:85], v[194:197], v[238:241], v[50:53]
	v_mfma_f32_16x16x32_bf16 v[50:53], v[10:13], v[242:245], v[210:213]
	v_mfma_f32_16x16x32_bf16 v[58:61], v[22:25], v[246:249], v[50:53]
	v_mfma_f32_16x16x32_bf16 v[50:53], v[174:177], v[242:245], v[94:97]
	v_mfma_f32_16x16x32_bf16 v[50:53], v[194:197], v[246:249], v[50:53]
	s_setprio 0
	s_setprio 1
	v_mfma_f32_16x16x32_bf16 v[66:69], v[198:201], v[18:21], v[214:217]
	v_mfma_f32_16x16x32_bf16 v[18:21], v[226:229], v[18:21], v[34:37]
	v_mfma_f32_16x16x32_bf16 v[118:121], v[230:233], v[26:29], v[18:21]
	v_mfma_f32_16x16x32_bf16 v[18:21], v[198:201], v[62:65], v[38:41]
	v_mfma_f32_16x16x32_bf16 v[110:113], v[222:225], v[102:105], v[18:21]
	v_mfma_f32_16x16x32_bf16 v[18:21], v[226:229], v[62:65], v[42:45]
	v_mfma_f32_16x16x32_bf16 v[102:105], v[230:233], v[102:105], v[18:21]
	v_mfma_f32_16x16x32_bf16 v[18:21], v[198:201], v[234:237], v[46:49]
	s_setprio 0
	s_setprio 1
	v_mfma_f32_16x16x32_bf16 v[94:97], v[222:225], v[238:241], v[18:21]
	v_mfma_f32_16x16x32_bf16 v[18:21], v[226:229], v[234:237], v[178:181]
	v_mfma_f32_16x16x32_bf16 v[86:89], v[230:233], v[238:241], v[18:21]
	v_mfma_f32_16x16x32_bf16 v[18:21], v[198:201], v[242:245], v[54:57]
	v_mfma_f32_16x16x32_bf16 v[62:65], v[222:225], v[246:249], v[18:21]
	v_mfma_f32_16x16x32_bf16 v[18:21], v[226:229], v[242:245], v[182:185]
	v_mfma_f32_16x16x32_bf16 v[126:129], v[222:225], v[26:29], v[66:69]
	v_mfma_f32_16x16x32_bf16 v[54:57], v[230:233], v[246:249], v[18:21]
	s_setprio 0
	s_barrier
	s_mov_b32 m0, s57
	s_nop 2
	v_lshl_add_u64 v[18:19], v[250:251], 0, s[6:7]
	s_add_u32 s28, s34, 0x10080
	ds_read_b128 v[38:41], v148 offset:49152
	ds_read_b128 v[46:49], v148 offset:50176
	ds_read_b128 v[178:181], v148 offset:51200
	ds_read_b128 v[182:185], v148 offset:52224
	ds_read_b128 v[210:213], v148 offset:53248
	ds_read_b128 v[214:217], v148 offset:54272
	ds_read_b128 v[234:237], v148 offset:55296
	ds_read_b128 v[238:241], v148 offset:56320
	global_load_lds_dwordx4 v[18:19], off
	v_lshl_add_u64 v[18:19], v[252:253], 0, s[6:7]
	s_mov_b32 m0, s55
	s_addc_u32 s29, s35, 0
	global_load_lds_dwordx4 v[18:19], off
	v_lshl_add_u64 v[18:19], s[28:29], 0, v[132:133]
	s_mov_b32 m0, s30
	s_nop 0
	global_load_lds_dwordx4 v[18:19], off
	v_lshl_add_u64 v[18:19], s[28:29], 0, v[136:137]
	s_mov_b32 m0, s31
	s_nop 0
	global_load_lds_dwordx4 v[18:19], off
	v_lshl_add_u64 v[18:19], v[138:139], 0, s[6:7]
	s_mov_b32 m0, s45
	s_nop 0
	global_load_lds_dwordx4 v[18:19], off
	v_lshl_add_u64 v[18:19], v[140:141], 0, s[6:7]
	s_mov_b32 m0, s46
	s_nop 0
	global_load_lds_dwordx4 v[18:19], off
	s_waitcnt vmcnt(8)
	s_waitcnt lgkmcnt(0)
	s_barrier
	s_setprio 1
	s_waitcnt lgkmcnt(0)
	v_mfma_f32_16x16x32_bf16 v[18:21], v[10:13], v[38:41], v[142:145]
	v_mfma_f32_16x16x32_bf16 v[78:81], v[22:25], v[46:49], v[18:21]
	v_mfma_f32_16x16x32_bf16 v[18:21], v[174:177], v[38:41], v[150:153]
	v_mfma_f32_16x16x32_bf16 v[70:73], v[194:197], v[46:49], v[18:21]
	v_mfma_f32_16x16x32_bf16 v[18:21], v[10:13], v[178:181], v[154:157]
	v_mfma_f32_16x16x32_bf16 v[42:45], v[22:25], v[182:185], v[18:21]
	v_mfma_f32_16x16x32_bf16 v[18:21], v[174:177], v[178:181], v[158:161]
	v_mfma_f32_16x16x32_bf16 v[34:37], v[194:197], v[182:185], v[18:21]
	s_setprio 0
	s_setprio 1
	v_mfma_f32_16x16x32_bf16 v[18:21], v[10:13], v[210:213], v[162:165]
	v_mfma_f32_16x16x32_bf16 v[2:5], v[10:13], v[234:237], v[2:5]
	v_mfma_f32_16x16x32_bf16 v[26:29], v[22:25], v[214:217], v[18:21]
	v_mfma_f32_16x16x32_bf16 v[18:21], v[174:177], v[210:213], v[166:169]
	v_mfma_f32_16x16x32_bf16 v[10:13], v[22:25], v[238:241], v[2:5]
	v_mfma_f32_16x16x32_bf16 v[2:5], v[174:177], v[234:237], v[6:9]
	v_mfma_f32_16x16x32_bf16 v[18:21], v[194:197], v[214:217], v[18:21]
	v_mfma_f32_16x16x32_bf16 v[2:5], v[194:197], v[238:241], v[2:5]
	s_setprio 0
	s_setprio 1
	v_mfma_f32_16x16x32_bf16 v[6:9], v[198:201], v[38:41], v[202:205]
	v_mfma_f32_16x16x32_bf16 v[74:77], v[222:225], v[46:49], v[6:9]
	v_mfma_f32_16x16x32_bf16 v[6:9], v[226:229], v[38:41], v[14:17]
	v_mfma_f32_16x16x32_bf16 v[66:69], v[230:233], v[46:49], v[6:9]
	v_mfma_f32_16x16x32_bf16 v[6:9], v[198:201], v[178:181], v[206:209]
	v_mfma_f32_16x16x32_bf16 v[46:49], v[222:225], v[182:185], v[6:9]
	v_mfma_f32_16x16x32_bf16 v[6:9], v[226:229], v[178:181], v[30:33]
	v_mfma_f32_16x16x32_bf16 v[38:41], v[230:233], v[182:185], v[6:9]
	s_setprio 0
	s_setprio 1
	v_mfma_f32_16x16x32_bf16 v[6:9], v[198:201], v[210:213], v[218:221]
	v_mfma_f32_16x16x32_bf16 v[30:33], v[222:225], v[214:217], v[6:9]
	v_mfma_f32_16x16x32_bf16 v[6:9], v[226:229], v[210:213], v[186:189]
	v_mfma_f32_16x16x32_bf16 v[22:25], v[230:233], v[214:217], v[6:9]
	v_mfma_f32_16x16x32_bf16 v[6:9], v[198:201], v[234:237], v[190:193]
	v_mfma_f32_16x16x32_bf16 v[14:17], v[222:225], v[238:241], v[6:9]
	v_mfma_f32_16x16x32_bf16 v[6:9], v[226:229], v[234:237], v[170:173]
	v_mfma_f32_16x16x32_bf16 v[6:9], v[230:233], v[238:241], v[6:9]
	s_setprio 0
	s_barrier
	s_andn2_b64 vcc, exec, s[8:9]
	s_cbranch_vccnz .LBB0_2246
	s_barrier

; #define PG8_STAGE(bufoff, gbase, voff) do { _Pragma("unroll") for (int _i = 0; _i < 2; ++_i) \
;         __builtin_amdgcn_global_load_lds((const unsigned*)((const char*)(gbase) + (voff)[_i]), (PG8_LAS unsigned*)(lds + (bufoff) + ldsw + _i * 8192), 16, 0, 0); } while (0)
; #define PG8_LDA(dst, b, h) do { _Pragma("unroll") for (int m = 0; m < 4; ++m) _Pragma("unroll") for (int k = 0; k < 2; ++k) dst[m][k] = *(const PG8_LAS bf16x8*)(lds + PG8_SA(b, h) + aoff + m * 2048 + k * 1024); } while (0)
; #define PG8_LDB(dst, b, h) do { _Pragma("unroll") for (int n = 0; n < 2; ++n) _Pragma("unroll") for (int k = 0; k < 2; ++k) dst[n][k] = *(const PG8_LAS bf16x8*)(lds + PG8_SB(b, h) + boff + n * 2048 + k * 1024); } while (0)
; #define PG8_MMA(ai, bj, At, Bt) do { __builtin_amdgcn_s_setprio(1); _Pragma("unroll") for (int m = 0; m < 4; ++m) _Pragma("unroll") for (int n = 0; n < 2; ++n) _Pragma("unroll") for (int k = 0; k < 2; ++k) \
;         acc[ai][bj][m][n] = mma_<I8>(Bt[n][k], At[m][k], acc[ai][bj][m][n]); __builtin_amdgcn_s_setprio(0); } while (0)
; #define PG8_WAIT_V(n) asm volatile("s_waitcnt vmcnt(" #n ")" ::: "memory")
; #define PG8_WAIT_L(n) asm volatile("s_waitcnt lgkmcnt(" #n ")" ::: "memory")
; template <class Epi, class Sched, bool ALIGN_EPI = false, bool SP2 = false, bool I8 = false>
; __device__ __forceinline__ void gemm_phase(PG8_LAS unsigned char* lds, const Gemm g, const Sched& S, const Epi& E) {
;     ...
;         for (int t = 0; t < nt; t += 2) {
;             const bool last = (t == nt - 2);
;             const char* a1 = cA + (size_t)(t + 1) * kstep;
;             const char* a2 = last ? nA : cA + (size_t)(t + 2) * kstep; const char* b2 = last ? nB : cB + (size_t)(t + 2) * kstep;
;             const char* a3 = a2 + kstep; const char* b3 = b2 + kstep;
;             if (last && has_next) S.a_ready(nxt);
;             if constexpr (SP2) {
;             PG8_LDB(B0, 0, 0); PG8_LDB(B1, 0, 1); PG8_SCHED; PG8_LDA(At, 0, 0); PG8_STAGE(PG8_SA(1, 1), a1 + hstepA, voffA);
;             PG8_WAIT_V(8); PG8_WAIT_L(0); PG8_BAR; PG8_MMA(0, 0, At, B0); PG8_MMA(0, 1, At, B1); PG8_BAR; PG8_SCHED;
;             PG8_LDA(At, 0, 1); PG8_STAGE(PG8_SB(0, 0), b2, voffB); PG8_STAGE(PG8_SB(0, 1), b2 + hstepB, voffB); PG8_STAGE(PG8_SA(0, 0), a2, voffA);
;             PG8_WAIT_V(8); PG8_WAIT_L(0); PG8_BAR; PG8_MMA(1, 0, At, B0); PG8_MMA(1, 1, At, B1); PG8_BAR; PG8_SCHED;
.LBB0_2322:
	ds_read_b128 v[58:61], v183
	ds_read_b128 v[66:69], v183 offset:1024
	ds_read_b128 v[74:77], v183 offset:2048
	ds_read_b128 v[78:81], v183 offset:3072
	ds_read_b128 v[146:149], v189
	ds_read_b128 v[150:153], v189 offset:1024
	ds_read_b128 v[154:157], v189 offset:2048
	ds_read_b128 v[158:161], v189 offset:3072
	s_add_u32 s28, s26, 0xfff80080
	s_addc_u32 s29, s27, -1
	s_cmp_eq_u32 s53, 28
	s_cselect_b32 s31, s21, s29
	s_cselect_b32 s30, s49, s28
	s_cselect_b32 s29, s19, s52
	s_cselect_b32 s28, s50, s51
	v_lshl_add_u64 v[190:191], s[26:27], 0, v[170:171]
	s_add_i32 m0, s3, 0xc000
	ds_read_b128 v[162:165], v193
	ds_read_b128 v[178:181], v193 offset:1024
	ds_read_b128 v[184:187], v193 offset:2048
	ds_read_b128 v[198:201], v193 offset:3072
	ds_read_b128 v[202:205], v193 offset:4096
	ds_read_b128 v[206:209], v193 offset:5120
	ds_read_b128 v[210:213], v193 offset:6144
	ds_read_b128 v[214:217], v193 offset:7168
	global_load_lds_dwordx4 v[190:191], off
	v_lshl_add_u64 v[190:191], s[26:27], 0, v[172:173]
	s_add_i32 m0, s3, 0xe000
	s_nop 0
	global_load_lds_dwordx4 v[190:191], off
	s_waitcnt vmcnt(8)
	s_waitcnt lgkmcnt(0)
	s_barrier
	s_setprio 1
	s_waitcnt lgkmcnt(0)
	v_mfma_i32_16x16x64_i8 v[142:145], v[58:61], v[162:165], v[142:145]
	v_mfma_i32_16x16x64_i8 v[138:141], v[74:77], v[162:165], v[138:141]
	v_mfma_i32_16x16x64_i8 v[126:129], v[58:61], v[184:187], v[126:129]
	v_mfma_i32_16x16x64_i8 v[122:125], v[74:77], v[184:187], v[122:125]
	v_mfma_i32_16x16x64_i8 v[110:113], v[58:61], v[202:205], v[110:113]
	v_mfma_i32_16x16x64_i8 v[106:109], v[74:77], v[202:205], v[106:109]
	v_mfma_i32_16x16x64_i8 v[94:97], v[58:61], v[210:213], v[94:97]
	v_mfma_i32_16x16x64_i8 v[90:93], v[74:77], v[210:213], v[90:93]
	s_setprio 0
	s_setprio 1
	v_mfma_i32_16x16x64_i8 v[142:145], v[66:69], v[178:181], v[142:145]
	v_mfma_i32_16x16x64_i8 v[138:141], v[78:81], v[178:181], v[138:141]
	v_mfma_i32_16x16x64_i8 v[126:129], v[66:69], v[198:201], v[126:129]
	v_mfma_i32_16x16x64_i8 v[122:125], v[78:81], v[198:201], v[122:125]
	v_mfma_i32_16x16x64_i8 v[110:113], v[66:69], v[206:209], v[110:113]
	v_mfma_i32_16x16x64_i8 v[106:109], v[78:81], v[206:209], v[106:109]
	v_mfma_i32_16x16x64_i8 v[94:97], v[66:69], v[214:217], v[94:97]
	v_mfma_i32_16x16x64_i8 v[90:93], v[78:81], v[214:217], v[90:93]
	s_setprio 0
	s_setprio 1
	v_mfma_i32_16x16x64_i8 v[134:137], v[146:149], v[162:165], v[134:137]
	v_mfma_i32_16x16x64_i8 v[130:133], v[154:157], v[162:165], v[130:133]
	v_mfma_i32_16x16x64_i8 v[118:121], v[146:149], v[184:187], v[118:121]
	v_mfma_i32_16x16x64_i8 v[114:117], v[154:157], v[184:187], v[114:117]
	v_mfma_i32_16x16x64_i8 v[102:105], v[146:149], v[202:205], v[102:105]
	v_mfma_i32_16x16x64_i8 v[98:101], v[154:157], v[202:205], v[98:101]
	v_mfma_i32_16x16x64_i8 v[86:89], v[146:149], v[210:213], v[86:89]
	v_mfma_i32_16x16x64_i8 v[82:85], v[154:157], v[210:213], v[82:85]
	s_setprio 0
	s_setprio 1
	v_mfma_i32_16x16x64_i8 v[134:137], v[150:153], v[178:181], v[134:137]
	v_mfma_i32_16x16x64_i8 v[130:133], v[158:161], v[178:181], v[130:133]
	v_mfma_i32_16x16x64_i8 v[118:121], v[150:153], v[198:201], v[118:121]
	v_mfma_i32_16x16x64_i8 v[114:117], v[158:161], v[198:201], v[114:117]
	v_mfma_i32_16x16x64_i8 v[102:105], v[150:153], v[206:209], v[102:105]
	v_mfma_i32_16x16x64_i8 v[98:101], v[158:161], v[206:209], v[98:101]
	v_mfma_i32_16x16x64_i8 v[86:89], v[150:153], v[214:217], v[86:89]
	v_mfma_i32_16x16x64_i8 v[82:85], v[158:161], v[214:217], v[82:85]
	s_setprio 0
	s_barrier
	s_add_i32 s54, s46, s38
	v_lshl_add_u64 v[190:191], s[28:29], 0, v[166:167]
	s_mov_b32 m0, s54
	ds_read_b128 v[162:165], v193 offset:16384
	ds_read_b128 v[178:181], v193 offset:17408
	ds_read_b128 v[184:187], v193 offset:18432
	ds_read_b128 v[198:201], v193 offset:19456
	ds_read_b128 v[202:205], v193 offset:20480
	ds_read_b128 v[206:209], v193 offset:21504
	ds_read_b128 v[210:213], v193 offset:22528
	ds_read_b128 v[214:217], v193 offset:23552
	global_load_lds_dwordx4 v[190:191], off
	s_add_i32 m0, s54, 0x2000
	s_add_u32 s54, s28, 0x80000
	v_lshl_add_u64 v[194:195], s[28:29], 0, v[168:169]
	s_addc_u32 s55, s29, 0
	s_add_i32 s56, s47, s38
	global_load_lds_dwordx4 v[194:195], off
	v_lshl_add_u64 v[218:219], s[54:55], 0, v[166:167]
	s_mov_b32 m0, s56
	v_lshl_add_u64 v[220:221], s[30:31], 0, v[168:169]
	global_load_lds_dwordx4 v[218:219], off
	v_lshl_add_u64 v[218:219], s[54:55], 0, v[168:169]
	s_add_i32 m0, s56, 0x2000
	s_nop 0
	global_load_lds_dwordx4 v[218:219], off
	v_lshl_add_u64 v[218:219], s[30:31], 0, v[166:167]
	s_mov_b32 m0, s3
	s_nop 0
	global_load_lds_dwordx4 v[218:219], off
	s_mov_b32 m0, s39
	s_nop 0
	global_load_lds_dwordx4 v[220:221], off
	s_waitcnt vmcnt(8)
	s_waitcnt lgkmcnt(0)
	s_barrier
; #define PG8_STAGE(bufoff, gbase, voff) do { _Pragma("unroll") for (int _i = 0; _i < 2; ++_i) \
;         __builtin_amdgcn_global_load_lds((const unsigned*)((const char*)(gbase) + (voff)[_i]), (PG8_LAS unsigned*)(lds + (bufoff) + ldsw + _i * 8192), 16, 0, 0); } while (0)
; #define PG8_LDA(dst, b, h) do { _Pragma("unroll") for (int m = 0; m < 4; ++m) _Pragma("unroll") for (int k = 0; k < 2; ++k) dst[m][k] = *(const PG8_LAS bf16x8*)(lds + PG8_SA(b, h) + aoff + m * 2048 + k * 1024); } while (0)
; #define PG8_LDB(dst, b, h) do { _Pragma("unroll") for (int n = 0; n < 2; ++n) _Pragma("unroll") for (int k = 0; k < 2; ++k) dst[n][k] = *(const PG8_LAS bf16x8*)(lds + PG8_SB(b, h) + boff + n * 2048 + k * 1024); } while (0)
; #define PG8_MMA(ai, bj, At, Bt) do { __builtin_amdgcn_s_setprio(1); _Pragma("unroll") for (int m = 0; m < 4; ++m) _Pragma("unroll") for (int n = 0; n < 2; ++n) _Pragma("unroll") for (int k = 0; k < 2; ++k) \
;         acc[ai][bj][m][n] = mma_<I8>(Bt[n][k], At[m][k], acc[ai][bj][m][n]); __builtin_amdgcn_s_setprio(0); } while (0)
; #define PG8_WAIT_V(n) asm volatile("s_waitcnt vmcnt(" #n ")" ::: "memory")
; #define PG8_WAIT_L(n) asm volatile("s_waitcnt lgkmcnt(" #n ")" ::: "memory")
; #define PG8_BAR __builtin_amdgcn_s_barrier()
; #define PG8_SCHED __builtin_amdgcn_sched_barrier(0)
; template <class Epi, class Sched, bool ALIGN_EPI = false, bool SP2 = false, bool I8 = false>
; __device__ __forceinline__ void gemm_phase(PG8_LAS unsigned char* lds, const Gemm g, const Sched& S, const Epi& E) {
;     ...
;             PG8_WAIT_V(8); PG8_WAIT_L(0); PG8_BAR; PG8_MMA(0, 0, At, B0); PG8_MMA(0, 1, At, B1); PG8_BAR; PG8_SCHED;
;             PG8_LDA(At, 0, 1); PG8_STAGE(PG8_SB(0, 0), b2, voffB); PG8_STAGE(PG8_SB(0, 1), b2 + hstepB, voffB); PG8_STAGE(PG8_SA(0, 0), a2, voffA);
;             PG8_WAIT_V(8); PG8_WAIT_L(0); PG8_BAR; PG8_MMA(1, 0, At, B0); PG8_MMA(1, 1, At, B1); PG8_BAR; PG8_SCHED;
;             PG8_LDB(B0, 1, 0); PG8_LDB(B1, 1, 1); PG8_SCHED; PG8_LDA(At, 1, 0); PG8_STAGE(PG8_SA(0, 1), a2 + hstepA, voffA);
;             PG8_WAIT_V(8); PG8_WAIT_L(0); PG8_BAR; PG8_MMA(0, 0, At, B0); PG8_MMA(0, 1, At, B1); PG8_BAR; PG8_SCHED;
	s_setprio 1
	s_waitcnt lgkmcnt(0)
	v_mfma_i32_16x16x64_i8 v[70:73], v[58:61], v[162:165], v[70:73]
	v_mfma_i32_16x16x64_i8 v[62:65], v[74:77], v[162:165], v[62:65]
	v_mfma_i32_16x16x64_i8 v[46:49], v[58:61], v[184:187], v[46:49]
	v_mfma_i32_16x16x64_i8 v[42:45], v[74:77], v[184:187], v[42:45]
	v_mfma_i32_16x16x64_i8 v[30:33], v[58:61], v[202:205], v[30:33]
	v_mfma_i32_16x16x64_i8 v[26:29], v[74:77], v[202:205], v[26:29]
	v_mfma_i32_16x16x64_i8 v[14:17], v[58:61], v[210:213], v[14:17]
	v_mfma_i32_16x16x64_i8 v[10:13], v[74:77], v[210:213], v[10:13]
	s_setprio 0
	s_setprio 1
	v_mfma_i32_16x16x64_i8 v[70:73], v[66:69], v[178:181], v[70:73]
	v_mfma_i32_16x16x64_i8 v[62:65], v[78:81], v[178:181], v[62:65]
	v_mfma_i32_16x16x64_i8 v[46:49], v[66:69], v[198:201], v[46:49]
	v_mfma_i32_16x16x64_i8 v[42:45], v[78:81], v[198:201], v[42:45]
	v_mfma_i32_16x16x64_i8 v[30:33], v[66:69], v[206:209], v[30:33]
	v_mfma_i32_16x16x64_i8 v[26:29], v[78:81], v[206:209], v[26:29]
	v_mfma_i32_16x16x64_i8 v[14:17], v[66:69], v[214:217], v[14:17]
	v_mfma_i32_16x16x64_i8 v[10:13], v[78:81], v[214:217], v[10:13]
	s_setprio 0
	s_setprio 1
	v_mfma_i32_16x16x64_i8 v[54:57], v[146:149], v[162:165], v[54:57]
	v_mfma_i32_16x16x64_i8 v[50:53], v[154:157], v[162:165], v[50:53]
	v_mfma_i32_16x16x64_i8 v[38:41], v[146:149], v[184:187], v[38:41]
	v_mfma_i32_16x16x64_i8 v[34:37], v[154:157], v[184:187], v[34:37]
	v_mfma_i32_16x16x64_i8 v[22:25], v[146:149], v[202:205], v[22:25]
	v_mfma_i32_16x16x64_i8 v[18:21], v[154:157], v[202:205], v[18:21]
	v_mfma_i32_16x16x64_i8 v[6:9], v[146:149], v[210:213], v[6:9]
	v_mfma_i32_16x16x64_i8 v[2:5], v[154:157], v[210:213], v[2:5]
	s_setprio 0
	s_setprio 1
	v_mfma_i32_16x16x64_i8 v[54:57], v[150:153], v[178:181], v[54:57]
	v_mfma_i32_16x16x64_i8 v[50:53], v[158:161], v[178:181], v[50:53]
	v_mfma_i32_16x16x64_i8 v[38:41], v[150:153], v[198:201], v[38:41]
	v_mfma_i32_16x16x64_i8 v[34:37], v[158:161], v[198:201], v[34:37]
	v_mfma_i32_16x16x64_i8 v[22:25], v[150:153], v[206:209], v[22:25]
	v_mfma_i32_16x16x64_i8 v[18:21], v[158:161], v[206:209], v[18:21]
	v_mfma_i32_16x16x64_i8 v[6:9], v[150:153], v[214:217], v[6:9]
	v_mfma_i32_16x16x64_i8 v[2:5], v[158:161], v[214:217], v[2:5]
	s_setprio 0
	s_barrier
	s_add_i32 s54, 0, 0x18000
	s_add_i32 s55, 0, 0x1c000
	v_add_u32_e32 v78, s54, v1
	v_add_u32_e32 v158, s55, v1
	ds_read_b128 v[58:61], v78
	ds_read_b128 v[66:69], v78 offset:1024
	ds_read_b128 v[74:77], v78 offset:2048
	ds_read_b128 v[78:81], v78 offset:3072
	ds_read_b128 v[146:149], v158
	ds_read_b128 v[150:153], v158 offset:1024
	ds_read_b128 v[154:157], v158 offset:2048
	ds_read_b128 v[158:161], v158 offset:3072
	s_add_u32 s30, s30, 0x80000
	s_addc_u32 s31, s31, 0
	s_mov_b32 m0, s40
	v_lshl_add_u64 v[222:223], s[30:31], 0, v[166:167]
	ds_read_b128 v[162:165], v193 offset:32768
	ds_read_b128 v[178:181], v193 offset:33792
	ds_read_b128 v[184:187], v193 offset:34816
	ds_read_b128 v[198:201], v193 offset:35840
	ds_read_b128 v[202:205], v193 offset:36864
	ds_read_b128 v[206:209], v193 offset:37888
	ds_read_b128 v[210:213], v193 offset:38912
	ds_read_b128 v[214:217], v193 offset:39936
	global_load_lds_dwordx4 v[222:223], off
	v_lshl_add_u64 v[222:223], s[30:31], 0, v[168:169]
	s_mov_b32 m0, s41
	s_nop 0
	global_load_lds_dwordx4 v[222:223], off
	s_waitcnt vmcnt(8)
	s_waitcnt lgkmcnt(0)
	s_barrier
	s_setprio 1
	s_waitcnt lgkmcnt(0)
	v_mfma_i32_16x16x64_i8 v[142:145], v[58:61], v[162:165], v[142:145]
	v_mfma_i32_16x16x64_i8 v[138:141], v[74:77], v[162:165], v[138:141]
	v_mfma_i32_16x16x64_i8 v[126:129], v[58:61], v[184:187], v[126:129]
	v_mfma_i32_16x16x64_i8 v[122:125], v[74:77], v[184:187], v[122:125]
	v_mfma_i32_16x16x64_i8 v[110:113], v[58:61], v[202:205], v[110:113]
	v_mfma_i32_16x16x64_i8 v[106:109], v[74:77], v[202:205], v[106:109]
	v_mfma_i32_16x16x64_i8 v[94:97], v[58:61], v[210:213], v[94:97]
	v_mfma_i32_16x16x64_i8 v[90:93], v[74:77], v[210:213], v[90:93]
	s_setprio 0
	s_setprio 1
	v_mfma_i32_16x16x64_i8 v[142:145], v[66:69], v[178:181], v[142:145]
	v_mfma_i32_16x16x64_i8 v[138:141], v[78:81], v[178:181], v[138:141]
	v_mfma_i32_16x16x64_i8 v[126:129], v[66:69], v[198:201], v[126:129]
	v_mfma_i32_16x16x64_i8 v[122:125], v[78:81], v[198:201], v[122:125]
	v_mfma_i32_16x16x64_i8 v[110:113], v[66:69], v[206:209], v[110:113]
	v_mfma_i32_16x16x64_i8 v[106:109], v[78:81], v[206:209], v[106:109]
	v_mfma_i32_16x16x64_i8 v[94:97], v[66:69], v[214:217], v[94:97]
	v_mfma_i32_16x16x64_i8 v[90:93], v[78:81], v[214:217], v[90:93]
	s_setprio 0
	s_setprio 1
	v_mfma_i32_16x16x64_i8 v[134:137], v[146:149], v[162:165], v[134:137]
	v_mfma_i32_16x16x64_i8 v[130:133], v[154:157], v[162:165], v[130:133]
	v_mfma_i32_16x16x64_i8 v[118:121], v[146:149], v[184:187], v[118:121]
	v_mfma_i32_16x16x64_i8 v[114:117], v[154:157], v[184:187], v[114:117]
	v_mfma_i32_16x16x64_i8 v[102:105], v[146:149], v[202:205], v[102:105]
	v_mfma_i32_16x16x64_i8 v[98:101], v[154:157], v[202:205], v[98:101]
	v_mfma_i32_16x16x64_i8 v[86:89], v[146:149], v[210:213], v[86:89]
	v_mfma_i32_16x16x64_i8 v[82:85], v[154:157], v[210:213], v[82:85]
	s_setprio 0
	s_setprio 1
	v_mfma_i32_16x16x64_i8 v[134:137], v[150:153], v[178:181], v[134:137]
	v_mfma_i32_16x16x64_i8 v[130:133], v[158:161], v[178:181], v[130:133]
	v_mfma_i32_16x16x64_i8 v[118:121], v[150:153], v[198:201], v[118:121]
	v_mfma_i32_16x16x64_i8 v[114:117], v[158:161], v[198:201], v[114:117]
	v_mfma_i32_16x16x64_i8 v[102:105], v[150:153], v[206:209], v[102:105]
	v_mfma_i32_16x16x64_i8 v[98:101], v[158:161], v[206:209], v[98:101]
	v_mfma_i32_16x16x64_i8 v[86:89], v[150:153], v[214:217], v[86:89]
	v_mfma_i32_16x16x64_i8 v[82:85], v[158:161], v[214:217], v[82:85]
	s_setprio 0
	s_barrier
; #define PG8_STAGE(bufoff, gbase, voff) do { _Pragma("unroll") for (int _i = 0; _i < 2; ++_i) \
;         __builtin_amdgcn_global_load_lds((const unsigned*)((const char*)(gbase) + (voff)[_i]), (PG8_LAS unsigned*)(lds + (bufoff) + ldsw + _i * 8192), 16, 0, 0); } while (0)
; #define PG8_LDA(dst, b, h) do { _Pragma("unroll") for (int m = 0; m < 4; ++m) _Pragma("unroll") for (int k = 0; k < 2; ++k) dst[m][k] = *(const PG8_LAS bf16x8*)(lds + PG8_SA(b, h) + aoff + m * 2048 + k * 1024); } while (0)
; #define PG8_LDB(dst, b, h) do { _Pragma("unroll") for (int n = 0; n < 2; ++n) _Pragma("unroll") for (int k = 0; k < 2; ++k) dst[n][k] = *(const PG8_LAS bf16x8*)(lds + PG8_SB(b, h) + boff + n * 2048 + k * 1024); } while (0)
; #define PG8_MMA(ai, bj, At, Bt) do { __builtin_amdgcn_s_setprio(1); _Pragma("unroll") for (int m = 0; m < 4; ++m) _Pragma("unroll") for (int n = 0; n < 2; ++n) _Pragma("unroll") for (int k = 0; k < 2; ++k) \
;         acc[ai][bj][m][n] = mma_<I8>(Bt[n][k], At[m][k], acc[ai][bj][m][n]); __builtin_amdgcn_s_setprio(0); } while (0)
; #define PG8_WAIT_V(n) asm volatile("s_waitcnt vmcnt(" #n ")" ::: "memory")
; #define PG8_WAIT_L(n) asm volatile("s_waitcnt lgkmcnt(" #n ")" ::: "memory")
; #define PG8_BAR __builtin_amdgcn_s_barrier()
; #define PG8_SCHED __builtin_amdgcn_sched_barrier(0)
; template <class Epi, class Sched, bool ALIGN_EPI = false, bool SP2 = false, bool I8 = false>
; __device__ __forceinline__ void gemm_phase(PG8_LAS unsigned char* lds, const Gemm g, const Sched& S, const Epi& E) {
;     ...
;         for (int t = 0; t < nt; t += 2) {
;             const bool last = (t == nt - 2);
;     ...
;             PG8_WAIT_V(8); PG8_WAIT_L(0); PG8_BAR; PG8_MMA(1, 0, At, B0); PG8_MMA(1, 1, At, B1); PG8_BAR; PG8_SCHED;
;             PG8_LDB(B0, 1, 0); PG8_LDB(B1, 1, 1); PG8_SCHED; PG8_LDA(At, 1, 0); PG8_STAGE(PG8_SA(0, 1), a2 + hstepA, voffA);
;             PG8_WAIT_V(8); PG8_WAIT_L(0); PG8_BAR; PG8_MMA(0, 0, At, B0); PG8_MMA(0, 1, At, B1); PG8_BAR; PG8_SCHED;
;             PG8_LDA(At, 1, 1); PG8_STAGE(PG8_SB(1, 0), b3, voffB); PG8_STAGE(PG8_SB(1, 1), b3 + hstepB, voffB); PG8_STAGE(PG8_SA(1, 0), a3, voffA);
;             PG8_WAIT_V(8); PG8_WAIT_L(0); PG8_BAR; PG8_MMA(1, 0, At, B0); PG8_MMA(1, 1, At, B1); PG8_BAR; PG8_SCHED;
	s_add_i32 s30, s54, s38
	v_lshl_add_u64 v[190:191], v[190:191], 0, s[14:15]
	s_mov_b32 m0, s30
	ds_read_b128 v[162:165], v193 offset:49152
	ds_read_b128 v[178:181], v193 offset:50176
	ds_read_b128 v[184:187], v193 offset:51200
	ds_read_b128 v[198:201], v193 offset:52224
	ds_read_b128 v[202:205], v193 offset:53248
	ds_read_b128 v[206:209], v193 offset:54272
	ds_read_b128 v[210:213], v193 offset:55296
	ds_read_b128 v[214:217], v193 offset:56320
	global_load_lds_dwordx4 v[190:191], off
	s_add_i32 m0, s30, 0x2000
	s_add_u32 s28, s28, 0x80080
	v_lshl_add_u64 v[190:191], v[194:195], 0, s[14:15]
	s_addc_u32 s29, s29, 0
	s_add_i32 s30, s55, s38
	global_load_lds_dwordx4 v[190:191], off
	v_lshl_add_u64 v[190:191], s[28:29], 0, v[166:167]
	s_mov_b32 m0, s30
	s_nop 0
	global_load_lds_dwordx4 v[190:191], off
	v_lshl_add_u64 v[190:191], s[28:29], 0, v[168:169]
	s_add_i32 m0, s30, 0x2000
	s_nop 0
	global_load_lds_dwordx4 v[190:191], off
	v_lshl_add_u64 v[190:191], v[218:219], 0, s[14:15]
	s_mov_b32 m0, s43
	s_nop 0
	global_load_lds_dwordx4 v[190:191], off
	v_lshl_add_u64 v[190:191], v[220:221], 0, s[14:15]
	s_mov_b32 m0, s44
	s_nop 0
	global_load_lds_dwordx4 v[190:191], off
	s_waitcnt vmcnt(8)
	s_waitcnt lgkmcnt(0)
	s_barrier
	s_setprio 1
	s_waitcnt lgkmcnt(0)
	v_mfma_i32_16x16x64_i8 v[70:73], v[58:61], v[162:165], v[70:73]
	v_mfma_i32_16x16x64_i8 v[62:65], v[74:77], v[162:165], v[62:65]
	v_mfma_i32_16x16x64_i8 v[46:49], v[58:61], v[184:187], v[46:49]
	v_mfma_i32_16x16x64_i8 v[42:45], v[74:77], v[184:187], v[42:45]
	v_mfma_i32_16x16x64_i8 v[30:33], v[58:61], v[202:205], v[30:33]
	v_mfma_i32_16x16x64_i8 v[26:29], v[74:77], v[202:205], v[26:29]
	v_mfma_i32_16x16x64_i8 v[14:17], v[58:61], v[210:213], v[14:17]
	v_mfma_i32_16x16x64_i8 v[10:13], v[74:77], v[210:213], v[10:13]
	s_setprio 0
	s_setprio 1
	v_mfma_i32_16x16x64_i8 v[70:73], v[66:69], v[178:181], v[70:73]
	v_mfma_i32_16x16x64_i8 v[62:65], v[78:81], v[178:181], v[62:65]
	v_mfma_i32_16x16x64_i8 v[46:49], v[66:69], v[198:201], v[46:49]
	v_mfma_i32_16x16x64_i8 v[42:45], v[78:81], v[198:201], v[42:45]
	v_mfma_i32_16x16x64_i8 v[30:33], v[66:69], v[206:209], v[30:33]
	v_mfma_i32_16x16x64_i8 v[26:29], v[78:81], v[206:209], v[26:29]
	v_mfma_i32_16x16x64_i8 v[14:17], v[66:69], v[214:217], v[14:17]
	v_mfma_i32_16x16x64_i8 v[10:13], v[78:81], v[214:217], v[10:13]
	s_setprio 0
	s_setprio 1
	v_mfma_i32_16x16x64_i8 v[54:57], v[146:149], v[162:165], v[54:57]
	v_mfma_i32_16x16x64_i8 v[50:53], v[154:157], v[162:165], v[50:53]
	v_mfma_i32_16x16x64_i8 v[38:41], v[146:149], v[184:187], v[38:41]
	v_mfma_i32_16x16x64_i8 v[34:37], v[154:157], v[184:187], v[34:37]
	v_mfma_i32_16x16x64_i8 v[22:25], v[146:149], v[202:205], v[22:25]
	v_mfma_i32_16x16x64_i8 v[18:21], v[154:157], v[202:205], v[18:21]
	v_mfma_i32_16x16x64_i8 v[6:9], v[146:149], v[210:213], v[6:9]
	v_mfma_i32_16x16x64_i8 v[2:5], v[154:157], v[210:213], v[2:5]
	s_setprio 0
	s_setprio 1
	v_mfma_i32_16x16x64_i8 v[54:57], v[150:153], v[178:181], v[54:57]
	v_mfma_i32_16x16x64_i8 v[50:53], v[158:161], v[178:181], v[50:53]
	v_mfma_i32_16x16x64_i8 v[38:41], v[150:153], v[198:201], v[38:41]
	v_mfma_i32_16x16x64_i8 v[34:37], v[158:161], v[198:201], v[34:37]
	v_mfma_i32_16x16x64_i8 v[22:25], v[150:153], v[206:209], v[22:25]
	v_mfma_i32_16x16x64_i8 v[18:21], v[158:161], v[206:209], v[18:21]
	v_mfma_i32_16x16x64_i8 v[6:9], v[150:153], v[214:217], v[6:9]
	v_mfma_i32_16x16x64_i8 v[2:5], v[158:161], v[214:217], v[2:5]
	s_setprio 0
	s_barrier
	s_add_i32 s53, s53, 2
	s_add_u32 s26, s26, 0x100
	s_addc_u32 s27, s27, 0
	s_add_u32 s51, s51, 0x100
	s_addc_u32 s52, s52, 0
	s_cmp_gt_u32 s53, 29
	s_cbranch_scc0 .LBB0_2322
	s_and_b64 vcc, exec, s[16:17]
	s_cbranch_vccz .LBB0_2325
	s_barrier
